# GEMM main loops: removed the second s_waitcnt lgkmcnt(0) after each phase barrier (already waited before the barrier)
# baseline (speedup 1.0000x reference)
; #define PG8_STAGE(bufoff, gbase, voff) do { _Pragma("unroll") for (int _i = 0; _i < 2; ++_i) \
;         __builtin_amdgcn_global_load_lds((const unsigned*)((const char*)(gbase) + (voff)[_i]), (LAS unsigned*)(lds + (bufoff) + ldsw + _i * 8192), 16, 0, 0); } while (0)
; #define PG8_LDA(dst, b, h) do { _Pragma("unroll") for (int m = 0; m < 4; ++m) _Pragma("unroll") for (int k = 0; k < 2; ++k) dst[m][k] = *(const LAS bf16x8*)(lds + PG8_SA(b, h) + aoff + m * 2048 + k * 1024); } while (0)
; #define PG8_LDB(dst, b, h) do { _Pragma("unroll") for (int n = 0; n < 2; ++n) _Pragma("unroll") for (int k = 0; k < 2; ++k) dst[n][k] = *(const LAS bf16x8*)(lds + PG8_SB(b, h) + boff + n * 2048 + k * 1024); } while (0)
; #define PG8_MMA(ai, bj, At, Bt) do { __builtin_amdgcn_s_setprio(1); _Pragma("unroll") for (int m = 0; m < 4; ++m) _Pragma("unroll") for (int n = 0; n < 2; ++n) _Pragma("unroll") for (int k = 0; k < 2; ++k) \
;         acc[ai][bj][m][n] = __builtin_amdgcn_mfma_f32_16x16x32_bf16(Bt[n][k], At[m][k], acc[ai][bj][m][n], 0, 0, 0); __builtin_amdgcn_s_setprio(0); } while (0)
; #define PG8_WAIT_V(n) asm volatile("s_waitcnt vmcnt(" #n ")" ::: "memory")
; #define PG8_WAIT_L(n) asm volatile("s_waitcnt lgkmcnt(" #n ")" ::: "memory")
; #define PG8_BAR __builtin_amdgcn_s_barrier()
; #define PG8_SCHED __builtin_amdgcn_sched_barrier(0)
; template <class Epi>
; __device__ __forceinline__ void gemm_phase(LAS unsigned char* lds, const Gemm g, const StaticOrder& S, const Epi& E) {
;     ...
;             const char* a1 = PG8_AP(cA, t + 1);
;             const char* a2 = last ? nA : PG8_AP(cA, t + 2); const char* b2 = last ? nB : cB + (size_t)(t + 2) * kstep;
;             const char* a3 = last ? nA + kstep : PG8_AP(cA, t + 3); const char* b3 = b2 + kstep;
;             PG8_LDB(B0, 0, 0); PG8_LDB(B1, 0, 1); PG8_SCHED; PG8_LDA(At, 0, 0); PG8_STAGE(PG8_SA(1, 1), a1 + hstepA, voffA);
;             PG8_WAIT_V(8); PG8_WAIT_L(0); PG8_BAR; PG8_MMA(0, 0, At, B0); PG8_MMA(0, 1, At, B1); PG8_BAR; PG8_SCHED;
;             PG8_LDA(At, 0, 1); PG8_STAGE(PG8_SB(0, 0), b2, voffB); PG8_STAGE(PG8_SB(0, 1), b2 + hstep, voffB); PG8_STAGE(PG8_SA(0, 0), a2, voffA);
.LBB0_233:
	s_add_u32 s50, s46, s48
	s_addc_u32 s51, s47, s49
	s_add_u32 s56, s50, 0x100
	s_addc_u32 s57, s51, 0
	s_add_u32 s54, s93, s48
	s_addc_u32 s55, s94, s49
	s_add_u32 s50, s50, 0x180
	s_addc_u32 s51, s51, 0
	s_add_i32 s90, 0, 0x10000
	s_add_i32 s91, 0, 0x14000
	v_add_u32_e32 v147, s90, v1
	ds_read_b128 v[148:151], v147
	ds_read_b128 v[152:155], v147 offset:1024
	ds_read_b128 v[156:159], v147 offset:2048
	ds_read_b128 v[160:163], v147 offset:3072
	v_add_u32_e32 v147, s91, v1
	ds_read_b128 v[186:189], v147
	ds_read_b128 v[190:193], v147 offset:1024
	ds_read_b128 v[194:197], v147 offset:2048
	ds_read_b128 v[198:201], v147 offset:3072
	s_cmpk_eq_i32 s48, 0xf00
	s_cselect_b32 s51, s92, s51
	s_cselect_b32 s50, s87, s50
	s_cselect_b32 s55, s37, s55
	s_cselect_b32 s54, s86, s54
	s_cselect_b32 s57, s41, s57
	s_cselect_b32 s56, s85, s56
	v_lshl_add_u64 v[222:223], v[142:143], 0, s[48:49]
	s_add_i32 m0, s25, 0xc000
	ds_read_b128 v[202:205], v146
	ds_read_b128 v[206:209], v146 offset:1024
	ds_read_b128 v[226:229], v146 offset:2048
	ds_read_b128 v[230:233], v146 offset:3072
	ds_read_b128 v[234:237], v146 offset:4096
	ds_read_b128 v[238:241], v146 offset:5120
	ds_read_b128 v[242:245], v146 offset:6144
	ds_read_b128 v[246:249], v146 offset:7168
	global_load_lds_dwordx4 v[222:223], off
	v_lshl_add_u64 v[222:223], v[144:145], 0, s[48:49]
	s_add_i32 m0, s25, 0xe000
	s_nop 0
	global_load_lds_dwordx4 v[222:223], off
	s_waitcnt vmcnt(8)
	s_waitcnt lgkmcnt(0)
	s_barrier
	s_setprio 1
	v_mfma_f32_16x16x32_bf16 v[126:129], v[148:151], v[202:205], v[126:129]
	v_mfma_f32_16x16x32_bf16 v[122:125], v[156:159], v[202:205], v[122:125]
	v_mfma_f32_16x16x32_bf16 v[118:121], v[148:151], v[226:229], v[118:121]
	v_mfma_f32_16x16x32_bf16 v[110:113], v[156:159], v[226:229], v[110:113]
	v_mfma_f32_16x16x32_bf16 v[102:105], v[148:151], v[234:237], v[102:105]
	v_mfma_f32_16x16x32_bf16 v[94:97], v[156:159], v[234:237], v[94:97]
	v_mfma_f32_16x16x32_bf16 v[86:89], v[148:151], v[242:245], v[86:89]
	v_mfma_f32_16x16x32_bf16 v[78:81], v[156:159], v[242:245], v[78:81]
	v_mfma_f32_16x16x32_bf16 v[126:129], v[152:155], v[206:209], v[126:129]
	v_mfma_f32_16x16x32_bf16 v[122:125], v[160:163], v[206:209], v[122:125]
	v_mfma_f32_16x16x32_bf16 v[118:121], v[152:155], v[230:233], v[118:121]
	v_mfma_f32_16x16x32_bf16 v[110:113], v[160:163], v[230:233], v[110:113]
	v_mfma_f32_16x16x32_bf16 v[102:105], v[152:155], v[238:241], v[102:105]
	v_mfma_f32_16x16x32_bf16 v[94:97], v[160:163], v[238:241], v[94:97]
	v_mfma_f32_16x16x32_bf16 v[86:89], v[152:155], v[246:249], v[86:89]
	v_mfma_f32_16x16x32_bf16 v[78:81], v[160:163], v[246:249], v[78:81]
	v_mfma_f32_16x16x32_bf16 v[114:117], v[186:189], v[202:205], v[114:117]
	v_mfma_f32_16x16x32_bf16 v[106:109], v[194:197], v[202:205], v[106:109]
	v_mfma_f32_16x16x32_bf16 v[98:101], v[186:189], v[226:229], v[98:101]
	v_mfma_f32_16x16x32_bf16 v[90:93], v[194:197], v[226:229], v[90:93]
	v_mfma_f32_16x16x32_bf16 v[82:85], v[186:189], v[234:237], v[82:85]
	v_mfma_f32_16x16x32_bf16 v[74:77], v[194:197], v[234:237], v[74:77]
	v_mfma_f32_16x16x32_bf16 v[70:73], v[186:189], v[242:245], v[70:73]
	v_mfma_f32_16x16x32_bf16 v[66:69], v[194:197], v[242:245], v[66:69]
	v_mfma_f32_16x16x32_bf16 v[114:117], v[190:193], v[206:209], v[114:117]
	v_mfma_f32_16x16x32_bf16 v[106:109], v[198:201], v[206:209], v[106:109]
	v_mfma_f32_16x16x32_bf16 v[98:101], v[190:193], v[230:233], v[98:101]
	v_mfma_f32_16x16x32_bf16 v[90:93], v[198:201], v[230:233], v[90:93]
	v_mfma_f32_16x16x32_bf16 v[82:85], v[190:193], v[238:241], v[82:85]
	v_mfma_f32_16x16x32_bf16 v[74:77], v[198:201], v[238:241], v[74:77]
	v_mfma_f32_16x16x32_bf16 v[70:73], v[190:193], v[246:249], v[70:73]
	v_mfma_f32_16x16x32_bf16 v[66:69], v[198:201], v[246:249], v[66:69]
	s_setprio 0
	s_barrier
	s_add_i32 s90, s90, s24
	v_lshl_add_u64 v[222:223], s[54:55], 0, v[134:135]
	s_mov_b32 m0, s90
	ds_read_b128 v[202:205], v146 offset:16384
	ds_read_b128 v[206:209], v146 offset:17408
	ds_read_b128 v[226:229], v146 offset:18432
	ds_read_b128 v[230:233], v146 offset:19456
	ds_read_b128 v[234:237], v146 offset:20480
	ds_read_b128 v[238:241], v146 offset:21504
	ds_read_b128 v[242:245], v146 offset:22528
	ds_read_b128 v[246:249], v146 offset:23552
	global_load_lds_dwordx4 v[222:223], off
	s_add_i32 m0, s90, 0x2000
	s_add_u32 vcc_lo, s54, 0x80000
	v_lshl_add_u64 v[224:225], s[54:55], 0, v[130:131]
	s_addc_u32 vcc_hi, s55, 0
	s_add_i32 s90, s91, s24
	global_load_lds_dwordx4 v[224:225], off
	v_lshl_add_u64 v[212:213], vcc, 0, v[134:135]
	s_mov_b32 m0, s90
	s_nop 0
	global_load_lds_dwordx4 v[212:213], off
	v_lshl_add_u64 v[212:213], vcc, 0, v[130:131]
	s_add_i32 m0, s90, 0x2000
	s_nop 0
	global_load_lds_dwordx4 v[212:213], off
	v_lshl_add_u64 v[212:213], s[56:57], 0, v[136:137]
	s_mov_b32 m0, s25
	s_nop 0
	global_load_lds_dwordx4 v[212:213], off
	v_lshl_add_u64 v[212:213], s[56:57], 0, v[132:133]
	s_mov_b32 m0, s26
	s_nop 0
	global_load_lds_dwordx4 v[212:213], off
	s_waitcnt vmcnt(8)
	s_waitcnt lgkmcnt(0)
	s_barrier
; #define PG8_STAGE(bufoff, gbase, voff) do { _Pragma("unroll") for (int _i = 0; _i < 2; ++_i) \
;         __builtin_amdgcn_global_load_lds((const unsigned*)((const char*)(gbase) + (voff)[_i]), (LAS unsigned*)(lds + (bufoff) + ldsw + _i * 8192), 16, 0, 0); } while (0)
; #define PG8_LDA(dst, b, h) do { _Pragma("unroll") for (int m = 0; m < 4; ++m) _Pragma("unroll") for (int k = 0; k < 2; ++k) dst[m][k] = *(const LAS bf16x8*)(lds + PG8_SA(b, h) + aoff + m * 2048 + k * 1024); } while (0)
; #define PG8_LDB(dst, b, h) do { _Pragma("unroll") for (int n = 0; n < 2; ++n) _Pragma("unroll") for (int k = 0; k < 2; ++k) dst[n][k] = *(const LAS bf16x8*)(lds + PG8_SB(b, h) + boff + n * 2048 + k * 1024); } while (0)
; #define PG8_MMA(ai, bj, At, Bt) do { __builtin_amdgcn_s_setprio(1); _Pragma("unroll") for (int m = 0; m < 4; ++m) _Pragma("unroll") for (int n = 0; n < 2; ++n) _Pragma("unroll") for (int k = 0; k < 2; ++k) \
;         acc[ai][bj][m][n] = __builtin_amdgcn_mfma_f32_16x16x32_bf16(Bt[n][k], At[m][k], acc[ai][bj][m][n], 0, 0, 0); __builtin_amdgcn_s_setprio(0); } while (0)
; #define PG8_WAIT_V(n) asm volatile("s_waitcnt vmcnt(" #n ")" ::: "memory")
; #define PG8_WAIT_L(n) asm volatile("s_waitcnt lgkmcnt(" #n ")" ::: "memory")
; #define PG8_BAR __builtin_amdgcn_s_barrier()
; #define PG8_SCHED __builtin_amdgcn_sched_barrier(0)
; template <class Epi>
; __device__ __forceinline__ void gemm_phase(LAS unsigned char* lds, const Gemm g, const StaticOrder& S, const Epi& E) {
;     ...
;             PG8_WAIT_V(8); PG8_WAIT_L(0); PG8_BAR; PG8_MMA(1, 0, At, B0); PG8_MMA(1, 1, At, B1); PG8_BAR; PG8_SCHED;
;             PG8_LDB(B0, 1, 0); PG8_LDB(B1, 1, 1); PG8_SCHED; PG8_LDA(At, 1, 0); PG8_STAGE(PG8_SA(0, 1), a2 + hstepA, voffA);
;             PG8_WAIT_V(8); PG8_WAIT_L(0); PG8_BAR; PG8_MMA(0, 0, At, B0); PG8_MMA(0, 1, At, B1); PG8_BAR; PG8_SCHED;
	s_setprio 1
	v_mfma_f32_16x16x32_bf16 v[62:65], v[148:151], v[202:205], v[62:65]
	v_mfma_f32_16x16x32_bf16 v[58:61], v[156:159], v[202:205], v[58:61]
	v_mfma_f32_16x16x32_bf16 v[54:57], v[148:151], v[226:229], v[54:57]
	v_mfma_f32_16x16x32_bf16 v[46:49], v[156:159], v[226:229], v[46:49]
	v_mfma_f32_16x16x32_bf16 v[38:41], v[148:151], v[234:237], v[38:41]
	v_mfma_f32_16x16x32_bf16 v[30:33], v[156:159], v[234:237], v[30:33]
	v_mfma_f32_16x16x32_bf16 v[22:25], v[148:151], v[242:245], v[22:25]
	v_mfma_f32_16x16x32_bf16 v[14:17], v[156:159], v[242:245], v[14:17]
	v_mfma_f32_16x16x32_bf16 v[62:65], v[152:155], v[206:209], v[62:65]
	v_mfma_f32_16x16x32_bf16 v[58:61], v[160:163], v[206:209], v[58:61]
	v_mfma_f32_16x16x32_bf16 v[54:57], v[152:155], v[230:233], v[54:57]
	v_mfma_f32_16x16x32_bf16 v[46:49], v[160:163], v[230:233], v[46:49]
	v_mfma_f32_16x16x32_bf16 v[38:41], v[152:155], v[238:241], v[38:41]
	v_mfma_f32_16x16x32_bf16 v[30:33], v[160:163], v[238:241], v[30:33]
	v_mfma_f32_16x16x32_bf16 v[22:25], v[152:155], v[246:249], v[22:25]
	v_mfma_f32_16x16x32_bf16 v[14:17], v[160:163], v[246:249], v[14:17]
	v_mfma_f32_16x16x32_bf16 v[50:53], v[186:189], v[202:205], v[50:53]
	v_mfma_f32_16x16x32_bf16 v[42:45], v[194:197], v[202:205], v[42:45]
	v_mfma_f32_16x16x32_bf16 v[34:37], v[186:189], v[226:229], v[34:37]
	v_mfma_f32_16x16x32_bf16 v[26:29], v[194:197], v[226:229], v[26:29]
	v_mfma_f32_16x16x32_bf16 v[18:21], v[186:189], v[234:237], v[18:21]
	v_mfma_f32_16x16x32_bf16 v[10:13], v[194:197], v[234:237], v[10:13]
	v_mfma_f32_16x16x32_bf16 v[6:9], v[186:189], v[242:245], v[6:9]
	v_mfma_f32_16x16x32_bf16 v[2:5], v[194:197], v[242:245], v[2:5]
	v_mfma_f32_16x16x32_bf16 v[50:53], v[190:193], v[206:209], v[50:53]
	v_mfma_f32_16x16x32_bf16 v[42:45], v[198:201], v[206:209], v[42:45]
	v_mfma_f32_16x16x32_bf16 v[34:37], v[190:193], v[230:233], v[34:37]
	v_mfma_f32_16x16x32_bf16 v[26:29], v[198:201], v[230:233], v[26:29]
	v_mfma_f32_16x16x32_bf16 v[18:21], v[190:193], v[238:241], v[18:21]
	v_mfma_f32_16x16x32_bf16 v[10:13], v[198:201], v[238:241], v[10:13]
	v_mfma_f32_16x16x32_bf16 v[6:9], v[190:193], v[246:249], v[6:9]
	v_mfma_f32_16x16x32_bf16 v[2:5], v[198:201], v[246:249], v[2:5]
	s_setprio 0
	s_barrier
	s_add_i32 s90, 0, 0x18000
	v_add_u32_e32 v147, s90, v1
	s_add_i32 s91, 0, 0x1c000
	ds_read_b128 v[148:151], v147
	ds_read_b128 v[152:155], v147 offset:1024
	ds_read_b128 v[156:159], v147 offset:2048
	ds_read_b128 v[160:163], v147 offset:3072
	v_add_u32_e32 v147, s91, v1
	ds_read_b128 v[186:189], v147
	ds_read_b128 v[190:193], v147 offset:1024
	ds_read_b128 v[194:197], v147 offset:2048
	ds_read_b128 v[198:201], v147 offset:3072
	s_add_u32 s56, s56, 0x80000
	s_addc_u32 s57, s57, 0
	s_mov_b32 m0, s27
	v_lshl_add_u64 v[212:213], s[56:57], 0, v[136:137]
	ds_read_b128 v[202:205], v146 offset:32768
	ds_read_b128 v[206:209], v146 offset:33792
	ds_read_b128 v[226:229], v146 offset:34816
	ds_read_b128 v[230:233], v146 offset:35840
	ds_read_b128 v[234:237], v146 offset:36864
	ds_read_b128 v[238:241], v146 offset:37888
	ds_read_b128 v[242:245], v146 offset:38912
	ds_read_b128 v[246:249], v146 offset:39936
	global_load_lds_dwordx4 v[212:213], off
	v_lshl_add_u64 v[212:213], s[56:57], 0, v[132:133]
	s_mov_b32 m0, s33
	s_nop 0
	global_load_lds_dwordx4 v[212:213], off
	s_waitcnt vmcnt(8)
	s_waitcnt lgkmcnt(0)
	s_barrier
	s_setprio 1
	v_mfma_f32_16x16x32_bf16 v[126:129], v[148:151], v[202:205], v[126:129]
	v_mfma_f32_16x16x32_bf16 v[122:125], v[156:159], v[202:205], v[122:125]
	v_mfma_f32_16x16x32_bf16 v[118:121], v[148:151], v[226:229], v[118:121]
	v_mfma_f32_16x16x32_bf16 v[110:113], v[156:159], v[226:229], v[110:113]
	v_mfma_f32_16x16x32_bf16 v[102:105], v[148:151], v[234:237], v[102:105]
	v_mfma_f32_16x16x32_bf16 v[94:97], v[156:159], v[234:237], v[94:97]
	v_mfma_f32_16x16x32_bf16 v[86:89], v[148:151], v[242:245], v[86:89]
	v_mfma_f32_16x16x32_bf16 v[78:81], v[156:159], v[242:245], v[78:81]
	v_mfma_f32_16x16x32_bf16 v[126:129], v[152:155], v[206:209], v[126:129]
	v_mfma_f32_16x16x32_bf16 v[122:125], v[160:163], v[206:209], v[122:125]
	v_mfma_f32_16x16x32_bf16 v[118:121], v[152:155], v[230:233], v[118:121]
	v_mfma_f32_16x16x32_bf16 v[110:113], v[160:163], v[230:233], v[110:113]
	v_mfma_f32_16x16x32_bf16 v[102:105], v[152:155], v[238:241], v[102:105]
	v_mfma_f32_16x16x32_bf16 v[94:97], v[160:163], v[238:241], v[94:97]
	v_mfma_f32_16x16x32_bf16 v[86:89], v[152:155], v[246:249], v[86:89]
	v_mfma_f32_16x16x32_bf16 v[78:81], v[160:163], v[246:249], v[78:81]
	v_mfma_f32_16x16x32_bf16 v[114:117], v[186:189], v[202:205], v[114:117]
	v_mfma_f32_16x16x32_bf16 v[106:109], v[194:197], v[202:205], v[106:109]
	v_mfma_f32_16x16x32_bf16 v[98:101], v[186:189], v[226:229], v[98:101]
	v_mfma_f32_16x16x32_bf16 v[90:93], v[194:197], v[226:229], v[90:93]
	v_mfma_f32_16x16x32_bf16 v[82:85], v[186:189], v[234:237], v[82:85]
	v_mfma_f32_16x16x32_bf16 v[74:77], v[194:197], v[234:237], v[74:77]
	v_mfma_f32_16x16x32_bf16 v[70:73], v[186:189], v[242:245], v[70:73]
	v_mfma_f32_16x16x32_bf16 v[66:69], v[194:197], v[242:245], v[66:69]
	v_mfma_f32_16x16x32_bf16 v[114:117], v[190:193], v[206:209], v[114:117]
	v_mfma_f32_16x16x32_bf16 v[106:109], v[198:201], v[206:209], v[106:109]
	v_mfma_f32_16x16x32_bf16 v[98:101], v[190:193], v[230:233], v[98:101]
	v_mfma_f32_16x16x32_bf16 v[90:93], v[198:201], v[230:233], v[90:93]
	v_mfma_f32_16x16x32_bf16 v[82:85], v[190:193], v[238:241], v[82:85]
	v_mfma_f32_16x16x32_bf16 v[74:77], v[198:201], v[238:241], v[74:77]
	v_mfma_f32_16x16x32_bf16 v[70:73], v[190:193], v[246:249], v[70:73]
	v_mfma_f32_16x16x32_bf16 v[66:69], v[198:201], v[246:249], v[66:69]
	s_setprio 0
	s_barrier
; #define PG8_STAGE(bufoff, gbase, voff) do { _Pragma("unroll") for (int _i = 0; _i < 2; ++_i) \
;         __builtin_amdgcn_global_load_lds((const unsigned*)((const char*)(gbase) + (voff)[_i]), (LAS unsigned*)(lds + (bufoff) + ldsw + _i * 8192), 16, 0, 0); } while (0)
; #define PG8_LDA(dst, b, h) do { _Pragma("unroll") for (int m = 0; m < 4; ++m) _Pragma("unroll") for (int k = 0; k < 2; ++k) dst[m][k] = *(const LAS bf16x8*)(lds + PG8_SA(b, h) + aoff + m * 2048 + k * 1024); } while (0)
; #define PG8_MMA(ai, bj, At, Bt) do { __builtin_amdgcn_s_setprio(1); _Pragma("unroll") for (int m = 0; m < 4; ++m) _Pragma("unroll") for (int n = 0; n < 2; ++n) _Pragma("unroll") for (int k = 0; k < 2; ++k) \
;         acc[ai][bj][m][n] = __builtin_amdgcn_mfma_f32_16x16x32_bf16(Bt[n][k], At[m][k], acc[ai][bj][m][n], 0, 0, 0); __builtin_amdgcn_s_setprio(0); } while (0)
; #define PG8_WAIT_V(n) asm volatile("s_waitcnt vmcnt(" #n ")" ::: "memory")
; #define PG8_WAIT_L(n) asm volatile("s_waitcnt lgkmcnt(" #n ")" ::: "memory")
; #define PG8_BAR __builtin_amdgcn_s_barrier()
; #define PG8_SCHED __builtin_amdgcn_sched_barrier(0)
; template <class Epi>
; __device__ __forceinline__ void gemm_phase(LAS unsigned char* lds, const Gemm g, const StaticOrder& S, const Epi& E) {
;     ...
;             PG8_LDA(At, 1, 1); PG8_STAGE(PG8_SB(1, 0), b3, voffB); PG8_STAGE(PG8_SB(1, 1), b3 + hstep, voffB); PG8_STAGE(PG8_SA(1, 0), a3, voffA);
;             PG8_WAIT_V(8); PG8_WAIT_L(0); PG8_BAR; PG8_MMA(1, 0, At, B0); PG8_MMA(1, 1, At, B1); PG8_BAR; PG8_SCHED;
;         }
;         if (wr == 0) PG8_BAR;
	s_add_i32 s56, s90, s24
	v_lshl_add_u64 v[212:213], v[222:223], 0, s[6:7]
	s_mov_b32 m0, s56
	ds_read_b128 v[202:205], v146 offset:49152
	ds_read_b128 v[206:209], v146 offset:50176
	ds_read_b128 v[226:229], v146 offset:51200
	ds_read_b128 v[230:233], v146 offset:52224
	ds_read_b128 v[234:237], v146 offset:53248
	ds_read_b128 v[238:241], v146 offset:54272
	ds_read_b128 v[242:245], v146 offset:55296
	ds_read_b128 v[246:249], v146 offset:56320
	global_load_lds_dwordx4 v[212:213], off
	s_add_i32 m0, s56, 0x2000
	s_add_u32 s54, s54, 0x80080
	v_lshl_add_u64 v[212:213], v[224:225], 0, s[6:7]
	s_addc_u32 s55, s55, 0
	s_add_i32 s56, s91, s24
	global_load_lds_dwordx4 v[212:213], off
	v_lshl_add_u64 v[212:213], s[54:55], 0, v[134:135]
	s_mov_b32 m0, s56
	s_nop 0
	global_load_lds_dwordx4 v[212:213], off
	v_lshl_add_u64 v[212:213], s[54:55], 0, v[130:131]
	s_add_i32 m0, s56, 0x2000
	s_nop 0
	global_load_lds_dwordx4 v[212:213], off
	v_lshl_add_u64 v[212:213], s[50:51], 0, v[136:137]
	s_mov_b32 m0, s52
	s_nop 0
	global_load_lds_dwordx4 v[212:213], off
	v_lshl_add_u64 v[212:213], s[50:51], 0, v[132:133]
	s_mov_b32 m0, s63
	s_nop 0
	global_load_lds_dwordx4 v[212:213], off
	s_waitcnt vmcnt(8)
	s_waitcnt lgkmcnt(0)
	s_barrier
	s_setprio 1
	v_mfma_f32_16x16x32_bf16 v[62:65], v[148:151], v[202:205], v[62:65]
	v_mfma_f32_16x16x32_bf16 v[58:61], v[156:159], v[202:205], v[58:61]
	v_mfma_f32_16x16x32_bf16 v[54:57], v[148:151], v[226:229], v[54:57]
	v_mfma_f32_16x16x32_bf16 v[46:49], v[156:159], v[226:229], v[46:49]
	v_mfma_f32_16x16x32_bf16 v[38:41], v[148:151], v[234:237], v[38:41]
	v_mfma_f32_16x16x32_bf16 v[30:33], v[156:159], v[234:237], v[30:33]
	v_mfma_f32_16x16x32_bf16 v[22:25], v[148:151], v[242:245], v[22:25]
	v_mfma_f32_16x16x32_bf16 v[14:17], v[156:159], v[242:245], v[14:17]
	v_mfma_f32_16x16x32_bf16 v[62:65], v[152:155], v[206:209], v[62:65]
	v_mfma_f32_16x16x32_bf16 v[58:61], v[160:163], v[206:209], v[58:61]
	v_mfma_f32_16x16x32_bf16 v[54:57], v[152:155], v[230:233], v[54:57]
	v_mfma_f32_16x16x32_bf16 v[46:49], v[160:163], v[230:233], v[46:49]
	v_mfma_f32_16x16x32_bf16 v[38:41], v[152:155], v[238:241], v[38:41]
	v_mfma_f32_16x16x32_bf16 v[30:33], v[160:163], v[238:241], v[30:33]
	v_mfma_f32_16x16x32_bf16 v[22:25], v[152:155], v[246:249], v[22:25]
	v_mfma_f32_16x16x32_bf16 v[14:17], v[160:163], v[246:249], v[14:17]
	v_mfma_f32_16x16x32_bf16 v[50:53], v[186:189], v[202:205], v[50:53]
	v_mfma_f32_16x16x32_bf16 v[42:45], v[194:197], v[202:205], v[42:45]
	v_mfma_f32_16x16x32_bf16 v[34:37], v[186:189], v[226:229], v[34:37]
	v_mfma_f32_16x16x32_bf16 v[26:29], v[194:197], v[226:229], v[26:29]
	v_mfma_f32_16x16x32_bf16 v[18:21], v[186:189], v[234:237], v[18:21]
	v_mfma_f32_16x16x32_bf16 v[10:13], v[194:197], v[234:237], v[10:13]
	v_mfma_f32_16x16x32_bf16 v[6:9], v[186:189], v[242:245], v[6:9]
	v_mfma_f32_16x16x32_bf16 v[2:5], v[194:197], v[242:245], v[2:5]
	v_mfma_f32_16x16x32_bf16 v[50:53], v[190:193], v[206:209], v[50:53]
	v_mfma_f32_16x16x32_bf16 v[42:45], v[198:201], v[206:209], v[42:45]
	v_mfma_f32_16x16x32_bf16 v[34:37], v[190:193], v[230:233], v[34:37]
	v_mfma_f32_16x16x32_bf16 v[26:29], v[198:201], v[230:233], v[26:29]
	v_mfma_f32_16x16x32_bf16 v[18:21], v[190:193], v[238:241], v[18:21]
	v_mfma_f32_16x16x32_bf16 v[10:13], v[198:201], v[238:241], v[10:13]
	v_mfma_f32_16x16x32_bf16 v[6:9], v[190:193], v[246:249], v[6:9]
	v_mfma_f32_16x16x32_bf16 v[2:5], v[198:201], v[246:249], v[2:5]
	s_setprio 0
	s_barrier
	s_add_i32 s96, s96, 2
	s_add_u32 s48, s48, 0x100
	s_addc_u32 s49, s49, 0
	s_cmp_gt_u32 s96, 29
	s_cbranch_scc0 .LBB0_233
	s_and_b64 vcc, exec, s[34:35]
	s_cbranch_vccz .LBB0_236
	s_barrier

; #define PG8_STAGE(bufoff, gbase, voff) do { _Pragma("unroll") for (int _i = 0; _i < 2; ++_i) \
;         __builtin_amdgcn_global_load_lds((const unsigned*)((const char*)(gbase) + (voff)[_i]), (LAS unsigned*)(lds + (bufoff) + ldsw + _i * 8192), 16, 0, 0); } while (0)
; #define PG8_LDA(dst, b, h) do { _Pragma("unroll") for (int m = 0; m < 4; ++m) _Pragma("unroll") for (int k = 0; k < 2; ++k) dst[m][k] = *(const LAS bf16x8*)(lds + PG8_SA(b, h) + aoff + m * 2048 + k * 1024); } while (0)
; #define PG8_LDB(dst, b, h) do { _Pragma("unroll") for (int n = 0; n < 2; ++n) _Pragma("unroll") for (int k = 0; k < 2; ++k) dst[n][k] = *(const LAS bf16x8*)(lds + PG8_SB(b, h) + boff + n * 2048 + k * 1024); } while (0)
; #define PG8_MMA(ai, bj, At, Bt) do { __builtin_amdgcn_s_setprio(1); _Pragma("unroll") for (int m = 0; m < 4; ++m) _Pragma("unroll") for (int n = 0; n < 2; ++n) _Pragma("unroll") for (int k = 0; k < 2; ++k) \
;         acc[ai][bj][m][n] = __builtin_amdgcn_mfma_f32_16x16x32_bf16(Bt[n][k], At[m][k], acc[ai][bj][m][n], 0, 0, 0); __builtin_amdgcn_s_setprio(0); } while (0)
; #define PG8_WAIT_V(n) asm volatile("s_waitcnt vmcnt(" #n ")" ::: "memory")
; #define PG8_WAIT_L(n) asm volatile("s_waitcnt lgkmcnt(" #n ")" ::: "memory")
; #define PG8_BAR __builtin_amdgcn_s_barrier()
; #define PG8_SCHED __builtin_amdgcn_sched_barrier(0)
; template <class Epi>
; __device__ __forceinline__ void gemm_phase(LAS unsigned char* lds, const Gemm g, const StaticOrder& S, const Epi& E) {
;     ...
;             const char* a1 = PG8_AP(cA, t + 1);
;             const char* a2 = last ? nA : PG8_AP(cA, t + 2); const char* b2 = last ? nB : cB + (size_t)(t + 2) * kstep;
;             const char* a3 = last ? nA + kstep : PG8_AP(cA, t + 3); const char* b3 = b2 + kstep;
;             PG8_LDB(B0, 0, 0); PG8_LDB(B1, 0, 1); PG8_SCHED; PG8_LDA(At, 0, 0); PG8_STAGE(PG8_SA(1, 1), a1 + hstepA, voffA);
;             PG8_WAIT_V(8); PG8_WAIT_L(0); PG8_BAR; PG8_MMA(0, 0, At, B0); PG8_MMA(0, 1, At, B1); PG8_BAR; PG8_SCHED;
;             PG8_LDA(At, 0, 1); PG8_STAGE(PG8_SB(0, 0), b2, voffB); PG8_STAGE(PG8_SB(0, 1), b2 + hstep, voffB); PG8_STAGE(PG8_SA(0, 0), a2, voffA);
.LBB0_253:
	s_add_u32 s50, s46, s48
	s_addc_u32 s51, s47, s49
	s_add_u32 s56, s50, 0x100
	s_addc_u32 s57, s51, 0
	s_add_u32 s54, s93, s48
	s_addc_u32 s55, s94, s49
	s_add_u32 s50, s50, 0x180
	s_addc_u32 s51, s51, 0
	s_add_i32 s90, 0, 0x10000
	s_add_i32 s91, 0, 0x14000
	v_add_u32_e32 v147, s90, v1
	ds_read_b128 v[148:151], v147
	ds_read_b128 v[152:155], v147 offset:1024
	ds_read_b128 v[156:159], v147 offset:2048
	ds_read_b128 v[160:163], v147 offset:3072
	v_add_u32_e32 v147, s91, v1
	ds_read_b128 v[186:189], v147
	ds_read_b128 v[190:193], v147 offset:1024
	ds_read_b128 v[194:197], v147 offset:2048
	ds_read_b128 v[198:201], v147 offset:3072
	s_cmpk_eq_i32 s48, 0xf00
	s_cselect_b32 s51, s92, s51
	s_cselect_b32 s50, s87, s50
	s_cselect_b32 s55, s37, s55
	s_cselect_b32 s54, s86, s54
	s_cselect_b32 s57, s41, s57
	s_cselect_b32 s56, s85, s56
	v_lshl_add_u64 v[212:213], v[142:143], 0, s[48:49]
	s_add_i32 m0, s25, 0xc000
	ds_read_b128 v[202:205], v146
	ds_read_b128 v[206:209], v146 offset:1024
	ds_read_b128 v[226:229], v146 offset:2048
	ds_read_b128 v[230:233], v146 offset:3072
	ds_read_b128 v[234:237], v146 offset:4096
	ds_read_b128 v[238:241], v146 offset:5120
	ds_read_b128 v[242:245], v146 offset:6144
	ds_read_b128 v[246:249], v146 offset:7168
	global_load_lds_dwordx4 v[212:213], off
	v_lshl_add_u64 v[212:213], v[144:145], 0, s[48:49]
	s_add_i32 m0, s25, 0xe000
	s_nop 0
	global_load_lds_dwordx4 v[212:213], off
	s_waitcnt vmcnt(8)
	s_waitcnt lgkmcnt(0)
	s_barrier
	s_setprio 1
	v_mfma_f32_16x16x32_bf16 v[126:129], v[148:151], v[202:205], v[126:129]
	v_mfma_f32_16x16x32_bf16 v[122:125], v[156:159], v[202:205], v[122:125]
	v_mfma_f32_16x16x32_bf16 v[118:121], v[148:151], v[226:229], v[118:121]
	v_mfma_f32_16x16x32_bf16 v[110:113], v[156:159], v[226:229], v[110:113]
	v_mfma_f32_16x16x32_bf16 v[102:105], v[148:151], v[234:237], v[102:105]
	v_mfma_f32_16x16x32_bf16 v[94:97], v[156:159], v[234:237], v[94:97]
	v_mfma_f32_16x16x32_bf16 v[86:89], v[148:151], v[242:245], v[86:89]
	v_mfma_f32_16x16x32_bf16 v[78:81], v[156:159], v[242:245], v[78:81]
	v_mfma_f32_16x16x32_bf16 v[126:129], v[152:155], v[206:209], v[126:129]
	v_mfma_f32_16x16x32_bf16 v[122:125], v[160:163], v[206:209], v[122:125]
	v_mfma_f32_16x16x32_bf16 v[118:121], v[152:155], v[230:233], v[118:121]
	v_mfma_f32_16x16x32_bf16 v[110:113], v[160:163], v[230:233], v[110:113]
	v_mfma_f32_16x16x32_bf16 v[102:105], v[152:155], v[238:241], v[102:105]
	v_mfma_f32_16x16x32_bf16 v[94:97], v[160:163], v[238:241], v[94:97]
	v_mfma_f32_16x16x32_bf16 v[86:89], v[152:155], v[246:249], v[86:89]
	v_mfma_f32_16x16x32_bf16 v[78:81], v[160:163], v[246:249], v[78:81]
	v_mfma_f32_16x16x32_bf16 v[114:117], v[186:189], v[202:205], v[114:117]
	v_mfma_f32_16x16x32_bf16 v[106:109], v[194:197], v[202:205], v[106:109]
	v_mfma_f32_16x16x32_bf16 v[98:101], v[186:189], v[226:229], v[98:101]
	v_mfma_f32_16x16x32_bf16 v[90:93], v[194:197], v[226:229], v[90:93]
	v_mfma_f32_16x16x32_bf16 v[82:85], v[186:189], v[234:237], v[82:85]
	v_mfma_f32_16x16x32_bf16 v[74:77], v[194:197], v[234:237], v[74:77]
	v_mfma_f32_16x16x32_bf16 v[70:73], v[186:189], v[242:245], v[70:73]
	v_mfma_f32_16x16x32_bf16 v[66:69], v[194:197], v[242:245], v[66:69]
	v_mfma_f32_16x16x32_bf16 v[114:117], v[190:193], v[206:209], v[114:117]
	v_mfma_f32_16x16x32_bf16 v[106:109], v[198:201], v[206:209], v[106:109]
	v_mfma_f32_16x16x32_bf16 v[98:101], v[190:193], v[230:233], v[98:101]
	v_mfma_f32_16x16x32_bf16 v[90:93], v[198:201], v[230:233], v[90:93]
	v_mfma_f32_16x16x32_bf16 v[82:85], v[190:193], v[238:241], v[82:85]
	v_mfma_f32_16x16x32_bf16 v[74:77], v[198:201], v[238:241], v[74:77]
	v_mfma_f32_16x16x32_bf16 v[70:73], v[190:193], v[246:249], v[70:73]
	v_mfma_f32_16x16x32_bf16 v[66:69], v[198:201], v[246:249], v[66:69]
	s_setprio 0
	s_barrier
	s_add_i32 s90, s90, s24
	v_lshl_add_u64 v[212:213], s[54:55], 0, v[134:135]
	s_mov_b32 m0, s90
	ds_read_b128 v[202:205], v146 offset:16384
	ds_read_b128 v[206:209], v146 offset:17408
	ds_read_b128 v[226:229], v146 offset:18432
	ds_read_b128 v[230:233], v146 offset:19456
	ds_read_b128 v[234:237], v146 offset:20480
	ds_read_b128 v[238:241], v146 offset:21504
	ds_read_b128 v[242:245], v146 offset:22528
	ds_read_b128 v[246:249], v146 offset:23552
	global_load_lds_dwordx4 v[212:213], off
	s_add_i32 m0, s90, 0x2000
	s_add_u32 vcc_lo, s54, 0x80000
	v_lshl_add_u64 v[222:223], s[54:55], 0, v[130:131]
	s_addc_u32 vcc_hi, s55, 0
	s_add_i32 s90, s91, s24
	global_load_lds_dwordx4 v[222:223], off
	v_lshl_add_u64 v[224:225], vcc, 0, v[134:135]
	s_mov_b32 m0, s90
	s_nop 0
	global_load_lds_dwordx4 v[224:225], off
	v_lshl_add_u64 v[224:225], vcc, 0, v[130:131]
	s_add_i32 m0, s90, 0x2000
	s_nop 0
	global_load_lds_dwordx4 v[224:225], off
	v_lshl_add_u64 v[224:225], s[56:57], 0, v[136:137]
	s_mov_b32 m0, s25
	s_nop 0
	global_load_lds_dwordx4 v[224:225], off
	v_lshl_add_u64 v[224:225], s[56:57], 0, v[132:133]
	s_mov_b32 m0, s26
	s_nop 0
	global_load_lds_dwordx4 v[224:225], off
	s_waitcnt vmcnt(8)
	s_waitcnt lgkmcnt(0)
	s_barrier
; #define PG8_STAGE(bufoff, gbase, voff) do { _Pragma("unroll") for (int _i = 0; _i < 2; ++_i) \
;         __builtin_amdgcn_global_load_lds((const unsigned*)((const char*)(gbase) + (voff)[_i]), (LAS unsigned*)(lds + (bufoff) + ldsw + _i * 8192), 16, 0, 0); } while (0)
; #define PG8_LDA(dst, b, h) do { _Pragma("unroll") for (int m = 0; m < 4; ++m) _Pragma("unroll") for (int k = 0; k < 2; ++k) dst[m][k] = *(const LAS bf16x8*)(lds + PG8_SA(b, h) + aoff + m * 2048 + k * 1024); } while (0)
; #define PG8_LDB(dst, b, h) do { _Pragma("unroll") for (int n = 0; n < 2; ++n) _Pragma("unroll") for (int k = 0; k < 2; ++k) dst[n][k] = *(const LAS bf16x8*)(lds + PG8_SB(b, h) + boff + n * 2048 + k * 1024); } while (0)
; #define PG8_MMA(ai, bj, At, Bt) do { __builtin_amdgcn_s_setprio(1); _Pragma("unroll") for (int m = 0; m < 4; ++m) _Pragma("unroll") for (int n = 0; n < 2; ++n) _Pragma("unroll") for (int k = 0; k < 2; ++k) \
;         acc[ai][bj][m][n] = __builtin_amdgcn_mfma_f32_16x16x32_bf16(Bt[n][k], At[m][k], acc[ai][bj][m][n], 0, 0, 0); __builtin_amdgcn_s_setprio(0); } while (0)
; #define PG8_WAIT_V(n) asm volatile("s_waitcnt vmcnt(" #n ")" ::: "memory")
; #define PG8_WAIT_L(n) asm volatile("s_waitcnt lgkmcnt(" #n ")" ::: "memory")
; #define PG8_BAR __builtin_amdgcn_s_barrier()
; #define PG8_SCHED __builtin_amdgcn_sched_barrier(0)
; template <class Epi>
; __device__ __forceinline__ void gemm_phase(LAS unsigned char* lds, const Gemm g, const StaticOrder& S, const Epi& E) {
;     ...
;             PG8_WAIT_V(8); PG8_WAIT_L(0); PG8_BAR; PG8_MMA(1, 0, At, B0); PG8_MMA(1, 1, At, B1); PG8_BAR; PG8_SCHED;
;             PG8_LDB(B0, 1, 0); PG8_LDB(B1, 1, 1); PG8_SCHED; PG8_LDA(At, 1, 0); PG8_STAGE(PG8_SA(0, 1), a2 + hstepA, voffA);
;             PG8_WAIT_V(8); PG8_WAIT_L(0); PG8_BAR; PG8_MMA(0, 0, At, B0); PG8_MMA(0, 1, At, B1); PG8_BAR; PG8_SCHED;
	s_setprio 1
	v_mfma_f32_16x16x32_bf16 v[62:65], v[148:151], v[202:205], v[62:65]
	v_mfma_f32_16x16x32_bf16 v[58:61], v[156:159], v[202:205], v[58:61]
	v_mfma_f32_16x16x32_bf16 v[54:57], v[148:151], v[226:229], v[54:57]
	v_mfma_f32_16x16x32_bf16 v[46:49], v[156:159], v[226:229], v[46:49]
	v_mfma_f32_16x16x32_bf16 v[38:41], v[148:151], v[234:237], v[38:41]
	v_mfma_f32_16x16x32_bf16 v[30:33], v[156:159], v[234:237], v[30:33]
	v_mfma_f32_16x16x32_bf16 v[22:25], v[148:151], v[242:245], v[22:25]
	v_mfma_f32_16x16x32_bf16 v[14:17], v[156:159], v[242:245], v[14:17]
	v_mfma_f32_16x16x32_bf16 v[62:65], v[152:155], v[206:209], v[62:65]
	v_mfma_f32_16x16x32_bf16 v[58:61], v[160:163], v[206:209], v[58:61]
	v_mfma_f32_16x16x32_bf16 v[54:57], v[152:155], v[230:233], v[54:57]
	v_mfma_f32_16x16x32_bf16 v[46:49], v[160:163], v[230:233], v[46:49]
	v_mfma_f32_16x16x32_bf16 v[38:41], v[152:155], v[238:241], v[38:41]
	v_mfma_f32_16x16x32_bf16 v[30:33], v[160:163], v[238:241], v[30:33]
	v_mfma_f32_16x16x32_bf16 v[22:25], v[152:155], v[246:249], v[22:25]
	v_mfma_f32_16x16x32_bf16 v[14:17], v[160:163], v[246:249], v[14:17]
	v_mfma_f32_16x16x32_bf16 v[50:53], v[186:189], v[202:205], v[50:53]
	v_mfma_f32_16x16x32_bf16 v[42:45], v[194:197], v[202:205], v[42:45]
	v_mfma_f32_16x16x32_bf16 v[34:37], v[186:189], v[226:229], v[34:37]
	v_mfma_f32_16x16x32_bf16 v[26:29], v[194:197], v[226:229], v[26:29]
	v_mfma_f32_16x16x32_bf16 v[18:21], v[186:189], v[234:237], v[18:21]
	v_mfma_f32_16x16x32_bf16 v[10:13], v[194:197], v[234:237], v[10:13]
	v_mfma_f32_16x16x32_bf16 v[6:9], v[186:189], v[242:245], v[6:9]
	v_mfma_f32_16x16x32_bf16 v[2:5], v[194:197], v[242:245], v[2:5]
	v_mfma_f32_16x16x32_bf16 v[50:53], v[190:193], v[206:209], v[50:53]
	v_mfma_f32_16x16x32_bf16 v[42:45], v[198:201], v[206:209], v[42:45]
	v_mfma_f32_16x16x32_bf16 v[34:37], v[190:193], v[230:233], v[34:37]
	v_mfma_f32_16x16x32_bf16 v[26:29], v[198:201], v[230:233], v[26:29]
	v_mfma_f32_16x16x32_bf16 v[18:21], v[190:193], v[238:241], v[18:21]
	v_mfma_f32_16x16x32_bf16 v[10:13], v[198:201], v[238:241], v[10:13]
	v_mfma_f32_16x16x32_bf16 v[6:9], v[190:193], v[246:249], v[6:9]
	v_mfma_f32_16x16x32_bf16 v[2:5], v[198:201], v[246:249], v[2:5]
	s_setprio 0
	s_barrier
	s_add_i32 s90, 0, 0x18000
	v_add_u32_e32 v147, s90, v1
	s_add_i32 s91, 0, 0x1c000
	ds_read_b128 v[148:151], v147
	ds_read_b128 v[152:155], v147 offset:1024
	ds_read_b128 v[156:159], v147 offset:2048
	ds_read_b128 v[160:163], v147 offset:3072
	v_add_u32_e32 v147, s91, v1
	ds_read_b128 v[186:189], v147
	ds_read_b128 v[190:193], v147 offset:1024
	ds_read_b128 v[194:197], v147 offset:2048
	ds_read_b128 v[198:201], v147 offset:3072
	s_add_u32 s56, s56, 0x80000
	s_addc_u32 s57, s57, 0
	s_mov_b32 m0, s27
	v_lshl_add_u64 v[224:225], s[56:57], 0, v[136:137]
	ds_read_b128 v[202:205], v146 offset:32768
	ds_read_b128 v[206:209], v146 offset:33792
	ds_read_b128 v[226:229], v146 offset:34816
	ds_read_b128 v[230:233], v146 offset:35840
	ds_read_b128 v[234:237], v146 offset:36864
	ds_read_b128 v[238:241], v146 offset:37888
	ds_read_b128 v[242:245], v146 offset:38912
	ds_read_b128 v[246:249], v146 offset:39936
	global_load_lds_dwordx4 v[224:225], off
	v_lshl_add_u64 v[224:225], s[56:57], 0, v[132:133]
	s_mov_b32 m0, s33
	s_nop 0
	global_load_lds_dwordx4 v[224:225], off
	s_waitcnt vmcnt(8)
	s_waitcnt lgkmcnt(0)
	s_barrier
	s_setprio 1
	v_mfma_f32_16x16x32_bf16 v[126:129], v[148:151], v[202:205], v[126:129]
	v_mfma_f32_16x16x32_bf16 v[122:125], v[156:159], v[202:205], v[122:125]
	v_mfma_f32_16x16x32_bf16 v[118:121], v[148:151], v[226:229], v[118:121]
	v_mfma_f32_16x16x32_bf16 v[110:113], v[156:159], v[226:229], v[110:113]
	v_mfma_f32_16x16x32_bf16 v[102:105], v[148:151], v[234:237], v[102:105]
	v_mfma_f32_16x16x32_bf16 v[94:97], v[156:159], v[234:237], v[94:97]
	v_mfma_f32_16x16x32_bf16 v[86:89], v[148:151], v[242:245], v[86:89]
	v_mfma_f32_16x16x32_bf16 v[78:81], v[156:159], v[242:245], v[78:81]
	v_mfma_f32_16x16x32_bf16 v[126:129], v[152:155], v[206:209], v[126:129]
	v_mfma_f32_16x16x32_bf16 v[122:125], v[160:163], v[206:209], v[122:125]
	v_mfma_f32_16x16x32_bf16 v[118:121], v[152:155], v[230:233], v[118:121]
	v_mfma_f32_16x16x32_bf16 v[110:113], v[160:163], v[230:233], v[110:113]
	v_mfma_f32_16x16x32_bf16 v[102:105], v[152:155], v[238:241], v[102:105]
	v_mfma_f32_16x16x32_bf16 v[94:97], v[160:163], v[238:241], v[94:97]
	v_mfma_f32_16x16x32_bf16 v[86:89], v[152:155], v[246:249], v[86:89]
	v_mfma_f32_16x16x32_bf16 v[78:81], v[160:163], v[246:249], v[78:81]
	v_mfma_f32_16x16x32_bf16 v[114:117], v[186:189], v[202:205], v[114:117]
	v_mfma_f32_16x16x32_bf16 v[106:109], v[194:197], v[202:205], v[106:109]
	v_mfma_f32_16x16x32_bf16 v[98:101], v[186:189], v[226:229], v[98:101]
	v_mfma_f32_16x16x32_bf16 v[90:93], v[194:197], v[226:229], v[90:93]
	v_mfma_f32_16x16x32_bf16 v[82:85], v[186:189], v[234:237], v[82:85]
	v_mfma_f32_16x16x32_bf16 v[74:77], v[194:197], v[234:237], v[74:77]
	v_mfma_f32_16x16x32_bf16 v[70:73], v[186:189], v[242:245], v[70:73]
	v_mfma_f32_16x16x32_bf16 v[66:69], v[194:197], v[242:245], v[66:69]
	v_mfma_f32_16x16x32_bf16 v[114:117], v[190:193], v[206:209], v[114:117]
	v_mfma_f32_16x16x32_bf16 v[106:109], v[198:201], v[206:209], v[106:109]
	v_mfma_f32_16x16x32_bf16 v[98:101], v[190:193], v[230:233], v[98:101]
	v_mfma_f32_16x16x32_bf16 v[90:93], v[198:201], v[230:233], v[90:93]
	v_mfma_f32_16x16x32_bf16 v[82:85], v[190:193], v[238:241], v[82:85]
	v_mfma_f32_16x16x32_bf16 v[74:77], v[198:201], v[238:241], v[74:77]
	v_mfma_f32_16x16x32_bf16 v[70:73], v[190:193], v[246:249], v[70:73]
	v_mfma_f32_16x16x32_bf16 v[66:69], v[198:201], v[246:249], v[66:69]
	s_setprio 0
	s_barrier
; #define PG8_STAGE(bufoff, gbase, voff) do { _Pragma("unroll") for (int _i = 0; _i < 2; ++_i) \
;         __builtin_amdgcn_global_load_lds((const unsigned*)((const char*)(gbase) + (voff)[_i]), (LAS unsigned*)(lds + (bufoff) + ldsw + _i * 8192), 16, 0, 0); } while (0)
; #define PG8_LDA(dst, b, h) do { _Pragma("unroll") for (int m = 0; m < 4; ++m) _Pragma("unroll") for (int k = 0; k < 2; ++k) dst[m][k] = *(const LAS bf16x8*)(lds + PG8_SA(b, h) + aoff + m * 2048 + k * 1024); } while (0)
; #define PG8_MMA(ai, bj, At, Bt) do { __builtin_amdgcn_s_setprio(1); _Pragma("unroll") for (int m = 0; m < 4; ++m) _Pragma("unroll") for (int n = 0; n < 2; ++n) _Pragma("unroll") for (int k = 0; k < 2; ++k) \
;         acc[ai][bj][m][n] = __builtin_amdgcn_mfma_f32_16x16x32_bf16(Bt[n][k], At[m][k], acc[ai][bj][m][n], 0, 0, 0); __builtin_amdgcn_s_setprio(0); } while (0)
; #define PG8_WAIT_V(n) asm volatile("s_waitcnt vmcnt(" #n ")" ::: "memory")
; #define PG8_WAIT_L(n) asm volatile("s_waitcnt lgkmcnt(" #n ")" ::: "memory")
; #define PG8_BAR __builtin_amdgcn_s_barrier()
; #define PG8_SCHED __builtin_amdgcn_sched_barrier(0)
; template <class Epi>
; __device__ __forceinline__ void gemm_phase(LAS unsigned char* lds, const Gemm g, const StaticOrder& S, const Epi& E) {
;     ...
;             PG8_LDA(At, 1, 1); PG8_STAGE(PG8_SB(1, 0), b3, voffB); PG8_STAGE(PG8_SB(1, 1), b3 + hstep, voffB); PG8_STAGE(PG8_SA(1, 0), a3, voffA);
;             PG8_WAIT_V(8); PG8_WAIT_L(0); PG8_BAR; PG8_MMA(1, 0, At, B0); PG8_MMA(1, 1, At, B1); PG8_BAR; PG8_SCHED;
;         }
;         if (wr == 0) PG8_BAR;
	s_add_i32 s56, s90, s24
	v_lshl_add_u64 v[212:213], v[212:213], 0, s[6:7]
	s_mov_b32 m0, s56
	ds_read_b128 v[202:205], v146 offset:49152
	ds_read_b128 v[206:209], v146 offset:50176
	ds_read_b128 v[226:229], v146 offset:51200
	ds_read_b128 v[230:233], v146 offset:52224
	ds_read_b128 v[234:237], v146 offset:53248
	ds_read_b128 v[238:241], v146 offset:54272
	ds_read_b128 v[242:245], v146 offset:55296
	ds_read_b128 v[246:249], v146 offset:56320
	global_load_lds_dwordx4 v[212:213], off
	s_add_i32 m0, s56, 0x2000
	s_add_u32 s54, s54, 0x80080
	v_lshl_add_u64 v[212:213], v[222:223], 0, s[6:7]
	s_addc_u32 s55, s55, 0
	s_add_i32 s56, s91, s24
	global_load_lds_dwordx4 v[212:213], off
	v_lshl_add_u64 v[212:213], s[54:55], 0, v[134:135]
	s_mov_b32 m0, s56
	s_nop 0
	global_load_lds_dwordx4 v[212:213], off
	v_lshl_add_u64 v[212:213], s[54:55], 0, v[130:131]
	s_add_i32 m0, s56, 0x2000
	s_nop 0
	global_load_lds_dwordx4 v[212:213], off
	v_lshl_add_u64 v[212:213], s[50:51], 0, v[136:137]
	s_mov_b32 m0, s52
	s_nop 0
	global_load_lds_dwordx4 v[212:213], off
	v_lshl_add_u64 v[212:213], s[50:51], 0, v[132:133]
	s_mov_b32 m0, s63
	s_nop 0
	global_load_lds_dwordx4 v[212:213], off
	s_waitcnt vmcnt(8)
	s_waitcnt lgkmcnt(0)
	s_barrier
	s_setprio 1
	v_mfma_f32_16x16x32_bf16 v[62:65], v[148:151], v[202:205], v[62:65]
	v_mfma_f32_16x16x32_bf16 v[58:61], v[156:159], v[202:205], v[58:61]
	v_mfma_f32_16x16x32_bf16 v[54:57], v[148:151], v[226:229], v[54:57]
	v_mfma_f32_16x16x32_bf16 v[46:49], v[156:159], v[226:229], v[46:49]
	v_mfma_f32_16x16x32_bf16 v[38:41], v[148:151], v[234:237], v[38:41]
	v_mfma_f32_16x16x32_bf16 v[30:33], v[156:159], v[234:237], v[30:33]
	v_mfma_f32_16x16x32_bf16 v[22:25], v[148:151], v[242:245], v[22:25]
	v_mfma_f32_16x16x32_bf16 v[14:17], v[156:159], v[242:245], v[14:17]
	v_mfma_f32_16x16x32_bf16 v[62:65], v[152:155], v[206:209], v[62:65]
	v_mfma_f32_16x16x32_bf16 v[58:61], v[160:163], v[206:209], v[58:61]
	v_mfma_f32_16x16x32_bf16 v[54:57], v[152:155], v[230:233], v[54:57]
	v_mfma_f32_16x16x32_bf16 v[46:49], v[160:163], v[230:233], v[46:49]
	v_mfma_f32_16x16x32_bf16 v[38:41], v[152:155], v[238:241], v[38:41]
	v_mfma_f32_16x16x32_bf16 v[30:33], v[160:163], v[238:241], v[30:33]
	v_mfma_f32_16x16x32_bf16 v[22:25], v[152:155], v[246:249], v[22:25]
	v_mfma_f32_16x16x32_bf16 v[14:17], v[160:163], v[246:249], v[14:17]
	v_mfma_f32_16x16x32_bf16 v[50:53], v[186:189], v[202:205], v[50:53]
	v_mfma_f32_16x16x32_bf16 v[42:45], v[194:197], v[202:205], v[42:45]
	v_mfma_f32_16x16x32_bf16 v[34:37], v[186:189], v[226:229], v[34:37]
	v_mfma_f32_16x16x32_bf16 v[26:29], v[194:197], v[226:229], v[26:29]
	v_mfma_f32_16x16x32_bf16 v[18:21], v[186:189], v[234:237], v[18:21]
	v_mfma_f32_16x16x32_bf16 v[10:13], v[194:197], v[234:237], v[10:13]
	v_mfma_f32_16x16x32_bf16 v[6:9], v[186:189], v[242:245], v[6:9]
	v_mfma_f32_16x16x32_bf16 v[2:5], v[194:197], v[242:245], v[2:5]
	v_mfma_f32_16x16x32_bf16 v[50:53], v[190:193], v[206:209], v[50:53]
	v_mfma_f32_16x16x32_bf16 v[42:45], v[198:201], v[206:209], v[42:45]
	v_mfma_f32_16x16x32_bf16 v[34:37], v[190:193], v[230:233], v[34:37]
	v_mfma_f32_16x16x32_bf16 v[26:29], v[198:201], v[230:233], v[26:29]
	v_mfma_f32_16x16x32_bf16 v[18:21], v[190:193], v[238:241], v[18:21]
	v_mfma_f32_16x16x32_bf16 v[10:13], v[198:201], v[238:241], v[10:13]
	v_mfma_f32_16x16x32_bf16 v[6:9], v[190:193], v[246:249], v[6:9]
	v_mfma_f32_16x16x32_bf16 v[2:5], v[198:201], v[246:249], v[2:5]
	s_setprio 0
	s_barrier
	s_add_i32 s96, s96, 2
	s_add_u32 s48, s48, 0x100
	s_addc_u32 s49, s49, 0
	s_cmp_gt_u32 s96, 29
	s_cbranch_scc0 .LBB0_253
	s_and_b64 vcc, exec, s[34:35]
	s_cbranch_vccz .LBB0_256
	s_barrier

; #define PG8_STAGE(bufoff, gbase, voff) do { _Pragma("unroll") for (int _i = 0; _i < 2; ++_i) \
;         __builtin_amdgcn_global_load_lds((const unsigned*)((const char*)(gbase) + (voff)[_i]), (LAS unsigned*)(lds + (bufoff) + ldsw + _i * 8192), 16, 0, 0); } while (0)
; #define PG8_LDA(dst, b, h) do { _Pragma("unroll") for (int m = 0; m < 4; ++m) _Pragma("unroll") for (int k = 0; k < 2; ++k) dst[m][k] = *(const LAS bf16x8*)(lds + PG8_SA(b, h) + aoff + m * 2048 + k * 1024); } while (0)
; #define PG8_LDB(dst, b, h) do { _Pragma("unroll") for (int n = 0; n < 2; ++n) _Pragma("unroll") for (int k = 0; k < 2; ++k) dst[n][k] = *(const LAS bf16x8*)(lds + PG8_SB(b, h) + boff + n * 2048 + k * 1024); } while (0)
; #define PG8_MMA(ai, bj, At, Bt) do { __builtin_amdgcn_s_setprio(1); _Pragma("unroll") for (int m = 0; m < 4; ++m) _Pragma("unroll") for (int n = 0; n < 2; ++n) _Pragma("unroll") for (int k = 0; k < 2; ++k) \
;         acc[ai][bj][m][n] = __builtin_amdgcn_mfma_f32_16x16x32_bf16(Bt[n][k], At[m][k], acc[ai][bj][m][n], 0, 0, 0); __builtin_amdgcn_s_setprio(0); } while (0)
; #define PG8_WAIT_V(n) asm volatile("s_waitcnt vmcnt(" #n ")" ::: "memory")
; #define PG8_WAIT_L(n) asm volatile("s_waitcnt lgkmcnt(" #n ")" ::: "memory")
; #define PG8_BAR __builtin_amdgcn_s_barrier()
; #define PG8_SCHED __builtin_amdgcn_sched_barrier(0)
; template <class Epi>
; __device__ __forceinline__ void gemm_phase(LAS unsigned char* lds, const Gemm g, const StaticOrder& S, const Epi& E) {
;     ...
;             const char* a1 = PG8_AP(cA, t + 1);
;             const char* a2 = last ? nA : PG8_AP(cA, t + 2); const char* b2 = last ? nB : cB + (size_t)(t + 2) * kstep;
;             const char* a3 = last ? nA + kstep : PG8_AP(cA, t + 3); const char* b3 = b2 + kstep;
;             PG8_LDB(B0, 0, 0); PG8_LDB(B1, 0, 1); PG8_SCHED; PG8_LDA(At, 0, 0); PG8_STAGE(PG8_SA(1, 1), a1 + hstepA, voffA);
;             PG8_WAIT_V(8); PG8_WAIT_L(0); PG8_BAR; PG8_MMA(0, 0, At, B0); PG8_MMA(0, 1, At, B1); PG8_BAR; PG8_SCHED;
;             PG8_LDA(At, 0, 1); PG8_STAGE(PG8_SB(0, 0), b2, voffB); PG8_STAGE(PG8_SB(0, 1), b2 + hstep, voffB); PG8_STAGE(PG8_SA(0, 0), a2, voffA);
.LBB0_277:
	s_add_u32 s86, s54, s56
	s_addc_u32 s87, s55, s57
	s_add_u32 s90, s86, 0x100
	s_addc_u32 s91, s87, 0
	s_add_u32 s92, s80, s56
	s_addc_u32 s93, s81, s57
	s_add_u32 s86, s86, 0x180
	s_addc_u32 s87, s87, 0
	s_add_i32 s94, 0, 0x10000
	s_add_i32 s12, 0, 0x14000
	v_add_u32_e32 v147, s94, v1
	ds_read_b128 v[148:151], v147
	ds_read_b128 v[152:155], v147 offset:1024
	ds_read_b128 v[156:159], v147 offset:2048
	ds_read_b128 v[160:163], v147 offset:3072
	v_add_u32_e32 v147, s12, v1
	ds_read_b128 v[186:189], v147
	ds_read_b128 v[190:193], v147 offset:1024
	ds_read_b128 v[194:197], v147 offset:2048
	ds_read_b128 v[198:201], v147 offset:3072
	s_cmpk_eq_i32 s56, 0xf00
	s_cselect_b32 s97, s67, s87
	s_cselect_b32 s96, s63, s86
	s_cselect_b32 vcc_hi, s43, s93
	s_cselect_b32 vcc_lo, s52, s92
	s_cselect_b32 s87, s41, s91
	s_cselect_b32 s86, s45, s90
	v_lshl_add_u64 v[212:213], v[142:143], 0, s[56:57]
	s_add_i32 m0, s25, 0xc000
	ds_read_b128 v[202:205], v146
	ds_read_b128 v[206:209], v146 offset:1024
	ds_read_b128 v[226:229], v146 offset:2048
	ds_read_b128 v[230:233], v146 offset:3072
	ds_read_b128 v[234:237], v146 offset:4096
	ds_read_b128 v[238:241], v146 offset:5120
	ds_read_b128 v[242:245], v146 offset:6144
	ds_read_b128 v[246:249], v146 offset:7168
	global_load_lds_dwordx4 v[212:213], off
	v_lshl_add_u64 v[212:213], v[144:145], 0, s[56:57]
	s_add_i32 m0, s25, 0xe000
	s_nop 0
	global_load_lds_dwordx4 v[212:213], off
	s_waitcnt vmcnt(8)
	s_waitcnt lgkmcnt(0)
	s_barrier
	s_setprio 1
	v_mfma_f32_16x16x32_bf16 v[126:129], v[148:151], v[202:205], v[126:129]
	v_mfma_f32_16x16x32_bf16 v[122:125], v[156:159], v[202:205], v[122:125]
	v_mfma_f32_16x16x32_bf16 v[110:113], v[148:151], v[226:229], v[110:113]
	v_mfma_f32_16x16x32_bf16 v[106:109], v[156:159], v[226:229], v[106:109]
	v_mfma_f32_16x16x32_bf16 v[94:97], v[148:151], v[234:237], v[94:97]
	v_mfma_f32_16x16x32_bf16 v[90:93], v[156:159], v[234:237], v[90:93]
	v_mfma_f32_16x16x32_bf16 v[78:81], v[148:151], v[242:245], v[78:81]
	v_mfma_f32_16x16x32_bf16 v[74:77], v[156:159], v[242:245], v[74:77]
	v_mfma_f32_16x16x32_bf16 v[126:129], v[152:155], v[206:209], v[126:129]
	v_mfma_f32_16x16x32_bf16 v[122:125], v[160:163], v[206:209], v[122:125]
	v_mfma_f32_16x16x32_bf16 v[110:113], v[152:155], v[230:233], v[110:113]
	v_mfma_f32_16x16x32_bf16 v[106:109], v[160:163], v[230:233], v[106:109]
	v_mfma_f32_16x16x32_bf16 v[94:97], v[152:155], v[238:241], v[94:97]
	v_mfma_f32_16x16x32_bf16 v[90:93], v[160:163], v[238:241], v[90:93]
	v_mfma_f32_16x16x32_bf16 v[78:81], v[152:155], v[246:249], v[78:81]
	v_mfma_f32_16x16x32_bf16 v[74:77], v[160:163], v[246:249], v[74:77]
	v_mfma_f32_16x16x32_bf16 v[118:121], v[186:189], v[202:205], v[118:121]
	v_mfma_f32_16x16x32_bf16 v[114:117], v[194:197], v[202:205], v[114:117]
	v_mfma_f32_16x16x32_bf16 v[102:105], v[186:189], v[226:229], v[102:105]
	v_mfma_f32_16x16x32_bf16 v[98:101], v[194:197], v[226:229], v[98:101]
	v_mfma_f32_16x16x32_bf16 v[86:89], v[186:189], v[234:237], v[86:89]
	v_mfma_f32_16x16x32_bf16 v[82:85], v[194:197], v[234:237], v[82:85]
	v_mfma_f32_16x16x32_bf16 v[70:73], v[186:189], v[242:245], v[70:73]
	v_mfma_f32_16x16x32_bf16 v[66:69], v[194:197], v[242:245], v[66:69]
	v_mfma_f32_16x16x32_bf16 v[118:121], v[190:193], v[206:209], v[118:121]
	v_mfma_f32_16x16x32_bf16 v[114:117], v[198:201], v[206:209], v[114:117]
	v_mfma_f32_16x16x32_bf16 v[102:105], v[190:193], v[230:233], v[102:105]
	v_mfma_f32_16x16x32_bf16 v[98:101], v[198:201], v[230:233], v[98:101]
	v_mfma_f32_16x16x32_bf16 v[86:89], v[190:193], v[238:241], v[86:89]
	v_mfma_f32_16x16x32_bf16 v[82:85], v[198:201], v[238:241], v[82:85]
	v_mfma_f32_16x16x32_bf16 v[70:73], v[190:193], v[246:249], v[70:73]
	v_mfma_f32_16x16x32_bf16 v[66:69], v[198:201], v[246:249], v[66:69]
	s_setprio 0
	s_barrier
	s_add_i32 s13, s94, s24
	v_lshl_add_u64 v[212:213], vcc, 0, v[132:133]
	s_mov_b32 m0, s13
	ds_read_b128 v[202:205], v146 offset:16384
	ds_read_b128 v[206:209], v146 offset:17408
	ds_read_b128 v[226:229], v146 offset:18432
	ds_read_b128 v[230:233], v146 offset:19456
	ds_read_b128 v[234:237], v146 offset:20480
	ds_read_b128 v[238:241], v146 offset:21504
	ds_read_b128 v[242:245], v146 offset:22528
	ds_read_b128 v[246:249], v146 offset:23552
	global_load_lds_dwordx4 v[212:213], off
	s_add_i32 m0, s13, 0x2000
	s_add_u32 s92, vcc_lo, 0x80000
	v_lshl_add_u64 v[222:223], vcc, 0, v[136:137]
	s_addc_u32 s93, vcc_hi, 0
	s_add_i32 s12, s12, s24
	global_load_lds_dwordx4 v[222:223], off
	v_lshl_add_u64 v[224:225], s[92:93], 0, v[132:133]
	s_mov_b32 m0, s12
	s_nop 0
	global_load_lds_dwordx4 v[224:225], off
	v_lshl_add_u64 v[224:225], s[92:93], 0, v[136:137]
	s_add_i32 m0, s12, 0x2000
	s_nop 0
	global_load_lds_dwordx4 v[224:225], off
	v_lshl_add_u64 v[224:225], s[86:87], 0, v[130:131]
	s_mov_b32 m0, s25
	s_nop 0
	global_load_lds_dwordx4 v[224:225], off
	v_lshl_add_u64 v[224:225], s[86:87], 0, v[134:135]
	s_mov_b32 m0, s26
	s_nop 0
	global_load_lds_dwordx4 v[224:225], off
	s_waitcnt vmcnt(8)
	s_waitcnt lgkmcnt(0)
	s_barrier
; #define PG8_STAGE(bufoff, gbase, voff) do { _Pragma("unroll") for (int _i = 0; _i < 2; ++_i) \
;         __builtin_amdgcn_global_load_lds((const unsigned*)((const char*)(gbase) + (voff)[_i]), (LAS unsigned*)(lds + (bufoff) + ldsw + _i * 8192), 16, 0, 0); } while (0)
; #define PG8_LDA(dst, b, h) do { _Pragma("unroll") for (int m = 0; m < 4; ++m) _Pragma("unroll") for (int k = 0; k < 2; ++k) dst[m][k] = *(const LAS bf16x8*)(lds + PG8_SA(b, h) + aoff + m * 2048 + k * 1024); } while (0)
; #define PG8_LDB(dst, b, h) do { _Pragma("unroll") for (int n = 0; n < 2; ++n) _Pragma("unroll") for (int k = 0; k < 2; ++k) dst[n][k] = *(const LAS bf16x8*)(lds + PG8_SB(b, h) + boff + n * 2048 + k * 1024); } while (0)
; #define PG8_MMA(ai, bj, At, Bt) do { __builtin_amdgcn_s_setprio(1); _Pragma("unroll") for (int m = 0; m < 4; ++m) _Pragma("unroll") for (int n = 0; n < 2; ++n) _Pragma("unroll") for (int k = 0; k < 2; ++k) \
;         acc[ai][bj][m][n] = __builtin_amdgcn_mfma_f32_16x16x32_bf16(Bt[n][k], At[m][k], acc[ai][bj][m][n], 0, 0, 0); __builtin_amdgcn_s_setprio(0); } while (0)
; #define PG8_WAIT_V(n) asm volatile("s_waitcnt vmcnt(" #n ")" ::: "memory")
; #define PG8_WAIT_L(n) asm volatile("s_waitcnt lgkmcnt(" #n ")" ::: "memory")
; #define PG8_BAR __builtin_amdgcn_s_barrier()
; #define PG8_SCHED __builtin_amdgcn_sched_barrier(0)
; template <class Epi>
; __device__ __forceinline__ void gemm_phase(LAS unsigned char* lds, const Gemm g, const StaticOrder& S, const Epi& E) {
;     ...
;             PG8_WAIT_V(8); PG8_WAIT_L(0); PG8_BAR; PG8_MMA(1, 0, At, B0); PG8_MMA(1, 1, At, B1); PG8_BAR; PG8_SCHED;
;             PG8_LDB(B0, 1, 0); PG8_LDB(B1, 1, 1); PG8_SCHED; PG8_LDA(At, 1, 0); PG8_STAGE(PG8_SA(0, 1), a2 + hstepA, voffA);
;             PG8_WAIT_V(8); PG8_WAIT_L(0); PG8_BAR; PG8_MMA(0, 0, At, B0); PG8_MMA(0, 1, At, B1); PG8_BAR; PG8_SCHED;
	s_setprio 1
	v_mfma_f32_16x16x32_bf16 v[62:65], v[148:151], v[202:205], v[62:65]
	v_mfma_f32_16x16x32_bf16 v[58:61], v[156:159], v[202:205], v[58:61]
	v_mfma_f32_16x16x32_bf16 v[46:49], v[148:151], v[226:229], v[46:49]
	v_mfma_f32_16x16x32_bf16 v[42:45], v[156:159], v[226:229], v[42:45]
	v_mfma_f32_16x16x32_bf16 v[30:33], v[148:151], v[234:237], v[30:33]
	v_mfma_f32_16x16x32_bf16 v[26:29], v[156:159], v[234:237], v[26:29]
	v_mfma_f32_16x16x32_bf16 v[14:17], v[148:151], v[242:245], v[14:17]
	v_mfma_f32_16x16x32_bf16 v[10:13], v[156:159], v[242:245], v[10:13]
	v_mfma_f32_16x16x32_bf16 v[62:65], v[152:155], v[206:209], v[62:65]
	v_mfma_f32_16x16x32_bf16 v[58:61], v[160:163], v[206:209], v[58:61]
	v_mfma_f32_16x16x32_bf16 v[46:49], v[152:155], v[230:233], v[46:49]
	v_mfma_f32_16x16x32_bf16 v[42:45], v[160:163], v[230:233], v[42:45]
	v_mfma_f32_16x16x32_bf16 v[30:33], v[152:155], v[238:241], v[30:33]
	v_mfma_f32_16x16x32_bf16 v[26:29], v[160:163], v[238:241], v[26:29]
	v_mfma_f32_16x16x32_bf16 v[14:17], v[152:155], v[246:249], v[14:17]
	v_mfma_f32_16x16x32_bf16 v[10:13], v[160:163], v[246:249], v[10:13]
	v_mfma_f32_16x16x32_bf16 v[54:57], v[186:189], v[202:205], v[54:57]
	v_mfma_f32_16x16x32_bf16 v[50:53], v[194:197], v[202:205], v[50:53]
	v_mfma_f32_16x16x32_bf16 v[38:41], v[186:189], v[226:229], v[38:41]
	v_mfma_f32_16x16x32_bf16 v[34:37], v[194:197], v[226:229], v[34:37]
	v_mfma_f32_16x16x32_bf16 v[22:25], v[186:189], v[234:237], v[22:25]
	v_mfma_f32_16x16x32_bf16 v[18:21], v[194:197], v[234:237], v[18:21]
	v_mfma_f32_16x16x32_bf16 v[6:9], v[186:189], v[242:245], v[6:9]
	v_mfma_f32_16x16x32_bf16 v[2:5], v[194:197], v[242:245], v[2:5]
	v_mfma_f32_16x16x32_bf16 v[54:57], v[190:193], v[206:209], v[54:57]
	v_mfma_f32_16x16x32_bf16 v[50:53], v[198:201], v[206:209], v[50:53]
	v_mfma_f32_16x16x32_bf16 v[38:41], v[190:193], v[230:233], v[38:41]
	v_mfma_f32_16x16x32_bf16 v[34:37], v[198:201], v[230:233], v[34:37]
	v_mfma_f32_16x16x32_bf16 v[22:25], v[190:193], v[238:241], v[22:25]
	v_mfma_f32_16x16x32_bf16 v[18:21], v[198:201], v[238:241], v[18:21]
	v_mfma_f32_16x16x32_bf16 v[6:9], v[190:193], v[246:249], v[6:9]
	v_mfma_f32_16x16x32_bf16 v[2:5], v[198:201], v[246:249], v[2:5]
	s_setprio 0
	s_barrier
	s_add_i32 s12, 0, 0x18000
	v_add_u32_e32 v147, s12, v1
	s_add_i32 s13, 0, 0x1c000
	ds_read_b128 v[148:151], v147
	ds_read_b128 v[152:155], v147 offset:1024
	ds_read_b128 v[156:159], v147 offset:2048
	ds_read_b128 v[160:163], v147 offset:3072
	v_add_u32_e32 v147, s13, v1
	ds_read_b128 v[186:189], v147
	ds_read_b128 v[190:193], v147 offset:1024
	ds_read_b128 v[194:197], v147 offset:2048
	ds_read_b128 v[198:201], v147 offset:3072
	s_add_u32 s86, s86, 0x80000
	s_addc_u32 s87, s87, 0
	s_mov_b32 m0, s27
	v_lshl_add_u64 v[224:225], s[86:87], 0, v[130:131]
	ds_read_b128 v[202:205], v146 offset:32768
	ds_read_b128 v[206:209], v146 offset:33792
	ds_read_b128 v[226:229], v146 offset:34816
	ds_read_b128 v[230:233], v146 offset:35840
	ds_read_b128 v[234:237], v146 offset:36864
	ds_read_b128 v[238:241], v146 offset:37888
	ds_read_b128 v[242:245], v146 offset:38912
	ds_read_b128 v[246:249], v146 offset:39936
	global_load_lds_dwordx4 v[224:225], off
	v_lshl_add_u64 v[224:225], s[86:87], 0, v[134:135]
	s_mov_b32 m0, s28
	s_nop 0
	global_load_lds_dwordx4 v[224:225], off
	s_waitcnt vmcnt(8)
	s_waitcnt lgkmcnt(0)
	s_barrier
	s_setprio 1
	v_mfma_f32_16x16x32_bf16 v[126:129], v[148:151], v[202:205], v[126:129]
	v_mfma_f32_16x16x32_bf16 v[122:125], v[156:159], v[202:205], v[122:125]
	v_mfma_f32_16x16x32_bf16 v[110:113], v[148:151], v[226:229], v[110:113]
	v_mfma_f32_16x16x32_bf16 v[106:109], v[156:159], v[226:229], v[106:109]
	v_mfma_f32_16x16x32_bf16 v[94:97], v[148:151], v[234:237], v[94:97]
	v_mfma_f32_16x16x32_bf16 v[90:93], v[156:159], v[234:237], v[90:93]
	v_mfma_f32_16x16x32_bf16 v[78:81], v[148:151], v[242:245], v[78:81]
	v_mfma_f32_16x16x32_bf16 v[74:77], v[156:159], v[242:245], v[74:77]
	v_mfma_f32_16x16x32_bf16 v[126:129], v[152:155], v[206:209], v[126:129]
	v_mfma_f32_16x16x32_bf16 v[122:125], v[160:163], v[206:209], v[122:125]
	v_mfma_f32_16x16x32_bf16 v[110:113], v[152:155], v[230:233], v[110:113]
	v_mfma_f32_16x16x32_bf16 v[106:109], v[160:163], v[230:233], v[106:109]
	v_mfma_f32_16x16x32_bf16 v[94:97], v[152:155], v[238:241], v[94:97]
	v_mfma_f32_16x16x32_bf16 v[90:93], v[160:163], v[238:241], v[90:93]
	v_mfma_f32_16x16x32_bf16 v[78:81], v[152:155], v[246:249], v[78:81]
	v_mfma_f32_16x16x32_bf16 v[74:77], v[160:163], v[246:249], v[74:77]
	v_mfma_f32_16x16x32_bf16 v[118:121], v[186:189], v[202:205], v[118:121]
	v_mfma_f32_16x16x32_bf16 v[114:117], v[194:197], v[202:205], v[114:117]
	v_mfma_f32_16x16x32_bf16 v[102:105], v[186:189], v[226:229], v[102:105]
	v_mfma_f32_16x16x32_bf16 v[98:101], v[194:197], v[226:229], v[98:101]
	v_mfma_f32_16x16x32_bf16 v[86:89], v[186:189], v[234:237], v[86:89]
	v_mfma_f32_16x16x32_bf16 v[82:85], v[194:197], v[234:237], v[82:85]
	v_mfma_f32_16x16x32_bf16 v[70:73], v[186:189], v[242:245], v[70:73]
	v_mfma_f32_16x16x32_bf16 v[66:69], v[194:197], v[242:245], v[66:69]
	v_mfma_f32_16x16x32_bf16 v[118:121], v[190:193], v[206:209], v[118:121]
	v_mfma_f32_16x16x32_bf16 v[114:117], v[198:201], v[206:209], v[114:117]
	v_mfma_f32_16x16x32_bf16 v[102:105], v[190:193], v[230:233], v[102:105]
	v_mfma_f32_16x16x32_bf16 v[98:101], v[198:201], v[230:233], v[98:101]
	v_mfma_f32_16x16x32_bf16 v[86:89], v[190:193], v[238:241], v[86:89]
	v_mfma_f32_16x16x32_bf16 v[82:85], v[198:201], v[238:241], v[82:85]
	v_mfma_f32_16x16x32_bf16 v[70:73], v[190:193], v[246:249], v[70:73]
	v_mfma_f32_16x16x32_bf16 v[66:69], v[198:201], v[246:249], v[66:69]
	s_setprio 0
	s_barrier
; #define PG8_STAGE(bufoff, gbase, voff) do { _Pragma("unroll") for (int _i = 0; _i < 2; ++_i) \
;         __builtin_amdgcn_global_load_lds((const unsigned*)((const char*)(gbase) + (voff)[_i]), (LAS unsigned*)(lds + (bufoff) + ldsw + _i * 8192), 16, 0, 0); } while (0)
; #define PG8_LDA(dst, b, h) do { _Pragma("unroll") for (int m = 0; m < 4; ++m) _Pragma("unroll") for (int k = 0; k < 2; ++k) dst[m][k] = *(const LAS bf16x8*)(lds + PG8_SA(b, h) + aoff + m * 2048 + k * 1024); } while (0)
; #define PG8_MMA(ai, bj, At, Bt) do { __builtin_amdgcn_s_setprio(1); _Pragma("unroll") for (int m = 0; m < 4; ++m) _Pragma("unroll") for (int n = 0; n < 2; ++n) _Pragma("unroll") for (int k = 0; k < 2; ++k) \
;         acc[ai][bj][m][n] = __builtin_amdgcn_mfma_f32_16x16x32_bf16(Bt[n][k], At[m][k], acc[ai][bj][m][n], 0, 0, 0); __builtin_amdgcn_s_setprio(0); } while (0)
; #define PG8_WAIT_V(n) asm volatile("s_waitcnt vmcnt(" #n ")" ::: "memory")
; #define PG8_WAIT_L(n) asm volatile("s_waitcnt lgkmcnt(" #n ")" ::: "memory")
; #define PG8_BAR __builtin_amdgcn_s_barrier()
; #define PG8_SCHED __builtin_amdgcn_sched_barrier(0)
; template <class Epi>
; __device__ __forceinline__ void gemm_phase(LAS unsigned char* lds, const Gemm g, const StaticOrder& S, const Epi& E) {
;     ...
;             PG8_LDA(At, 1, 1); PG8_STAGE(PG8_SB(1, 0), b3, voffB); PG8_STAGE(PG8_SB(1, 1), b3 + hstep, voffB); PG8_STAGE(PG8_SA(1, 0), a3, voffA);
;             PG8_WAIT_V(8); PG8_WAIT_L(0); PG8_BAR; PG8_MMA(1, 0, At, B0); PG8_MMA(1, 1, At, B1); PG8_BAR; PG8_SCHED;
;         }
;         if (wr == 0) PG8_BAR;
	s_add_i32 s12, s12, s24
	v_lshl_add_u64 v[212:213], v[212:213], 0, s[6:7]
	s_mov_b32 m0, s12
	ds_read_b128 v[202:205], v146 offset:49152
	ds_read_b128 v[206:209], v146 offset:50176
	ds_read_b128 v[226:229], v146 offset:51200
	ds_read_b128 v[230:233], v146 offset:52224
	ds_read_b128 v[234:237], v146 offset:53248
	ds_read_b128 v[238:241], v146 offset:54272
	ds_read_b128 v[242:245], v146 offset:55296
	ds_read_b128 v[246:249], v146 offset:56320
	global_load_lds_dwordx4 v[212:213], off
	s_add_i32 m0, s12, 0x2000
	s_add_u32 s86, vcc_lo, 0x80080
	v_lshl_add_u64 v[212:213], v[222:223], 0, s[6:7]
	s_addc_u32 s87, vcc_hi, 0
	s_add_i32 s12, s13, s24
	global_load_lds_dwordx4 v[212:213], off
	v_lshl_add_u64 v[212:213], s[86:87], 0, v[132:133]
	s_mov_b32 m0, s12
	s_nop 0
	global_load_lds_dwordx4 v[212:213], off
	v_lshl_add_u64 v[212:213], s[86:87], 0, v[136:137]
	s_add_i32 m0, s12, 0x2000
	s_nop 0
	global_load_lds_dwordx4 v[212:213], off
	v_lshl_add_u64 v[212:213], s[96:97], 0, v[130:131]
	s_mov_b32 m0, s29
	s_nop 0
	global_load_lds_dwordx4 v[212:213], off
	v_lshl_add_u64 v[212:213], s[96:97], 0, v[134:135]
	s_mov_b32 m0, s33
	s_nop 0
	global_load_lds_dwordx4 v[212:213], off
	s_waitcnt vmcnt(8)
	s_waitcnt lgkmcnt(0)
	s_barrier
	s_setprio 1
	v_mfma_f32_16x16x32_bf16 v[62:65], v[148:151], v[202:205], v[62:65]
	v_mfma_f32_16x16x32_bf16 v[58:61], v[156:159], v[202:205], v[58:61]
	v_mfma_f32_16x16x32_bf16 v[46:49], v[148:151], v[226:229], v[46:49]
	v_mfma_f32_16x16x32_bf16 v[42:45], v[156:159], v[226:229], v[42:45]
	v_mfma_f32_16x16x32_bf16 v[30:33], v[148:151], v[234:237], v[30:33]
	v_mfma_f32_16x16x32_bf16 v[26:29], v[156:159], v[234:237], v[26:29]
	v_mfma_f32_16x16x32_bf16 v[14:17], v[148:151], v[242:245], v[14:17]
	v_mfma_f32_16x16x32_bf16 v[10:13], v[156:159], v[242:245], v[10:13]
	v_mfma_f32_16x16x32_bf16 v[62:65], v[152:155], v[206:209], v[62:65]
	v_mfma_f32_16x16x32_bf16 v[58:61], v[160:163], v[206:209], v[58:61]
	v_mfma_f32_16x16x32_bf16 v[46:49], v[152:155], v[230:233], v[46:49]
	v_mfma_f32_16x16x32_bf16 v[42:45], v[160:163], v[230:233], v[42:45]
	v_mfma_f32_16x16x32_bf16 v[30:33], v[152:155], v[238:241], v[30:33]
	v_mfma_f32_16x16x32_bf16 v[26:29], v[160:163], v[238:241], v[26:29]
	v_mfma_f32_16x16x32_bf16 v[14:17], v[152:155], v[246:249], v[14:17]
	v_mfma_f32_16x16x32_bf16 v[10:13], v[160:163], v[246:249], v[10:13]
	v_mfma_f32_16x16x32_bf16 v[54:57], v[186:189], v[202:205], v[54:57]
	v_mfma_f32_16x16x32_bf16 v[50:53], v[194:197], v[202:205], v[50:53]
	v_mfma_f32_16x16x32_bf16 v[38:41], v[186:189], v[226:229], v[38:41]
	v_mfma_f32_16x16x32_bf16 v[34:37], v[194:197], v[226:229], v[34:37]
	v_mfma_f32_16x16x32_bf16 v[22:25], v[186:189], v[234:237], v[22:25]
	v_mfma_f32_16x16x32_bf16 v[18:21], v[194:197], v[234:237], v[18:21]
	v_mfma_f32_16x16x32_bf16 v[6:9], v[186:189], v[242:245], v[6:9]
	v_mfma_f32_16x16x32_bf16 v[2:5], v[194:197], v[242:245], v[2:5]
	v_mfma_f32_16x16x32_bf16 v[54:57], v[190:193], v[206:209], v[54:57]
	v_mfma_f32_16x16x32_bf16 v[50:53], v[198:201], v[206:209], v[50:53]
	v_mfma_f32_16x16x32_bf16 v[38:41], v[190:193], v[230:233], v[38:41]
	v_mfma_f32_16x16x32_bf16 v[34:37], v[198:201], v[230:233], v[34:37]
	v_mfma_f32_16x16x32_bf16 v[22:25], v[190:193], v[238:241], v[22:25]
	v_mfma_f32_16x16x32_bf16 v[18:21], v[198:201], v[238:241], v[18:21]
	v_mfma_f32_16x16x32_bf16 v[6:9], v[190:193], v[246:249], v[6:9]
	v_mfma_f32_16x16x32_bf16 v[2:5], v[198:201], v[246:249], v[2:5]
	s_setprio 0
	s_barrier
	s_add_i32 s85, s85, 2
	s_add_u32 s56, s56, 0x100
	s_addc_u32 s57, s57, 0
	s_cmp_gt_u32 s85, 29
	s_cbranch_scc0 .LBB0_277
	s_and_b64 vcc, exec, s[36:37]
	s_cbranch_vccz .LBB0_280
	s_barrier

; #define PG8_STAGE(bufoff, gbase, voff) do { _Pragma("unroll") for (int _i = 0; _i < 2; ++_i) \
;         __builtin_amdgcn_global_load_lds((const unsigned*)((const char*)(gbase) + (voff)[_i]), (LAS unsigned*)(lds + (bufoff) + ldsw + _i * 8192), 16, 0, 0); } while (0)
; #define PG8_LDA(dst, b, h) do { _Pragma("unroll") for (int m = 0; m < 4; ++m) _Pragma("unroll") for (int k = 0; k < 2; ++k) dst[m][k] = *(const LAS bf16x8*)(lds + PG8_SA(b, h) + aoff + m * 2048 + k * 1024); } while (0)
; #define PG8_LDB(dst, b, h) do { _Pragma("unroll") for (int n = 0; n < 2; ++n) _Pragma("unroll") for (int k = 0; k < 2; ++k) dst[n][k] = *(const LAS bf16x8*)(lds + PG8_SB(b, h) + boff + n * 2048 + k * 1024); } while (0)
; #define PG8_MMA(ai, bj, At, Bt) do { __builtin_amdgcn_s_setprio(1); _Pragma("unroll") for (int m = 0; m < 4; ++m) _Pragma("unroll") for (int n = 0; n < 2; ++n) _Pragma("unroll") for (int k = 0; k < 2; ++k) \
;         acc[ai][bj][m][n] = __builtin_amdgcn_mfma_f32_16x16x32_bf16(Bt[n][k], At[m][k], acc[ai][bj][m][n], 0, 0, 0); __builtin_amdgcn_s_setprio(0); } while (0)
; #define PG8_WAIT_V(n) asm volatile("s_waitcnt vmcnt(" #n ")" ::: "memory")
; #define PG8_WAIT_L(n) asm volatile("s_waitcnt lgkmcnt(" #n ")" ::: "memory")
; #define PG8_BAR __builtin_amdgcn_s_barrier()
; #define PG8_SCHED __builtin_amdgcn_sched_barrier(0)
; template <class Epi>
; __device__ __forceinline__ void gemm_phase(LAS unsigned char* lds, const Gemm g, const StaticOrder& S, const Epi& E) {
;     ...
;             const char* a1 = PG8_AP(cA, t + 1);
;             const char* a2 = last ? nA : PG8_AP(cA, t + 2); const char* b2 = last ? nB : cB + (size_t)(t + 2) * kstep;
;             const char* a3 = last ? nA + kstep : PG8_AP(cA, t + 3); const char* b3 = b2 + kstep;
;             PG8_LDB(B0, 0, 0); PG8_LDB(B1, 0, 1); PG8_SCHED; PG8_LDA(At, 0, 0); PG8_STAGE(PG8_SA(1, 1), a1 + hstepA, voffA);
;             PG8_WAIT_V(8); PG8_WAIT_L(0); PG8_BAR; PG8_MMA(0, 0, At, B0); PG8_MMA(0, 1, At, B1); PG8_BAR; PG8_SCHED;
;             PG8_LDA(At, 0, 1); PG8_STAGE(PG8_SB(0, 0), b2, voffB); PG8_STAGE(PG8_SB(0, 1), b2 + hstep, voffB); PG8_STAGE(PG8_SA(0, 0), a2, voffA);
.LBB0_494:
	s_add_u32 s12, s42, s40
	s_addc_u32 s13, s43, s41
	s_add_u32 s44, s12, 0x100
	s_addc_u32 s45, s13, 0
	s_add_u32 s86, s92, s40
	s_addc_u32 s87, s93, s41
	s_add_u32 s12, s12, 0x180
	s_addc_u32 s13, s13, 0
	s_add_i32 s90, 0, 0x10000
	s_add_i32 s91, 0, 0x14000
	v_add_u32_e32 v150, s90, v1
	ds_read_b128 v[146:149], v150
	ds_read_b128 v[154:157], v150 offset:1024
	ds_read_b128 v[158:161], v150 offset:2048
	ds_read_b128 v[186:189], v150 offset:3072
	v_add_u32_e32 v150, s91, v1
	ds_read_b128 v[190:193], v150
	ds_read_b128 v[194:197], v150 offset:1024
	ds_read_b128 v[198:201], v150 offset:2048
	ds_read_b128 v[202:205], v150 offset:3072
	s_cmpk_eq_i32 s40, 0x200
	s_cselect_b32 s97, s85, s13
	s_cselect_b32 s96, s81, s12
	s_cselect_b32 vcc_hi, s57, s87
	s_cselect_b32 vcc_lo, s56, s86
	s_cselect_b32 s87, s55, s45
	s_cselect_b32 s86, s54, s44
	v_lshl_add_u64 v[150:151], v[142:143], 0, s[40:41]
	s_add_i32 m0, s25, 0xc000
	ds_read_b128 v[206:209], v152
	ds_read_b128 v[226:229], v152 offset:1024
	ds_read_b128 v[230:233], v152 offset:2048
	ds_read_b128 v[234:237], v152 offset:3072
	ds_read_b128 v[238:241], v152 offset:4096
	ds_read_b128 v[242:245], v152 offset:5120
	ds_read_b128 v[246:249], v152 offset:6144
	ds_read_b128 v[222:225], v152 offset:7168
	global_load_lds_dwordx4 v[150:151], off
	v_lshl_add_u64 v[150:151], v[144:145], 0, s[40:41]
	s_add_i32 m0, s25, 0xe000
	s_nop 0
	global_load_lds_dwordx4 v[150:151], off
	s_waitcnt vmcnt(8)
	s_waitcnt lgkmcnt(0)
	s_barrier
	s_setprio 1
	v_mfma_f32_16x16x32_bf16 v[126:129], v[146:149], v[206:209], v[126:129]
	v_mfma_f32_16x16x32_bf16 v[122:125], v[158:161], v[206:209], v[122:125]
	v_mfma_f32_16x16x32_bf16 v[110:113], v[146:149], v[230:233], v[110:113]
	v_mfma_f32_16x16x32_bf16 v[106:109], v[158:161], v[230:233], v[106:109]
	v_mfma_f32_16x16x32_bf16 v[94:97], v[146:149], v[238:241], v[94:97]
	v_mfma_f32_16x16x32_bf16 v[90:93], v[158:161], v[238:241], v[90:93]
	v_mfma_f32_16x16x32_bf16 v[78:81], v[146:149], v[246:249], v[78:81]
	v_mfma_f32_16x16x32_bf16 v[74:77], v[158:161], v[246:249], v[74:77]
	v_mfma_f32_16x16x32_bf16 v[126:129], v[154:157], v[226:229], v[126:129]
	v_mfma_f32_16x16x32_bf16 v[122:125], v[186:189], v[226:229], v[122:125]
	v_mfma_f32_16x16x32_bf16 v[110:113], v[154:157], v[234:237], v[110:113]
	v_mfma_f32_16x16x32_bf16 v[106:109], v[186:189], v[234:237], v[106:109]
	v_mfma_f32_16x16x32_bf16 v[94:97], v[154:157], v[242:245], v[94:97]
	v_mfma_f32_16x16x32_bf16 v[90:93], v[186:189], v[242:245], v[90:93]
	v_mfma_f32_16x16x32_bf16 v[78:81], v[154:157], v[222:225], v[78:81]
	v_mfma_f32_16x16x32_bf16 v[74:77], v[186:189], v[222:225], v[74:77]
	v_mfma_f32_16x16x32_bf16 v[118:121], v[190:193], v[206:209], v[118:121]
	v_mfma_f32_16x16x32_bf16 v[114:117], v[198:201], v[206:209], v[114:117]
	v_mfma_f32_16x16x32_bf16 v[102:105], v[190:193], v[230:233], v[102:105]
	v_mfma_f32_16x16x32_bf16 v[98:101], v[198:201], v[230:233], v[98:101]
	v_mfma_f32_16x16x32_bf16 v[86:89], v[190:193], v[238:241], v[86:89]
	v_mfma_f32_16x16x32_bf16 v[82:85], v[198:201], v[238:241], v[82:85]
	v_mfma_f32_16x16x32_bf16 v[70:73], v[190:193], v[246:249], v[70:73]
	v_mfma_f32_16x16x32_bf16 v[66:69], v[198:201], v[246:249], v[66:69]
	v_mfma_f32_16x16x32_bf16 v[118:121], v[194:197], v[226:229], v[118:121]
	v_mfma_f32_16x16x32_bf16 v[114:117], v[202:205], v[226:229], v[114:117]
	v_mfma_f32_16x16x32_bf16 v[102:105], v[194:197], v[234:237], v[102:105]
	v_mfma_f32_16x16x32_bf16 v[98:101], v[202:205], v[234:237], v[98:101]
	v_mfma_f32_16x16x32_bf16 v[86:89], v[194:197], v[242:245], v[86:89]
	v_mfma_f32_16x16x32_bf16 v[82:85], v[202:205], v[242:245], v[82:85]
	v_mfma_f32_16x16x32_bf16 v[70:73], v[194:197], v[222:225], v[70:73]
	v_mfma_f32_16x16x32_bf16 v[66:69], v[202:205], v[222:225], v[66:69]
	s_setprio 0
	s_barrier
	s_add_i32 s12, s90, s24
	v_lshl_add_u64 v[150:151], vcc, 0, v[134:135]
	s_mov_b32 m0, s12
	ds_read_b128 v[206:209], v152 offset:16384
	ds_read_b128 v[222:225], v152 offset:17408
	ds_read_b128 v[226:229], v152 offset:18432
	ds_read_b128 v[230:233], v152 offset:19456
	ds_read_b128 v[234:237], v152 offset:20480
	ds_read_b128 v[238:241], v152 offset:21504
	ds_read_b128 v[242:245], v152 offset:22528
	ds_read_b128 v[246:249], v152 offset:23552
	global_load_lds_dwordx4 v[150:151], off
	s_add_i32 m0, s12, 0x2000
	s_add_u32 s44, vcc_lo, 0x18000
	v_lshl_add_u64 v[162:163], vcc, 0, v[130:131]
	s_addc_u32 s45, vcc_hi, 0
	s_add_i32 s12, s91, s24
	global_load_lds_dwordx4 v[162:163], off
	v_lshl_add_u64 v[212:213], s[44:45], 0, v[134:135]
	s_mov_b32 m0, s12
	s_nop 0
	global_load_lds_dwordx4 v[212:213], off
	v_lshl_add_u64 v[212:213], s[44:45], 0, v[130:131]
	s_add_i32 m0, s12, 0x2000
	s_nop 0
	global_load_lds_dwordx4 v[212:213], off
	v_lshl_add_u64 v[212:213], s[86:87], 0, v[136:137]
	s_mov_b32 m0, s25
	s_nop 0
	global_load_lds_dwordx4 v[212:213], off
	v_lshl_add_u64 v[212:213], s[86:87], 0, v[132:133]
	s_mov_b32 m0, s26
	s_nop 0
	global_load_lds_dwordx4 v[212:213], off
	s_waitcnt vmcnt(8)
	s_waitcnt lgkmcnt(0)
	s_barrier
; #define PG8_STAGE(bufoff, gbase, voff) do { _Pragma("unroll") for (int _i = 0; _i < 2; ++_i) \
;         __builtin_amdgcn_global_load_lds((const unsigned*)((const char*)(gbase) + (voff)[_i]), (LAS unsigned*)(lds + (bufoff) + ldsw + _i * 8192), 16, 0, 0); } while (0)
; #define PG8_LDA(dst, b, h) do { _Pragma("unroll") for (int m = 0; m < 4; ++m) _Pragma("unroll") for (int k = 0; k < 2; ++k) dst[m][k] = *(const LAS bf16x8*)(lds + PG8_SA(b, h) + aoff + m * 2048 + k * 1024); } while (0)
; #define PG8_LDB(dst, b, h) do { _Pragma("unroll") for (int n = 0; n < 2; ++n) _Pragma("unroll") for (int k = 0; k < 2; ++k) dst[n][k] = *(const LAS bf16x8*)(lds + PG8_SB(b, h) + boff + n * 2048 + k * 1024); } while (0)
; #define PG8_MMA(ai, bj, At, Bt) do { __builtin_amdgcn_s_setprio(1); _Pragma("unroll") for (int m = 0; m < 4; ++m) _Pragma("unroll") for (int n = 0; n < 2; ++n) _Pragma("unroll") for (int k = 0; k < 2; ++k) \
;         acc[ai][bj][m][n] = __builtin_amdgcn_mfma_f32_16x16x32_bf16(Bt[n][k], At[m][k], acc[ai][bj][m][n], 0, 0, 0); __builtin_amdgcn_s_setprio(0); } while (0)
; #define PG8_WAIT_V(n) asm volatile("s_waitcnt vmcnt(" #n ")" ::: "memory")
; #define PG8_WAIT_L(n) asm volatile("s_waitcnt lgkmcnt(" #n ")" ::: "memory")
; #define PG8_BAR __builtin_amdgcn_s_barrier()
; #define PG8_SCHED __builtin_amdgcn_sched_barrier(0)
; template <class Epi>
; __device__ __forceinline__ void gemm_phase(LAS unsigned char* lds, const Gemm g, const StaticOrder& S, const Epi& E) {
;     ...
;             PG8_WAIT_V(8); PG8_WAIT_L(0); PG8_BAR; PG8_MMA(1, 0, At, B0); PG8_MMA(1, 1, At, B1); PG8_BAR; PG8_SCHED;
;             PG8_LDB(B0, 1, 0); PG8_LDB(B1, 1, 1); PG8_SCHED; PG8_LDA(At, 1, 0); PG8_STAGE(PG8_SA(0, 1), a2 + hstepA, voffA);
;             PG8_WAIT_V(8); PG8_WAIT_L(0); PG8_BAR; PG8_MMA(0, 0, At, B0); PG8_MMA(0, 1, At, B1); PG8_BAR; PG8_SCHED;
	s_setprio 1
	v_mfma_f32_16x16x32_bf16 v[62:65], v[146:149], v[206:209], v[62:65]
	v_mfma_f32_16x16x32_bf16 v[58:61], v[158:161], v[206:209], v[58:61]
	v_mfma_f32_16x16x32_bf16 v[46:49], v[146:149], v[226:229], v[46:49]
	v_mfma_f32_16x16x32_bf16 v[42:45], v[158:161], v[226:229], v[42:45]
	v_mfma_f32_16x16x32_bf16 v[30:33], v[146:149], v[234:237], v[30:33]
	v_mfma_f32_16x16x32_bf16 v[26:29], v[158:161], v[234:237], v[26:29]
	v_mfma_f32_16x16x32_bf16 v[14:17], v[146:149], v[242:245], v[14:17]
	v_mfma_f32_16x16x32_bf16 v[10:13], v[158:161], v[242:245], v[10:13]
	v_mfma_f32_16x16x32_bf16 v[62:65], v[154:157], v[222:225], v[62:65]
	v_mfma_f32_16x16x32_bf16 v[58:61], v[186:189], v[222:225], v[58:61]
	v_mfma_f32_16x16x32_bf16 v[46:49], v[154:157], v[230:233], v[46:49]
	v_mfma_f32_16x16x32_bf16 v[42:45], v[186:189], v[230:233], v[42:45]
	v_mfma_f32_16x16x32_bf16 v[30:33], v[154:157], v[238:241], v[30:33]
	v_mfma_f32_16x16x32_bf16 v[26:29], v[186:189], v[238:241], v[26:29]
	v_mfma_f32_16x16x32_bf16 v[14:17], v[154:157], v[246:249], v[14:17]
	v_mfma_f32_16x16x32_bf16 v[10:13], v[186:189], v[246:249], v[10:13]
	v_mfma_f32_16x16x32_bf16 v[54:57], v[190:193], v[206:209], v[54:57]
	v_mfma_f32_16x16x32_bf16 v[50:53], v[198:201], v[206:209], v[50:53]
	v_mfma_f32_16x16x32_bf16 v[38:41], v[190:193], v[226:229], v[38:41]
	v_mfma_f32_16x16x32_bf16 v[34:37], v[198:201], v[226:229], v[34:37]
	v_mfma_f32_16x16x32_bf16 v[22:25], v[190:193], v[234:237], v[22:25]
	v_mfma_f32_16x16x32_bf16 v[18:21], v[198:201], v[234:237], v[18:21]
	v_mfma_f32_16x16x32_bf16 v[6:9], v[190:193], v[242:245], v[6:9]
	v_mfma_f32_16x16x32_bf16 v[2:5], v[198:201], v[242:245], v[2:5]
	v_mfma_f32_16x16x32_bf16 v[54:57], v[194:197], v[222:225], v[54:57]
	v_mfma_f32_16x16x32_bf16 v[50:53], v[202:205], v[222:225], v[50:53]
	v_mfma_f32_16x16x32_bf16 v[38:41], v[194:197], v[230:233], v[38:41]
	v_mfma_f32_16x16x32_bf16 v[34:37], v[202:205], v[230:233], v[34:37]
	v_mfma_f32_16x16x32_bf16 v[22:25], v[194:197], v[238:241], v[22:25]
	v_mfma_f32_16x16x32_bf16 v[18:21], v[202:205], v[238:241], v[18:21]
	v_mfma_f32_16x16x32_bf16 v[6:9], v[194:197], v[246:249], v[6:9]
	v_mfma_f32_16x16x32_bf16 v[2:5], v[202:205], v[246:249], v[2:5]
	s_setprio 0
	s_barrier
	s_add_i32 s12, 0, 0x18000
	v_add_u32_e32 v153, s12, v1
	s_add_i32 s13, 0, 0x1c000
	ds_read_b128 v[146:149], v153
	ds_read_b128 v[154:157], v153 offset:1024
	ds_read_b128 v[158:161], v153 offset:2048
	ds_read_b128 v[186:189], v153 offset:3072
	v_add_u32_e32 v153, s13, v1
	ds_read_b128 v[190:193], v153
	ds_read_b128 v[194:197], v153 offset:1024
	ds_read_b128 v[198:201], v153 offset:2048
	ds_read_b128 v[202:205], v153 offset:3072
	s_add_u32 s44, s86, 0x18000
	s_addc_u32 s45, s87, 0
	s_mov_b32 m0, s27
	v_lshl_add_u64 v[212:213], s[44:45], 0, v[136:137]
	ds_read_b128 v[206:209], v152 offset:32768
	ds_read_b128 v[222:225], v152 offset:33792
	ds_read_b128 v[226:229], v152 offset:34816
	ds_read_b128 v[230:233], v152 offset:35840
	ds_read_b128 v[234:237], v152 offset:36864
	ds_read_b128 v[238:241], v152 offset:37888
	ds_read_b128 v[242:245], v152 offset:38912
	ds_read_b128 v[246:249], v152 offset:39936
	global_load_lds_dwordx4 v[212:213], off
	v_lshl_add_u64 v[212:213], s[44:45], 0, v[132:133]
	s_mov_b32 m0, s28
	s_nop 0
	global_load_lds_dwordx4 v[212:213], off
	s_waitcnt vmcnt(8)
	s_waitcnt lgkmcnt(0)
	s_barrier
	s_setprio 1
	v_mfma_f32_16x16x32_bf16 v[126:129], v[146:149], v[206:209], v[126:129]
	v_mfma_f32_16x16x32_bf16 v[122:125], v[158:161], v[206:209], v[122:125]
	v_mfma_f32_16x16x32_bf16 v[110:113], v[146:149], v[226:229], v[110:113]
	v_mfma_f32_16x16x32_bf16 v[106:109], v[158:161], v[226:229], v[106:109]
	v_mfma_f32_16x16x32_bf16 v[94:97], v[146:149], v[234:237], v[94:97]
	v_mfma_f32_16x16x32_bf16 v[90:93], v[158:161], v[234:237], v[90:93]
	v_mfma_f32_16x16x32_bf16 v[78:81], v[146:149], v[242:245], v[78:81]
	v_mfma_f32_16x16x32_bf16 v[74:77], v[158:161], v[242:245], v[74:77]
	v_mfma_f32_16x16x32_bf16 v[126:129], v[154:157], v[222:225], v[126:129]
	v_mfma_f32_16x16x32_bf16 v[122:125], v[186:189], v[222:225], v[122:125]
	v_mfma_f32_16x16x32_bf16 v[110:113], v[154:157], v[230:233], v[110:113]
	v_mfma_f32_16x16x32_bf16 v[106:109], v[186:189], v[230:233], v[106:109]
	v_mfma_f32_16x16x32_bf16 v[94:97], v[154:157], v[238:241], v[94:97]
	v_mfma_f32_16x16x32_bf16 v[90:93], v[186:189], v[238:241], v[90:93]
	v_mfma_f32_16x16x32_bf16 v[78:81], v[154:157], v[246:249], v[78:81]
	v_mfma_f32_16x16x32_bf16 v[74:77], v[186:189], v[246:249], v[74:77]
	v_mfma_f32_16x16x32_bf16 v[118:121], v[190:193], v[206:209], v[118:121]
	v_mfma_f32_16x16x32_bf16 v[114:117], v[198:201], v[206:209], v[114:117]
	v_mfma_f32_16x16x32_bf16 v[102:105], v[190:193], v[226:229], v[102:105]
	v_mfma_f32_16x16x32_bf16 v[98:101], v[198:201], v[226:229], v[98:101]
	v_mfma_f32_16x16x32_bf16 v[86:89], v[190:193], v[234:237], v[86:89]
	v_mfma_f32_16x16x32_bf16 v[82:85], v[198:201], v[234:237], v[82:85]
	v_mfma_f32_16x16x32_bf16 v[70:73], v[190:193], v[242:245], v[70:73]
	v_mfma_f32_16x16x32_bf16 v[66:69], v[198:201], v[242:245], v[66:69]
	v_mfma_f32_16x16x32_bf16 v[118:121], v[194:197], v[222:225], v[118:121]
	v_mfma_f32_16x16x32_bf16 v[114:117], v[202:205], v[222:225], v[114:117]
	v_mfma_f32_16x16x32_bf16 v[102:105], v[194:197], v[230:233], v[102:105]
	v_mfma_f32_16x16x32_bf16 v[98:101], v[202:205], v[230:233], v[98:101]
	v_mfma_f32_16x16x32_bf16 v[86:89], v[194:197], v[238:241], v[86:89]
	v_mfma_f32_16x16x32_bf16 v[82:85], v[202:205], v[238:241], v[82:85]
	v_mfma_f32_16x16x32_bf16 v[70:73], v[194:197], v[246:249], v[70:73]
	v_mfma_f32_16x16x32_bf16 v[66:69], v[202:205], v[246:249], v[66:69]
	s_setprio 0
	s_barrier
; #define PG8_STAGE(bufoff, gbase, voff) do { _Pragma("unroll") for (int _i = 0; _i < 2; ++_i) \
;         __builtin_amdgcn_global_load_lds((const unsigned*)((const char*)(gbase) + (voff)[_i]), (LAS unsigned*)(lds + (bufoff) + ldsw + _i * 8192), 16, 0, 0); } while (0)
; #define PG8_LDA(dst, b, h) do { _Pragma("unroll") for (int m = 0; m < 4; ++m) _Pragma("unroll") for (int k = 0; k < 2; ++k) dst[m][k] = *(const LAS bf16x8*)(lds + PG8_SA(b, h) + aoff + m * 2048 + k * 1024); } while (0)
; #define PG8_MMA(ai, bj, At, Bt) do { __builtin_amdgcn_s_setprio(1); _Pragma("unroll") for (int m = 0; m < 4; ++m) _Pragma("unroll") for (int n = 0; n < 2; ++n) _Pragma("unroll") for (int k = 0; k < 2; ++k) \
;         acc[ai][bj][m][n] = __builtin_amdgcn_mfma_f32_16x16x32_bf16(Bt[n][k], At[m][k], acc[ai][bj][m][n], 0, 0, 0); __builtin_amdgcn_s_setprio(0); } while (0)
; #define PG8_WAIT_V(n) asm volatile("s_waitcnt vmcnt(" #n ")" ::: "memory")
; #define PG8_WAIT_L(n) asm volatile("s_waitcnt lgkmcnt(" #n ")" ::: "memory")
; #define PG8_BAR __builtin_amdgcn_s_barrier()
; #define PG8_SCHED __builtin_amdgcn_sched_barrier(0)
; template <class Epi>
; __device__ __forceinline__ void gemm_phase(LAS unsigned char* lds, const Gemm g, const StaticOrder& S, const Epi& E) {
;     ...
;             PG8_LDA(At, 1, 1); PG8_STAGE(PG8_SB(1, 0), b3, voffB); PG8_STAGE(PG8_SB(1, 1), b3 + hstep, voffB); PG8_STAGE(PG8_SA(1, 0), a3, voffA);
;             PG8_WAIT_V(8); PG8_WAIT_L(0); PG8_BAR; PG8_MMA(1, 0, At, B0); PG8_MMA(1, 1, At, B1); PG8_BAR; PG8_SCHED;
;         }
;         if (wr == 0) PG8_BAR;
	s_add_i32 s12, s12, s24
	v_lshl_add_u64 v[150:151], v[150:151], 0, s[6:7]
	s_mov_b32 m0, s12
	ds_read_b128 v[206:209], v152 offset:49152
	ds_read_b128 v[222:225], v152 offset:50176
	ds_read_b128 v[226:229], v152 offset:51200
	ds_read_b128 v[230:233], v152 offset:52224
	ds_read_b128 v[234:237], v152 offset:53248
	ds_read_b128 v[238:241], v152 offset:54272
	ds_read_b128 v[242:245], v152 offset:55296
	ds_read_b128 v[246:249], v152 offset:56320
	global_load_lds_dwordx4 v[150:151], off
	s_add_i32 m0, s12, 0x2000
	s_add_u32 s44, vcc_lo, 0x18080
	v_lshl_add_u64 v[150:151], v[162:163], 0, s[6:7]
	s_addc_u32 s45, vcc_hi, 0
	s_add_i32 s12, s13, s24
	global_load_lds_dwordx4 v[150:151], off
	v_lshl_add_u64 v[150:151], s[44:45], 0, v[134:135]
	s_mov_b32 m0, s12
	s_nop 0
	global_load_lds_dwordx4 v[150:151], off
	v_lshl_add_u64 v[150:151], s[44:45], 0, v[130:131]
	s_add_i32 m0, s12, 0x2000
	s_nop 0
	global_load_lds_dwordx4 v[150:151], off
	v_lshl_add_u64 v[150:151], s[96:97], 0, v[136:137]
	s_mov_b32 m0, s29
	s_nop 0
	global_load_lds_dwordx4 v[150:151], off
	v_lshl_add_u64 v[150:151], s[96:97], 0, v[132:133]
	s_mov_b32 m0, s33
	s_nop 0
	global_load_lds_dwordx4 v[150:151], off
	s_waitcnt vmcnt(8)
	s_waitcnt lgkmcnt(0)
	s_barrier
	s_setprio 1
	v_mfma_f32_16x16x32_bf16 v[62:65], v[146:149], v[206:209], v[62:65]
	v_mfma_f32_16x16x32_bf16 v[58:61], v[158:161], v[206:209], v[58:61]
	v_mfma_f32_16x16x32_bf16 v[46:49], v[146:149], v[226:229], v[46:49]
	v_mfma_f32_16x16x32_bf16 v[42:45], v[158:161], v[226:229], v[42:45]
	v_mfma_f32_16x16x32_bf16 v[30:33], v[146:149], v[234:237], v[30:33]
	v_mfma_f32_16x16x32_bf16 v[26:29], v[158:161], v[234:237], v[26:29]
	v_mfma_f32_16x16x32_bf16 v[14:17], v[146:149], v[242:245], v[14:17]
	v_mfma_f32_16x16x32_bf16 v[10:13], v[158:161], v[242:245], v[10:13]
	v_mfma_f32_16x16x32_bf16 v[62:65], v[154:157], v[222:225], v[62:65]
	v_mfma_f32_16x16x32_bf16 v[58:61], v[186:189], v[222:225], v[58:61]
	v_mfma_f32_16x16x32_bf16 v[46:49], v[154:157], v[230:233], v[46:49]
	v_mfma_f32_16x16x32_bf16 v[42:45], v[186:189], v[230:233], v[42:45]
	v_mfma_f32_16x16x32_bf16 v[30:33], v[154:157], v[238:241], v[30:33]
	v_mfma_f32_16x16x32_bf16 v[26:29], v[186:189], v[238:241], v[26:29]
	v_mfma_f32_16x16x32_bf16 v[14:17], v[154:157], v[246:249], v[14:17]
	v_mfma_f32_16x16x32_bf16 v[10:13], v[186:189], v[246:249], v[10:13]
	v_mfma_f32_16x16x32_bf16 v[54:57], v[190:193], v[206:209], v[54:57]
	v_mfma_f32_16x16x32_bf16 v[50:53], v[198:201], v[206:209], v[50:53]
	v_mfma_f32_16x16x32_bf16 v[38:41], v[190:193], v[226:229], v[38:41]
	v_mfma_f32_16x16x32_bf16 v[34:37], v[198:201], v[226:229], v[34:37]
	v_mfma_f32_16x16x32_bf16 v[22:25], v[190:193], v[234:237], v[22:25]
	v_mfma_f32_16x16x32_bf16 v[18:21], v[198:201], v[234:237], v[18:21]
	v_mfma_f32_16x16x32_bf16 v[6:9], v[190:193], v[242:245], v[6:9]
	v_mfma_f32_16x16x32_bf16 v[2:5], v[198:201], v[242:245], v[2:5]
	v_mfma_f32_16x16x32_bf16 v[54:57], v[194:197], v[222:225], v[54:57]
	v_mfma_f32_16x16x32_bf16 v[50:53], v[202:205], v[222:225], v[50:53]
	v_mfma_f32_16x16x32_bf16 v[38:41], v[194:197], v[230:233], v[38:41]
	v_mfma_f32_16x16x32_bf16 v[34:37], v[202:205], v[230:233], v[34:37]
	v_mfma_f32_16x16x32_bf16 v[22:25], v[194:197], v[238:241], v[22:25]
	v_mfma_f32_16x16x32_bf16 v[18:21], v[202:205], v[238:241], v[18:21]
	v_mfma_f32_16x16x32_bf16 v[6:9], v[194:197], v[246:249], v[6:9]
	v_mfma_f32_16x16x32_bf16 v[2:5], v[202:205], v[246:249], v[2:5]
	s_setprio 0
	s_barrier
	s_add_i32 s94, s94, 2
	s_add_u32 s40, s40, 0x100
	s_addc_u32 s41, s41, 0
	s_cmp_gt_u32 s94, 3
	s_cbranch_scc0 .LBB0_494
	s_and_b64 vcc, exec, s[50:51]
	s_cbranch_vccz .LBB0_497
	s_barrier

; #define PG8_STAGE(bufoff, gbase, voff) do { _Pragma("unroll") for (int _i = 0; _i < 2; ++_i) \
;         __builtin_amdgcn_global_load_lds((const unsigned*)((const char*)(gbase) + (voff)[_i]), (LAS unsigned*)(lds + (bufoff) + ldsw + _i * 8192), 16, 0, 0); } while (0)
; #define PG8_LDA(dst, b, h) do { _Pragma("unroll") for (int m = 0; m < 4; ++m) _Pragma("unroll") for (int k = 0; k < 2; ++k) dst[m][k] = *(const LAS bf16x8*)(lds + PG8_SA(b, h) + aoff + m * 2048 + k * 1024); } while (0)
; #define PG8_LDB(dst, b, h) do { _Pragma("unroll") for (int n = 0; n < 2; ++n) _Pragma("unroll") for (int k = 0; k < 2; ++k) dst[n][k] = *(const LAS bf16x8*)(lds + PG8_SB(b, h) + boff + n * 2048 + k * 1024); } while (0)
; #define PG8_MMA(ai, bj, At, Bt) do { __builtin_amdgcn_s_setprio(1); _Pragma("unroll") for (int m = 0; m < 4; ++m) _Pragma("unroll") for (int n = 0; n < 2; ++n) _Pragma("unroll") for (int k = 0; k < 2; ++k) \
;         acc[ai][bj][m][n] = __builtin_amdgcn_mfma_f32_16x16x32_bf16(Bt[n][k], At[m][k], acc[ai][bj][m][n], 0, 0, 0); __builtin_amdgcn_s_setprio(0); } while (0)
; #define PG8_WAIT_V(n) asm volatile("s_waitcnt vmcnt(" #n ")" ::: "memory")
; #define PG8_WAIT_L(n) asm volatile("s_waitcnt lgkmcnt(" #n ")" ::: "memory")
; template <class Epi>
; __device__ __forceinline__ void gemm_phase(LAS unsigned char* lds, const Gemm g, const StaticOrder& S, const Epi& E) {
;     ...
;         for (int t = 0; t < nt; t += 2) {
;             if constexpr (Epi::GATED) { if (t == 8 || t == 16) E.rescale(acc, cur, t == 8 ? 0 : 1, wr, wc, fr, fq); }
;             const bool last = (t == nt - 2);
;             const char* a1 = PG8_AP(cA, t + 1);
;             const char* a2 = last ? nA : PG8_AP(cA, t + 2); const char* b2 = last ? nB : cB + (size_t)(t + 2) * kstep;
;             const char* a3 = last ? nA + kstep : PG8_AP(cA, t + 3); const char* b3 = b2 + kstep;
;             PG8_LDB(B0, 0, 0); PG8_LDB(B1, 0, 1); PG8_SCHED; PG8_LDA(At, 0, 0); PG8_STAGE(PG8_SA(1, 1), a1 + hstepA, voffA);
;             PG8_WAIT_V(8); PG8_WAIT_L(0); PG8_BAR; PG8_MMA(0, 0, At, B0); PG8_MMA(0, 1, At, B1); PG8_BAR; PG8_SCHED;
;             PG8_LDA(At, 0, 1); PG8_STAGE(PG8_SB(0, 0), b2, voffB); PG8_STAGE(PG8_SB(0, 1), b2 + hstep, voffB); PG8_STAGE(PG8_SA(0, 0), a2, voffA);
;             PG8_WAIT_V(8); PG8_WAIT_L(0); PG8_BAR; PG8_MMA(1, 0, At, B0); PG8_MMA(1, 1, At, B1); PG8_BAR; PG8_SCHED;
.LBB0_644:
	s_add_u32 s12, s40, s54
	s_addc_u32 s13, s41, s55
	s_add_u32 s44, s12, 0x100
	s_addc_u32 s45, s13, 0
	s_add_u32 s86, s93, s54
	s_addc_u32 s87, s94, s55
	s_add_u32 s12, s12, 0x180
	s_addc_u32 s13, s13, 0
	s_add_i32 s90, 0, 0x10000
	s_add_i32 s91, 0, 0x14000
	v_add_u32_e32 v147, s90, v1
	ds_read_b128 v[148:151], v147
	ds_read_b128 v[152:155], v147 offset:1024
	ds_read_b128 v[156:159], v147 offset:2048
	ds_read_b128 v[160:163], v147 offset:3072
	v_add_u32_e32 v147, s91, v1
	ds_read_b128 v[186:189], v147
	ds_read_b128 v[190:193], v147 offset:1024
	ds_read_b128 v[194:197], v147 offset:2048
	ds_read_b128 v[198:201], v147 offset:3072
	s_cmpk_eq_i32 s54, 0xf00
	s_cselect_b32 s57, s92, s13
	s_cselect_b32 s56, s85, s12
	s_cselect_b32 s97, s43, s87
	s_cselect_b32 s96, s81, s86
	s_cselect_b32 s87, s47, s45
	s_cselect_b32 s86, s80, s44
	v_lshl_add_u64 v[212:213], v[142:143], 0, s[54:55]
	s_add_i32 m0, s25, 0xc000
	ds_read_b128 v[202:205], v146
	ds_read_b128 v[206:209], v146 offset:1024
	ds_read_b128 v[222:225], v146 offset:2048
	ds_read_b128 v[226:229], v146 offset:3072
	ds_read_b128 v[230:233], v146 offset:4096
	ds_read_b128 v[234:237], v146 offset:5120
	ds_read_b128 v[238:241], v146 offset:6144
	ds_read_b128 v[242:245], v146 offset:7168
	global_load_lds_dwordx4 v[212:213], off
	v_lshl_add_u64 v[212:213], v[144:145], 0, s[54:55]
	s_add_i32 m0, s25, 0xe000
	s_nop 0
	global_load_lds_dwordx4 v[212:213], off
	s_waitcnt vmcnt(8)
	s_waitcnt lgkmcnt(0)
	s_barrier
	s_setprio 1
	v_mfma_f32_16x16x32_bf16 v[126:129], v[148:151], v[202:205], v[126:129]
	v_mfma_f32_16x16x32_bf16 v[122:125], v[156:159], v[202:205], v[122:125]
	v_mfma_f32_16x16x32_bf16 v[110:113], v[148:151], v[222:225], v[110:113]
	v_mfma_f32_16x16x32_bf16 v[106:109], v[156:159], v[222:225], v[106:109]
	v_mfma_f32_16x16x32_bf16 v[94:97], v[148:151], v[230:233], v[94:97]
	v_mfma_f32_16x16x32_bf16 v[90:93], v[156:159], v[230:233], v[90:93]
	v_mfma_f32_16x16x32_bf16 v[78:81], v[148:151], v[238:241], v[78:81]
	v_mfma_f32_16x16x32_bf16 v[74:77], v[156:159], v[238:241], v[74:77]
	v_mfma_f32_16x16x32_bf16 v[126:129], v[152:155], v[206:209], v[126:129]
	v_mfma_f32_16x16x32_bf16 v[122:125], v[160:163], v[206:209], v[122:125]
	v_mfma_f32_16x16x32_bf16 v[110:113], v[152:155], v[226:229], v[110:113]
	v_mfma_f32_16x16x32_bf16 v[106:109], v[160:163], v[226:229], v[106:109]
	v_mfma_f32_16x16x32_bf16 v[94:97], v[152:155], v[234:237], v[94:97]
	v_mfma_f32_16x16x32_bf16 v[90:93], v[160:163], v[234:237], v[90:93]
	v_mfma_f32_16x16x32_bf16 v[78:81], v[152:155], v[242:245], v[78:81]
	v_mfma_f32_16x16x32_bf16 v[74:77], v[160:163], v[242:245], v[74:77]
	v_mfma_f32_16x16x32_bf16 v[118:121], v[186:189], v[202:205], v[118:121]
	v_mfma_f32_16x16x32_bf16 v[114:117], v[194:197], v[202:205], v[114:117]
	v_mfma_f32_16x16x32_bf16 v[102:105], v[186:189], v[222:225], v[102:105]
	v_mfma_f32_16x16x32_bf16 v[98:101], v[194:197], v[222:225], v[98:101]
	v_mfma_f32_16x16x32_bf16 v[86:89], v[186:189], v[230:233], v[86:89]
	v_mfma_f32_16x16x32_bf16 v[82:85], v[194:197], v[230:233], v[82:85]
	v_mfma_f32_16x16x32_bf16 v[70:73], v[186:189], v[238:241], v[70:73]
	v_mfma_f32_16x16x32_bf16 v[66:69], v[194:197], v[238:241], v[66:69]
	v_mfma_f32_16x16x32_bf16 v[118:121], v[190:193], v[206:209], v[118:121]
	v_mfma_f32_16x16x32_bf16 v[114:117], v[198:201], v[206:209], v[114:117]
	v_mfma_f32_16x16x32_bf16 v[102:105], v[190:193], v[226:229], v[102:105]
	v_mfma_f32_16x16x32_bf16 v[98:101], v[198:201], v[226:229], v[98:101]
	v_mfma_f32_16x16x32_bf16 v[86:89], v[190:193], v[234:237], v[86:89]
	v_mfma_f32_16x16x32_bf16 v[82:85], v[198:201], v[234:237], v[82:85]
	v_mfma_f32_16x16x32_bf16 v[70:73], v[190:193], v[242:245], v[70:73]
	v_mfma_f32_16x16x32_bf16 v[66:69], v[198:201], v[242:245], v[66:69]
	s_setprio 0
	s_barrier
	s_add_i32 s12, s90, s24
	v_lshl_add_u64 v[212:213], s[96:97], 0, v[134:135]
	s_mov_b32 m0, s12
	ds_read_b128 v[202:205], v146 offset:16384
	ds_read_b128 v[206:209], v146 offset:17408
	ds_read_b128 v[222:225], v146 offset:18432
	ds_read_b128 v[226:229], v146 offset:19456
	ds_read_b128 v[230:233], v146 offset:20480
	ds_read_b128 v[234:237], v146 offset:21504
	ds_read_b128 v[238:241], v146 offset:22528
	ds_read_b128 v[242:245], v146 offset:23552
	global_load_lds_dwordx4 v[212:213], off
	s_add_i32 m0, s12, 0x2000
	s_add_u32 s44, s96, 0x80000
	v_lshl_add_u64 v[246:247], s[96:97], 0, v[130:131]
	s_addc_u32 s45, s97, 0
	s_add_i32 s12, s91, s24
	global_load_lds_dwordx4 v[246:247], off
	v_lshl_add_u64 v[248:249], s[44:45], 0, v[134:135]
	s_mov_b32 m0, s12
	s_nop 0
	global_load_lds_dwordx4 v[248:249], off
	v_lshl_add_u64 v[248:249], s[44:45], 0, v[130:131]
	s_add_i32 m0, s12, 0x2000
	s_nop 0
	global_load_lds_dwordx4 v[248:249], off
	v_lshl_add_u64 v[248:249], s[86:87], 0, v[136:137]
	s_mov_b32 m0, s25
	s_nop 0
	global_load_lds_dwordx4 v[248:249], off
	v_lshl_add_u64 v[248:249], s[86:87], 0, v[132:133]
	s_mov_b32 m0, s26
	s_nop 0
	global_load_lds_dwordx4 v[248:249], off
	s_waitcnt vmcnt(8)
	s_waitcnt lgkmcnt(0)
	s_barrier
; #define PG8_STAGE(bufoff, gbase, voff) do { _Pragma("unroll") for (int _i = 0; _i < 2; ++_i) \
;         __builtin_amdgcn_global_load_lds((const unsigned*)((const char*)(gbase) + (voff)[_i]), (LAS unsigned*)(lds + (bufoff) + ldsw + _i * 8192), 16, 0, 0); } while (0)
; #define PG8_LDA(dst, b, h) do { _Pragma("unroll") for (int m = 0; m < 4; ++m) _Pragma("unroll") for (int k = 0; k < 2; ++k) dst[m][k] = *(const LAS bf16x8*)(lds + PG8_SA(b, h) + aoff + m * 2048 + k * 1024); } while (0)
; #define PG8_LDB(dst, b, h) do { _Pragma("unroll") for (int n = 0; n < 2; ++n) _Pragma("unroll") for (int k = 0; k < 2; ++k) dst[n][k] = *(const LAS bf16x8*)(lds + PG8_SB(b, h) + boff + n * 2048 + k * 1024); } while (0)
; #define PG8_MMA(ai, bj, At, Bt) do { __builtin_amdgcn_s_setprio(1); _Pragma("unroll") for (int m = 0; m < 4; ++m) _Pragma("unroll") for (int n = 0; n < 2; ++n) _Pragma("unroll") for (int k = 0; k < 2; ++k) \
;         acc[ai][bj][m][n] = __builtin_amdgcn_mfma_f32_16x16x32_bf16(Bt[n][k], At[m][k], acc[ai][bj][m][n], 0, 0, 0); __builtin_amdgcn_s_setprio(0); } while (0)
; #define PG8_WAIT_V(n) asm volatile("s_waitcnt vmcnt(" #n ")" ::: "memory")
; #define PG8_WAIT_L(n) asm volatile("s_waitcnt lgkmcnt(" #n ")" ::: "memory")
; #define PG8_BAR __builtin_amdgcn_s_barrier()
; #define PG8_SCHED __builtin_amdgcn_sched_barrier(0)
; template <class Epi>
; __device__ __forceinline__ void gemm_phase(LAS unsigned char* lds, const Gemm g, const StaticOrder& S, const Epi& E) {
;     ...
;             PG8_WAIT_V(8); PG8_WAIT_L(0); PG8_BAR; PG8_MMA(1, 0, At, B0); PG8_MMA(1, 1, At, B1); PG8_BAR; PG8_SCHED;
;             PG8_LDB(B0, 1, 0); PG8_LDB(B1, 1, 1); PG8_SCHED; PG8_LDA(At, 1, 0); PG8_STAGE(PG8_SA(0, 1), a2 + hstepA, voffA);
;             PG8_WAIT_V(8); PG8_WAIT_L(0); PG8_BAR; PG8_MMA(0, 0, At, B0); PG8_MMA(0, 1, At, B1); PG8_BAR; PG8_SCHED;
	s_setprio 1
	v_mfma_f32_16x16x32_bf16 v[62:65], v[148:151], v[202:205], v[62:65]
	v_mfma_f32_16x16x32_bf16 v[58:61], v[156:159], v[202:205], v[58:61]
	v_mfma_f32_16x16x32_bf16 v[46:49], v[148:151], v[222:225], v[46:49]
	v_mfma_f32_16x16x32_bf16 v[42:45], v[156:159], v[222:225], v[42:45]
	v_mfma_f32_16x16x32_bf16 v[30:33], v[148:151], v[230:233], v[30:33]
	v_mfma_f32_16x16x32_bf16 v[26:29], v[156:159], v[230:233], v[26:29]
	v_mfma_f32_16x16x32_bf16 v[14:17], v[148:151], v[238:241], v[14:17]
	v_mfma_f32_16x16x32_bf16 v[10:13], v[156:159], v[238:241], v[10:13]
	v_mfma_f32_16x16x32_bf16 v[62:65], v[152:155], v[206:209], v[62:65]
	v_mfma_f32_16x16x32_bf16 v[58:61], v[160:163], v[206:209], v[58:61]
	v_mfma_f32_16x16x32_bf16 v[46:49], v[152:155], v[226:229], v[46:49]
	v_mfma_f32_16x16x32_bf16 v[42:45], v[160:163], v[226:229], v[42:45]
	v_mfma_f32_16x16x32_bf16 v[30:33], v[152:155], v[234:237], v[30:33]
	v_mfma_f32_16x16x32_bf16 v[26:29], v[160:163], v[234:237], v[26:29]
	v_mfma_f32_16x16x32_bf16 v[14:17], v[152:155], v[242:245], v[14:17]
	v_mfma_f32_16x16x32_bf16 v[10:13], v[160:163], v[242:245], v[10:13]
	v_mfma_f32_16x16x32_bf16 v[54:57], v[186:189], v[202:205], v[54:57]
	v_mfma_f32_16x16x32_bf16 v[50:53], v[194:197], v[202:205], v[50:53]
	v_mfma_f32_16x16x32_bf16 v[38:41], v[186:189], v[222:225], v[38:41]
	v_mfma_f32_16x16x32_bf16 v[34:37], v[194:197], v[222:225], v[34:37]
	v_mfma_f32_16x16x32_bf16 v[22:25], v[186:189], v[230:233], v[22:25]
	v_mfma_f32_16x16x32_bf16 v[18:21], v[194:197], v[230:233], v[18:21]
	v_mfma_f32_16x16x32_bf16 v[6:9], v[186:189], v[238:241], v[6:9]
	v_mfma_f32_16x16x32_bf16 v[2:5], v[194:197], v[238:241], v[2:5]
	v_mfma_f32_16x16x32_bf16 v[54:57], v[190:193], v[206:209], v[54:57]
	v_mfma_f32_16x16x32_bf16 v[50:53], v[198:201], v[206:209], v[50:53]
	v_mfma_f32_16x16x32_bf16 v[38:41], v[190:193], v[226:229], v[38:41]
	v_mfma_f32_16x16x32_bf16 v[34:37], v[198:201], v[226:229], v[34:37]
	v_mfma_f32_16x16x32_bf16 v[22:25], v[190:193], v[234:237], v[22:25]
	v_mfma_f32_16x16x32_bf16 v[18:21], v[198:201], v[234:237], v[18:21]
	v_mfma_f32_16x16x32_bf16 v[6:9], v[190:193], v[242:245], v[6:9]
	v_mfma_f32_16x16x32_bf16 v[2:5], v[198:201], v[242:245], v[2:5]
	s_setprio 0
	s_barrier
	s_add_i32 s12, 0, 0x18000
	v_add_u32_e32 v147, s12, v1
	s_add_i32 s13, 0, 0x1c000
	ds_read_b128 v[148:151], v147
	ds_read_b128 v[152:155], v147 offset:1024
	ds_read_b128 v[156:159], v147 offset:2048
	ds_read_b128 v[160:163], v147 offset:3072
	v_add_u32_e32 v147, s13, v1
	ds_read_b128 v[186:189], v147
	ds_read_b128 v[190:193], v147 offset:1024
	ds_read_b128 v[194:197], v147 offset:2048
	ds_read_b128 v[198:201], v147 offset:3072
	s_add_u32 s44, s86, 0x80000
	s_addc_u32 s45, s87, 0
	s_mov_b32 m0, s27
	v_lshl_add_u64 v[248:249], s[44:45], 0, v[136:137]
	ds_read_b128 v[202:205], v146 offset:32768
	ds_read_b128 v[206:209], v146 offset:33792
	ds_read_b128 v[222:225], v146 offset:34816
	ds_read_b128 v[226:229], v146 offset:35840
	ds_read_b128 v[230:233], v146 offset:36864
	ds_read_b128 v[234:237], v146 offset:37888
	ds_read_b128 v[238:241], v146 offset:38912
	ds_read_b128 v[242:245], v146 offset:39936
	global_load_lds_dwordx4 v[248:249], off
	v_lshl_add_u64 v[248:249], s[44:45], 0, v[132:133]
	s_mov_b32 m0, s28
	s_nop 0
	global_load_lds_dwordx4 v[248:249], off
	s_waitcnt vmcnt(8)
	s_waitcnt lgkmcnt(0)
	s_barrier
	s_setprio 1
	v_mfma_f32_16x16x32_bf16 v[126:129], v[148:151], v[202:205], v[126:129]
	v_mfma_f32_16x16x32_bf16 v[122:125], v[156:159], v[202:205], v[122:125]
	v_mfma_f32_16x16x32_bf16 v[110:113], v[148:151], v[222:225], v[110:113]
	v_mfma_f32_16x16x32_bf16 v[106:109], v[156:159], v[222:225], v[106:109]
	v_mfma_f32_16x16x32_bf16 v[94:97], v[148:151], v[230:233], v[94:97]
	v_mfma_f32_16x16x32_bf16 v[90:93], v[156:159], v[230:233], v[90:93]
	v_mfma_f32_16x16x32_bf16 v[78:81], v[148:151], v[238:241], v[78:81]
	v_mfma_f32_16x16x32_bf16 v[74:77], v[156:159], v[238:241], v[74:77]
	v_mfma_f32_16x16x32_bf16 v[126:129], v[152:155], v[206:209], v[126:129]
	v_mfma_f32_16x16x32_bf16 v[122:125], v[160:163], v[206:209], v[122:125]
	v_mfma_f32_16x16x32_bf16 v[110:113], v[152:155], v[226:229], v[110:113]
	v_mfma_f32_16x16x32_bf16 v[106:109], v[160:163], v[226:229], v[106:109]
	v_mfma_f32_16x16x32_bf16 v[94:97], v[152:155], v[234:237], v[94:97]
	v_mfma_f32_16x16x32_bf16 v[90:93], v[160:163], v[234:237], v[90:93]
	v_mfma_f32_16x16x32_bf16 v[78:81], v[152:155], v[242:245], v[78:81]
	v_mfma_f32_16x16x32_bf16 v[74:77], v[160:163], v[242:245], v[74:77]
	v_mfma_f32_16x16x32_bf16 v[118:121], v[186:189], v[202:205], v[118:121]
	v_mfma_f32_16x16x32_bf16 v[114:117], v[194:197], v[202:205], v[114:117]
	v_mfma_f32_16x16x32_bf16 v[102:105], v[186:189], v[222:225], v[102:105]
	v_mfma_f32_16x16x32_bf16 v[98:101], v[194:197], v[222:225], v[98:101]
	v_mfma_f32_16x16x32_bf16 v[86:89], v[186:189], v[230:233], v[86:89]
	v_mfma_f32_16x16x32_bf16 v[82:85], v[194:197], v[230:233], v[82:85]
	v_mfma_f32_16x16x32_bf16 v[70:73], v[186:189], v[238:241], v[70:73]
	v_mfma_f32_16x16x32_bf16 v[66:69], v[194:197], v[238:241], v[66:69]
	v_mfma_f32_16x16x32_bf16 v[118:121], v[190:193], v[206:209], v[118:121]
	v_mfma_f32_16x16x32_bf16 v[114:117], v[198:201], v[206:209], v[114:117]
	v_mfma_f32_16x16x32_bf16 v[102:105], v[190:193], v[226:229], v[102:105]
	v_mfma_f32_16x16x32_bf16 v[98:101], v[198:201], v[226:229], v[98:101]
	v_mfma_f32_16x16x32_bf16 v[86:89], v[190:193], v[234:237], v[86:89]
	v_mfma_f32_16x16x32_bf16 v[82:85], v[198:201], v[234:237], v[82:85]
	v_mfma_f32_16x16x32_bf16 v[70:73], v[190:193], v[242:245], v[70:73]
	v_mfma_f32_16x16x32_bf16 v[66:69], v[198:201], v[242:245], v[66:69]
	s_setprio 0
	s_barrier
; #define PG8_STAGE(bufoff, gbase, voff) do { _Pragma("unroll") for (int _i = 0; _i < 2; ++_i) \
;         __builtin_amdgcn_global_load_lds((const unsigned*)((const char*)(gbase) + (voff)[_i]), (LAS unsigned*)(lds + (bufoff) + ldsw + _i * 8192), 16, 0, 0); } while (0)
; #define PG8_LDA(dst, b, h) do { _Pragma("unroll") for (int m = 0; m < 4; ++m) _Pragma("unroll") for (int k = 0; k < 2; ++k) dst[m][k] = *(const LAS bf16x8*)(lds + PG8_SA(b, h) + aoff + m * 2048 + k * 1024); } while (0)
; #define PG8_MMA(ai, bj, At, Bt) do { __builtin_amdgcn_s_setprio(1); _Pragma("unroll") for (int m = 0; m < 4; ++m) _Pragma("unroll") for (int n = 0; n < 2; ++n) _Pragma("unroll") for (int k = 0; k < 2; ++k) \
;         acc[ai][bj][m][n] = __builtin_amdgcn_mfma_f32_16x16x32_bf16(Bt[n][k], At[m][k], acc[ai][bj][m][n], 0, 0, 0); __builtin_amdgcn_s_setprio(0); } while (0)
; #define PG8_WAIT_V(n) asm volatile("s_waitcnt vmcnt(" #n ")" ::: "memory")
; #define PG8_WAIT_L(n) asm volatile("s_waitcnt lgkmcnt(" #n ")" ::: "memory")
; #define PG8_BAR __builtin_amdgcn_s_barrier()
; #define PG8_SCHED __builtin_amdgcn_sched_barrier(0)
; template <class Epi>
; __device__ __forceinline__ void gemm_phase(LAS unsigned char* lds, const Gemm g, const StaticOrder& S, const Epi& E) {
;     ...
;             PG8_LDA(At, 1, 1); PG8_STAGE(PG8_SB(1, 0), b3, voffB); PG8_STAGE(PG8_SB(1, 1), b3 + hstep, voffB); PG8_STAGE(PG8_SA(1, 0), a3, voffA);
;             PG8_WAIT_V(8); PG8_WAIT_L(0); PG8_BAR; PG8_MMA(1, 0, At, B0); PG8_MMA(1, 1, At, B1); PG8_BAR; PG8_SCHED;
;         }
;         if (wr == 0) PG8_BAR;
	s_add_i32 s12, s12, s24
	v_lshl_add_u64 v[212:213], v[212:213], 0, s[6:7]
	s_mov_b32 m0, s12
	ds_read_b128 v[202:205], v146 offset:49152
	ds_read_b128 v[206:209], v146 offset:50176
	ds_read_b128 v[222:225], v146 offset:51200
	ds_read_b128 v[226:229], v146 offset:52224
	ds_read_b128 v[230:233], v146 offset:53248
	ds_read_b128 v[234:237], v146 offset:54272
	ds_read_b128 v[238:241], v146 offset:55296
	ds_read_b128 v[242:245], v146 offset:56320
	global_load_lds_dwordx4 v[212:213], off
	s_add_i32 m0, s12, 0x2000
	s_add_u32 s44, s96, 0x80080
	v_lshl_add_u64 v[212:213], v[246:247], 0, s[6:7]
	s_addc_u32 s45, s97, 0
	s_add_i32 s12, s13, s24
	global_load_lds_dwordx4 v[212:213], off
	v_lshl_add_u64 v[212:213], s[44:45], 0, v[134:135]
	s_mov_b32 m0, s12
	s_nop 0
	global_load_lds_dwordx4 v[212:213], off
	v_lshl_add_u64 v[212:213], s[44:45], 0, v[130:131]
	s_add_i32 m0, s12, 0x2000
	s_nop 0
	global_load_lds_dwordx4 v[212:213], off
	v_lshl_add_u64 v[212:213], s[56:57], 0, v[136:137]
	s_mov_b32 m0, s29
	s_nop 0
	global_load_lds_dwordx4 v[212:213], off
	v_lshl_add_u64 v[212:213], s[56:57], 0, v[132:133]
	s_mov_b32 m0, s33
	s_nop 0
	global_load_lds_dwordx4 v[212:213], off
	s_waitcnt vmcnt(8)
	s_waitcnt lgkmcnt(0)
	s_barrier
	s_setprio 1
	v_mfma_f32_16x16x32_bf16 v[62:65], v[148:151], v[202:205], v[62:65]
	v_mfma_f32_16x16x32_bf16 v[58:61], v[156:159], v[202:205], v[58:61]
	v_mfma_f32_16x16x32_bf16 v[46:49], v[148:151], v[222:225], v[46:49]
	v_mfma_f32_16x16x32_bf16 v[42:45], v[156:159], v[222:225], v[42:45]
	v_mfma_f32_16x16x32_bf16 v[30:33], v[148:151], v[230:233], v[30:33]
	v_mfma_f32_16x16x32_bf16 v[26:29], v[156:159], v[230:233], v[26:29]
	v_mfma_f32_16x16x32_bf16 v[14:17], v[148:151], v[238:241], v[14:17]
	v_mfma_f32_16x16x32_bf16 v[10:13], v[156:159], v[238:241], v[10:13]
	v_mfma_f32_16x16x32_bf16 v[62:65], v[152:155], v[206:209], v[62:65]
	v_mfma_f32_16x16x32_bf16 v[58:61], v[160:163], v[206:209], v[58:61]
	v_mfma_f32_16x16x32_bf16 v[46:49], v[152:155], v[226:229], v[46:49]
	v_mfma_f32_16x16x32_bf16 v[42:45], v[160:163], v[226:229], v[42:45]
	v_mfma_f32_16x16x32_bf16 v[30:33], v[152:155], v[234:237], v[30:33]
	v_mfma_f32_16x16x32_bf16 v[26:29], v[160:163], v[234:237], v[26:29]
	v_mfma_f32_16x16x32_bf16 v[14:17], v[152:155], v[242:245], v[14:17]
	v_mfma_f32_16x16x32_bf16 v[10:13], v[160:163], v[242:245], v[10:13]
	v_mfma_f32_16x16x32_bf16 v[54:57], v[186:189], v[202:205], v[54:57]
	v_mfma_f32_16x16x32_bf16 v[50:53], v[194:197], v[202:205], v[50:53]
	v_mfma_f32_16x16x32_bf16 v[38:41], v[186:189], v[222:225], v[38:41]
	v_mfma_f32_16x16x32_bf16 v[34:37], v[194:197], v[222:225], v[34:37]
	v_mfma_f32_16x16x32_bf16 v[22:25], v[186:189], v[230:233], v[22:25]
	v_mfma_f32_16x16x32_bf16 v[18:21], v[194:197], v[230:233], v[18:21]
	v_mfma_f32_16x16x32_bf16 v[6:9], v[186:189], v[238:241], v[6:9]
	v_mfma_f32_16x16x32_bf16 v[2:5], v[194:197], v[238:241], v[2:5]
	v_mfma_f32_16x16x32_bf16 v[54:57], v[190:193], v[206:209], v[54:57]
	v_mfma_f32_16x16x32_bf16 v[50:53], v[198:201], v[206:209], v[50:53]
	v_mfma_f32_16x16x32_bf16 v[38:41], v[190:193], v[226:229], v[38:41]
	v_mfma_f32_16x16x32_bf16 v[34:37], v[198:201], v[226:229], v[34:37]
	v_mfma_f32_16x16x32_bf16 v[22:25], v[190:193], v[234:237], v[22:25]
	v_mfma_f32_16x16x32_bf16 v[18:21], v[198:201], v[234:237], v[18:21]
	v_mfma_f32_16x16x32_bf16 v[6:9], v[190:193], v[242:245], v[6:9]
	v_mfma_f32_16x16x32_bf16 v[2:5], v[198:201], v[242:245], v[2:5]
	s_setprio 0
	s_barrier
	s_add_i32 vcc_lo, vcc_lo, 2
	s_add_u32 s54, s54, 0x100
	s_addc_u32 s55, s55, 0
	s_cmp_gt_u32 vcc_lo, 29
	s_cbranch_scc0 .LBB0_644
	s_and_b64 vcc, exec, s[36:37]
	s_cbranch_vccz .LBB0_647
	s_barrier

; #define PG8_STAGE(bufoff, gbase, voff) do { _Pragma("unroll") for (int _i = 0; _i < 2; ++_i) \
;         __builtin_amdgcn_global_load_lds((const unsigned*)((const char*)(gbase) + (voff)[_i]), (LAS unsigned*)(lds + (bufoff) + ldsw + _i * 8192), 16, 0, 0); } while (0)
; #define PG8_LDA(dst, b, h) do { _Pragma("unroll") for (int m = 0; m < 4; ++m) _Pragma("unroll") for (int k = 0; k < 2; ++k) dst[m][k] = *(const LAS bf16x8*)(lds + PG8_SA(b, h) + aoff + m * 2048 + k * 1024); } while (0)
; #define PG8_LDB(dst, b, h) do { _Pragma("unroll") for (int n = 0; n < 2; ++n) _Pragma("unroll") for (int k = 0; k < 2; ++k) dst[n][k] = *(const LAS bf16x8*)(lds + PG8_SB(b, h) + boff + n * 2048 + k * 1024); } while (0)
; #define PG8_MMA(ai, bj, At, Bt) do { __builtin_amdgcn_s_setprio(1); _Pragma("unroll") for (int m = 0; m < 4; ++m) _Pragma("unroll") for (int n = 0; n < 2; ++n) _Pragma("unroll") for (int k = 0; k < 2; ++k) \
;         acc[ai][bj][m][n] = __builtin_amdgcn_mfma_f32_16x16x32_bf16(Bt[n][k], At[m][k], acc[ai][bj][m][n], 0, 0, 0); __builtin_amdgcn_s_setprio(0); } while (0)
; #define PG8_WAIT_V(n) asm volatile("s_waitcnt vmcnt(" #n ")" ::: "memory")
; #define PG8_WAIT_L(n) asm volatile("s_waitcnt lgkmcnt(" #n ")" ::: "memory")
; #define PG8_BAR __builtin_amdgcn_s_barrier()
; template <class Epi>
; __device__ __forceinline__ void gemm_phase(LAS unsigned char* lds, const Gemm g, const StaticOrder& S, const Epi& E) {
;     ...
;             if constexpr (Epi::GATED) { if (t == 8 || t == 16) E.rescale(acc, cur, t == 8 ? 0 : 1, wr, wc, fr, fq); }
;             const bool last = (t == nt - 2);
;             const char* a1 = PG8_AP(cA, t + 1);
;             const char* a2 = last ? nA : PG8_AP(cA, t + 2); const char* b2 = last ? nB : cB + (size_t)(t + 2) * kstep;
;             const char* a3 = last ? nA + kstep : PG8_AP(cA, t + 3); const char* b3 = b2 + kstep;
;             PG8_LDB(B0, 0, 0); PG8_LDB(B1, 0, 1); PG8_SCHED; PG8_LDA(At, 0, 0); PG8_STAGE(PG8_SA(1, 1), a1 + hstepA, voffA);
;             PG8_WAIT_V(8); PG8_WAIT_L(0); PG8_BAR; PG8_MMA(0, 0, At, B0); PG8_MMA(0, 1, At, B1); PG8_BAR; PG8_SCHED;
;             PG8_LDA(At, 0, 1); PG8_STAGE(PG8_SB(0, 0), b2, voffB); PG8_STAGE(PG8_SB(0, 1), b2 + hstep, voffB); PG8_STAGE(PG8_SA(0, 0), a2, voffA);
;             PG8_WAIT_V(8); PG8_WAIT_L(0); PG8_BAR; PG8_MMA(1, 0, At, B0); PG8_MMA(1, 1, At, B1); PG8_BAR; PG8_SCHED;
.LBB0_881:
	s_cmp_gt_u32 s33, 15
	s_cselect_b32 s12, 0xfdeff800, 0
	s_cselect_b32 s13, -1, 0
	s_cmp_gt_u32 s33, 13
	s_cselect_b32 s87, 0xfdeff800, 0
	s_cselect_b32 s86, -1, 0
	s_add_u32 s87, s87, s36
	s_addc_u32 s86, s86, s37
	s_add_u32 s87, s56, s87
	s_addc_u32 s86, s57, s86
	s_add_u32 s90, s87, 0x100
	s_addc_u32 s86, s86, 0
	s_add_u32 s87, s80, s36
	s_addc_u32 s91, s81, s37
	s_cmp_gt_u32 s33, 12
	s_cselect_b32 s96, 0xfdeff800, 0
	s_cselect_b32 s94, -1, 0
	s_add_u32 s96, s96, s36
	s_addc_u32 s94, s94, s37
	s_add_u32 s96, s56, s96
	s_addc_u32 s94, s57, s94
	s_add_u32 s96, s96, 0x180
	s_addc_u32 s94, s94, 0
	s_add_i32 s14, 0, 0x10000
	s_add_i32 s15, 0, 0x14000
	v_add_u32_e32 v1, s14, v162
	ds_read_b128 v[132:135], v1
	ds_read_b128 v[136:139], v1 offset:1024
	ds_read_b128 v[156:159], v1 offset:2048
	ds_read_b128 v[186:189], v1 offset:3072
	v_add_u32_e32 v1, s15, v162
	ds_read_b128 v[190:193], v1
	ds_read_b128 v[194:197], v1 offset:1024
	ds_read_b128 v[198:201], v1 offset:2048
	ds_read_b128 v[202:205], v1 offset:3072
	s_cmpk_eq_i32 s36, 0xf00
	s_cselect_b32 vcc_lo, s4, s87
	s_cselect_b32 s87, s55, s86
	s_cselect_b32 s86, s92, s90
	s_cselect_b32 s97, s52, s94
	s_cselect_b32 s96, s5, s96
	s_cselect_b32 vcc_hi, s67, s91
	s_add_u32 s90, s12, s36
	s_addc_u32 s91, s13, s37
	v_lshl_add_u64 v[2:3], v[152:153], 0, s[90:91]
	s_add_i32 m0, s93, 0xc000
	ds_read_b128 v[206:209], v163
	ds_read_b128 v[222:225], v163 offset:1024
	ds_read_b128 v[226:229], v163 offset:2048
	ds_read_b128 v[230:233], v163 offset:3072
	ds_read_b128 v[234:237], v163 offset:4096
	ds_read_b128 v[238:241], v163 offset:5120
	ds_read_b128 v[242:245], v163 offset:6144
	ds_read_b128 v[246:249], v163 offset:7168
	global_load_lds_dwordx4 v[2:3], off
	v_lshl_add_u64 v[2:3], v[154:155], 0, s[90:91]
	s_add_i32 m0, s93, 0xe000
	s_nop 0
	global_load_lds_dwordx4 v[2:3], off
	s_waitcnt vmcnt(8)
	s_waitcnt lgkmcnt(0)
	s_barrier
	s_setprio 1
	v_mfma_f32_16x16x32_bf16 v[128:131], v[132:135], v[206:209], v[128:131]
	v_mfma_f32_16x16x32_bf16 v[124:127], v[156:159], v[206:209], v[124:127]
	v_mfma_f32_16x16x32_bf16 v[112:115], v[132:135], v[226:229], v[112:115]
	v_mfma_f32_16x16x32_bf16 v[108:111], v[156:159], v[226:229], v[108:111]
	v_mfma_f32_16x16x32_bf16 v[96:99], v[132:135], v[234:237], v[96:99]
	v_mfma_f32_16x16x32_bf16 v[92:95], v[156:159], v[234:237], v[92:95]
	v_mfma_f32_16x16x32_bf16 v[80:83], v[132:135], v[242:245], v[80:83]
	v_mfma_f32_16x16x32_bf16 v[76:79], v[156:159], v[242:245], v[76:79]
	v_mfma_f32_16x16x32_bf16 v[128:131], v[136:139], v[222:225], v[128:131]
	v_mfma_f32_16x16x32_bf16 v[124:127], v[186:189], v[222:225], v[124:127]
	v_mfma_f32_16x16x32_bf16 v[112:115], v[136:139], v[230:233], v[112:115]
	v_mfma_f32_16x16x32_bf16 v[108:111], v[186:189], v[230:233], v[108:111]
	v_mfma_f32_16x16x32_bf16 v[96:99], v[136:139], v[238:241], v[96:99]
	v_mfma_f32_16x16x32_bf16 v[92:95], v[186:189], v[238:241], v[92:95]
	v_mfma_f32_16x16x32_bf16 v[80:83], v[136:139], v[246:249], v[80:83]
	v_mfma_f32_16x16x32_bf16 v[76:79], v[186:189], v[246:249], v[76:79]
	v_mfma_f32_16x16x32_bf16 v[120:123], v[190:193], v[206:209], v[120:123]
	v_mfma_f32_16x16x32_bf16 v[116:119], v[198:201], v[206:209], v[116:119]
	v_mfma_f32_16x16x32_bf16 v[104:107], v[190:193], v[226:229], v[104:107]
	v_mfma_f32_16x16x32_bf16 v[100:103], v[198:201], v[226:229], v[100:103]
	v_mfma_f32_16x16x32_bf16 v[88:91], v[190:193], v[234:237], v[88:91]
	v_mfma_f32_16x16x32_bf16 v[84:87], v[198:201], v[234:237], v[84:87]
	v_mfma_f32_16x16x32_bf16 v[72:75], v[190:193], v[242:245], v[72:75]
	v_mfma_f32_16x16x32_bf16 v[68:71], v[198:201], v[242:245], v[68:71]
	v_mfma_f32_16x16x32_bf16 v[120:123], v[194:197], v[222:225], v[120:123]
	v_mfma_f32_16x16x32_bf16 v[116:119], v[202:205], v[222:225], v[116:119]
	v_mfma_f32_16x16x32_bf16 v[104:107], v[194:197], v[230:233], v[104:107]
	v_mfma_f32_16x16x32_bf16 v[100:103], v[202:205], v[230:233], v[100:103]
	v_mfma_f32_16x16x32_bf16 v[88:91], v[194:197], v[238:241], v[88:91]
	v_mfma_f32_16x16x32_bf16 v[84:87], v[202:205], v[238:241], v[84:87]
	v_mfma_f32_16x16x32_bf16 v[72:75], v[194:197], v[246:249], v[72:75]
	v_mfma_f32_16x16x32_bf16 v[68:71], v[202:205], v[246:249], v[68:71]
	s_setprio 0
	s_barrier
	s_add_i32 s12, s14, s85
	v_lshl_add_u64 v[160:161], vcc, 0, v[144:145]
	s_mov_b32 m0, s12
	ds_read_b128 v[206:209], v163 offset:16384
	ds_read_b128 v[222:225], v163 offset:17408
	ds_read_b128 v[226:229], v163 offset:18432
	ds_read_b128 v[230:233], v163 offset:19456
	ds_read_b128 v[234:237], v163 offset:20480
	ds_read_b128 v[238:241], v163 offset:21504
	ds_read_b128 v[242:245], v163 offset:22528
	ds_read_b128 v[246:249], v163 offset:23552
	global_load_lds_dwordx4 v[160:161], off
	s_add_i32 m0, s12, 0x2000
	s_add_u32 s90, vcc_lo, 0x80000
	v_lshl_add_u64 v[212:213], vcc, 0, v[140:141]
	s_addc_u32 s91, vcc_hi, 0
	s_add_i32 s12, s15, s85
	global_load_lds_dwordx4 v[212:213], off
	v_lshl_add_u64 v[2:3], s[90:91], 0, v[144:145]
	s_mov_b32 m0, s12
	s_nop 0
	global_load_lds_dwordx4 v[2:3], off
	v_lshl_add_u64 v[2:3], s[90:91], 0, v[140:141]
	s_add_i32 m0, s12, 0x2000
	s_nop 0
	global_load_lds_dwordx4 v[2:3], off
	v_lshl_add_u64 v[2:3], s[86:87], 0, v[146:147]
	s_mov_b32 m0, s93
	s_nop 0
	global_load_lds_dwordx4 v[2:3], off
	v_lshl_add_u64 v[2:3], s[86:87], 0, v[142:143]
	s_mov_b32 m0, s24
	s_nop 0
	global_load_lds_dwordx4 v[2:3], off
	s_waitcnt vmcnt(8)
	s_waitcnt lgkmcnt(0)
	s_barrier
; #define PG8_STAGE(bufoff, gbase, voff) do { _Pragma("unroll") for (int _i = 0; _i < 2; ++_i) \
;         __builtin_amdgcn_global_load_lds((const unsigned*)((const char*)(gbase) + (voff)[_i]), (LAS unsigned*)(lds + (bufoff) + ldsw + _i * 8192), 16, 0, 0); } while (0)
; #define PG8_LDA(dst, b, h) do { _Pragma("unroll") for (int m = 0; m < 4; ++m) _Pragma("unroll") for (int k = 0; k < 2; ++k) dst[m][k] = *(const LAS bf16x8*)(lds + PG8_SA(b, h) + aoff + m * 2048 + k * 1024); } while (0)
; #define PG8_LDB(dst, b, h) do { _Pragma("unroll") for (int n = 0; n < 2; ++n) _Pragma("unroll") for (int k = 0; k < 2; ++k) dst[n][k] = *(const LAS bf16x8*)(lds + PG8_SB(b, h) + boff + n * 2048 + k * 1024); } while (0)
; #define PG8_MMA(ai, bj, At, Bt) do { __builtin_amdgcn_s_setprio(1); _Pragma("unroll") for (int m = 0; m < 4; ++m) _Pragma("unroll") for (int n = 0; n < 2; ++n) _Pragma("unroll") for (int k = 0; k < 2; ++k) \
;         acc[ai][bj][m][n] = __builtin_amdgcn_mfma_f32_16x16x32_bf16(Bt[n][k], At[m][k], acc[ai][bj][m][n], 0, 0, 0); __builtin_amdgcn_s_setprio(0); } while (0)
; #define PG8_WAIT_V(n) asm volatile("s_waitcnt vmcnt(" #n ")" ::: "memory")
; #define PG8_WAIT_L(n) asm volatile("s_waitcnt lgkmcnt(" #n ")" ::: "memory")
; #define PG8_BAR __builtin_amdgcn_s_barrier()
; #define PG8_SCHED __builtin_amdgcn_sched_barrier(0)
; template <class Epi>
; __device__ __forceinline__ void gemm_phase(LAS unsigned char* lds, const Gemm g, const StaticOrder& S, const Epi& E) {
;     ...
;             PG8_WAIT_V(8); PG8_WAIT_L(0); PG8_BAR; PG8_MMA(1, 0, At, B0); PG8_MMA(1, 1, At, B1); PG8_BAR; PG8_SCHED;
;             PG8_LDB(B0, 1, 0); PG8_LDB(B1, 1, 1); PG8_SCHED; PG8_LDA(At, 1, 0); PG8_STAGE(PG8_SA(0, 1), a2 + hstepA, voffA);
;             PG8_WAIT_V(8); PG8_WAIT_L(0); PG8_BAR; PG8_MMA(0, 0, At, B0); PG8_MMA(0, 1, At, B1); PG8_BAR; PG8_SCHED;
	s_setprio 1
	v_mfma_f32_16x16x32_bf16 v[64:67], v[132:135], v[206:209], v[64:67]
	v_mfma_f32_16x16x32_bf16 v[60:63], v[156:159], v[206:209], v[60:63]
	v_mfma_f32_16x16x32_bf16 v[48:51], v[132:135], v[226:229], v[48:51]
	v_mfma_f32_16x16x32_bf16 v[44:47], v[156:159], v[226:229], v[44:47]
	v_mfma_f32_16x16x32_bf16 v[32:35], v[132:135], v[234:237], v[32:35]
	v_mfma_f32_16x16x32_bf16 v[28:31], v[156:159], v[234:237], v[28:31]
	v_mfma_f32_16x16x32_bf16 v[16:19], v[132:135], v[242:245], v[16:19]
	v_mfma_f32_16x16x32_bf16 v[12:15], v[156:159], v[242:245], v[12:15]
	v_mfma_f32_16x16x32_bf16 v[64:67], v[136:139], v[222:225], v[64:67]
	v_mfma_f32_16x16x32_bf16 v[60:63], v[186:189], v[222:225], v[60:63]
	v_mfma_f32_16x16x32_bf16 v[48:51], v[136:139], v[230:233], v[48:51]
	v_mfma_f32_16x16x32_bf16 v[44:47], v[186:189], v[230:233], v[44:47]
	v_mfma_f32_16x16x32_bf16 v[32:35], v[136:139], v[238:241], v[32:35]
	v_mfma_f32_16x16x32_bf16 v[28:31], v[186:189], v[238:241], v[28:31]
	v_mfma_f32_16x16x32_bf16 v[16:19], v[136:139], v[246:249], v[16:19]
	v_mfma_f32_16x16x32_bf16 v[12:15], v[186:189], v[246:249], v[12:15]
	v_mfma_f32_16x16x32_bf16 v[56:59], v[190:193], v[206:209], v[56:59]
	v_mfma_f32_16x16x32_bf16 v[52:55], v[198:201], v[206:209], v[52:55]
	v_mfma_f32_16x16x32_bf16 v[40:43], v[190:193], v[226:229], v[40:43]
	v_mfma_f32_16x16x32_bf16 v[36:39], v[198:201], v[226:229], v[36:39]
	v_mfma_f32_16x16x32_bf16 v[24:27], v[190:193], v[234:237], v[24:27]
	v_mfma_f32_16x16x32_bf16 v[20:23], v[198:201], v[234:237], v[20:23]
	v_mfma_f32_16x16x32_bf16 v[8:11], v[190:193], v[242:245], v[8:11]
	v_mfma_f32_16x16x32_bf16 v[2:5], v[198:201], v[242:245], v[4:7]
	v_mfma_f32_16x16x32_bf16 v[56:59], v[194:197], v[222:225], v[56:59]
	v_mfma_f32_16x16x32_bf16 v[52:55], v[202:205], v[222:225], v[52:55]
	v_mfma_f32_16x16x32_bf16 v[40:43], v[194:197], v[230:233], v[40:43]
	v_mfma_f32_16x16x32_bf16 v[36:39], v[202:205], v[230:233], v[36:39]
	v_mfma_f32_16x16x32_bf16 v[24:27], v[194:197], v[238:241], v[24:27]
	v_mfma_f32_16x16x32_bf16 v[20:23], v[202:205], v[238:241], v[20:23]
	v_mfma_f32_16x16x32_bf16 v[8:11], v[194:197], v[246:249], v[8:11]
	v_mfma_f32_16x16x32_bf16 v[2:5], v[202:205], v[246:249], v[2:5]
	s_setprio 0
	s_barrier
	s_add_i32 s12, 0, 0x18000
	v_add_u32_e32 v1, s12, v162
	s_add_i32 s13, 0, 0x1c000
	ds_read_b128 v[132:135], v1
	ds_read_b128 v[136:139], v1 offset:1024
	ds_read_b128 v[156:159], v1 offset:2048
	ds_read_b128 v[186:189], v1 offset:3072
	v_add_u32_e32 v1, s13, v162
	ds_read_b128 v[190:193], v1
	ds_read_b128 v[194:197], v1 offset:1024
	ds_read_b128 v[198:201], v1 offset:2048
	ds_read_b128 v[202:205], v1 offset:3072
	s_add_u32 s86, s86, 0x40000
	s_addc_u32 s87, s87, 0
	s_mov_b32 m0, s25
	v_lshl_add_u64 v[6:7], s[86:87], 0, v[146:147]
	ds_read_b128 v[206:209], v163 offset:32768
	ds_read_b128 v[222:225], v163 offset:33792
	ds_read_b128 v[226:229], v163 offset:34816
	ds_read_b128 v[230:233], v163 offset:35840
	ds_read_b128 v[234:237], v163 offset:36864
	ds_read_b128 v[238:241], v163 offset:37888
	ds_read_b128 v[242:245], v163 offset:38912
	ds_read_b128 v[246:249], v163 offset:39936
	global_load_lds_dwordx4 v[6:7], off
	v_lshl_add_u64 v[6:7], s[86:87], 0, v[142:143]
	s_mov_b32 m0, s26
	s_nop 0
	global_load_lds_dwordx4 v[6:7], off
	s_waitcnt vmcnt(8)
	s_waitcnt lgkmcnt(0)
	s_barrier
	s_setprio 1
	v_mfma_f32_16x16x32_bf16 v[128:131], v[132:135], v[206:209], v[128:131]
	v_mfma_f32_16x16x32_bf16 v[124:127], v[156:159], v[206:209], v[124:127]
	v_mfma_f32_16x16x32_bf16 v[112:115], v[132:135], v[226:229], v[112:115]
	v_mfma_f32_16x16x32_bf16 v[108:111], v[156:159], v[226:229], v[108:111]
	v_mfma_f32_16x16x32_bf16 v[96:99], v[132:135], v[234:237], v[96:99]
	v_mfma_f32_16x16x32_bf16 v[92:95], v[156:159], v[234:237], v[92:95]
	v_mfma_f32_16x16x32_bf16 v[80:83], v[132:135], v[242:245], v[80:83]
	v_mfma_f32_16x16x32_bf16 v[76:79], v[156:159], v[242:245], v[76:79]
	v_mfma_f32_16x16x32_bf16 v[128:131], v[136:139], v[222:225], v[128:131]
	v_mfma_f32_16x16x32_bf16 v[124:127], v[186:189], v[222:225], v[124:127]
	v_mfma_f32_16x16x32_bf16 v[112:115], v[136:139], v[230:233], v[112:115]
	v_mfma_f32_16x16x32_bf16 v[108:111], v[186:189], v[230:233], v[108:111]
	v_mfma_f32_16x16x32_bf16 v[96:99], v[136:139], v[238:241], v[96:99]
	v_mfma_f32_16x16x32_bf16 v[92:95], v[186:189], v[238:241], v[92:95]
	v_mfma_f32_16x16x32_bf16 v[80:83], v[136:139], v[246:249], v[80:83]
	v_mfma_f32_16x16x32_bf16 v[76:79], v[186:189], v[246:249], v[76:79]
	v_mfma_f32_16x16x32_bf16 v[120:123], v[190:193], v[206:209], v[120:123]
	v_mfma_f32_16x16x32_bf16 v[116:119], v[198:201], v[206:209], v[116:119]
	v_mfma_f32_16x16x32_bf16 v[104:107], v[190:193], v[226:229], v[104:107]
	v_mfma_f32_16x16x32_bf16 v[100:103], v[198:201], v[226:229], v[100:103]
	v_mfma_f32_16x16x32_bf16 v[88:91], v[190:193], v[234:237], v[88:91]
	v_mfma_f32_16x16x32_bf16 v[84:87], v[198:201], v[234:237], v[84:87]
	v_mfma_f32_16x16x32_bf16 v[72:75], v[190:193], v[242:245], v[72:75]
	v_mfma_f32_16x16x32_bf16 v[68:71], v[198:201], v[242:245], v[68:71]
	v_mfma_f32_16x16x32_bf16 v[120:123], v[194:197], v[222:225], v[120:123]
	v_mfma_f32_16x16x32_bf16 v[116:119], v[202:205], v[222:225], v[116:119]
	v_mfma_f32_16x16x32_bf16 v[104:107], v[194:197], v[230:233], v[104:107]
	v_mfma_f32_16x16x32_bf16 v[100:103], v[202:205], v[230:233], v[100:103]
	v_mfma_f32_16x16x32_bf16 v[88:91], v[194:197], v[238:241], v[88:91]
	v_mfma_f32_16x16x32_bf16 v[84:87], v[202:205], v[238:241], v[84:87]
	v_mfma_f32_16x16x32_bf16 v[72:75], v[194:197], v[246:249], v[72:75]
	v_mfma_f32_16x16x32_bf16 v[68:71], v[202:205], v[246:249], v[68:71]
	s_setprio 0
	s_barrier
; #define PG8_STAGE(bufoff, gbase, voff) do { _Pragma("unroll") for (int _i = 0; _i < 2; ++_i) \
;         __builtin_amdgcn_global_load_lds((const unsigned*)((const char*)(gbase) + (voff)[_i]), (LAS unsigned*)(lds + (bufoff) + ldsw + _i * 8192), 16, 0, 0); } while (0)
; #define PG8_LDA(dst, b, h) do { _Pragma("unroll") for (int m = 0; m < 4; ++m) _Pragma("unroll") for (int k = 0; k < 2; ++k) dst[m][k] = *(const LAS bf16x8*)(lds + PG8_SA(b, h) + aoff + m * 2048 + k * 1024); } while (0)
; #define PG8_LDB(dst, b, h) do { _Pragma("unroll") for (int n = 0; n < 2; ++n) _Pragma("unroll") for (int k = 0; k < 2; ++k) dst[n][k] = *(const LAS bf16x8*)(lds + PG8_SB(b, h) + boff + n * 2048 + k * 1024); } while (0)
; #define PG8_BAR __builtin_amdgcn_s_barrier()
; template <class Epi>
; __device__ __forceinline__ void gemm_phase(LAS unsigned char* lds, const Gemm g, const StaticOrder& S, const Epi& E) {
;     ...
;             if constexpr (Epi::GATED) { if (t == 8 || t == 16) E.rescale(acc, cur, t == 8 ? 0 : 1, wr, wc, fr, fq); }
;             const bool last = (t == nt - 2);
;             const char* a1 = PG8_AP(cA, t + 1);
;             const char* a2 = last ? nA : PG8_AP(cA, t + 2); const char* b2 = last ? nB : cB + (size_t)(t + 2) * kstep;
;             const char* a3 = last ? nA + kstep : PG8_AP(cA, t + 3); const char* b3 = b2 + kstep;
;             PG8_LDB(B0, 0, 0); PG8_LDB(B1, 0, 1); PG8_SCHED; PG8_LDA(At, 0, 0); PG8_STAGE(PG8_SA(1, 1), a1 + hstepA, voffA);
;             PG8_WAIT_V(8); PG8_WAIT_L(0); PG8_BAR; PG8_MMA(0, 0, At, B0); PG8_MMA(0, 1, At, B1); PG8_BAR; PG8_SCHED;
;             PG8_LDA(At, 0, 1); PG8_STAGE(PG8_SB(0, 0), b2, voffB); PG8_STAGE(PG8_SB(0, 1), b2 + hstep, voffB); PG8_STAGE(PG8_SA(0, 0), a2, voffA);
;             PG8_WAIT_V(8); PG8_WAIT_L(0); PG8_BAR; PG8_MMA(1, 0, At, B0); PG8_MMA(1, 1, At, B1); PG8_BAR; PG8_SCHED;
;             PG8_LDB(B0, 1, 0); PG8_LDB(B1, 1, 1); PG8_SCHED; PG8_LDA(At, 1, 0); PG8_STAGE(PG8_SA(0, 1), a2 + hstepA, voffA);
;             PG8_WAIT_V(8); PG8_WAIT_L(0); PG8_BAR; PG8_MMA(0, 0, At, B0); PG8_MMA(0, 1, At, B1); PG8_BAR; PG8_SCHED;
;             PG8_LDA(At, 1, 1); PG8_STAGE(PG8_SB(1, 0), b3, voffB); PG8_STAGE(PG8_SB(1, 1), b3 + hstep, voffB); PG8_STAGE(PG8_SA(1, 0), a3, voffA);
;             PG8_WAIT_V(8); PG8_WAIT_L(0); PG8_BAR; PG8_MMA(1, 0, At, B0); PG8_MMA(1, 1, At, B1); PG8_BAR; PG8_SCHED;
;         }
	s_add_i32 s12, s12, s85
	v_lshl_add_u64 v[6:7], v[160:161], 0, s[6:7]
	s_mov_b32 m0, s12
	ds_read_b128 v[206:209], v163 offset:49152
	ds_read_b128 v[222:225], v163 offset:50176
	ds_read_b128 v[226:229], v163 offset:51200
	ds_read_b128 v[230:233], v163 offset:52224
	ds_read_b128 v[234:237], v163 offset:53248
	ds_read_b128 v[238:241], v163 offset:54272
	ds_read_b128 v[242:245], v163 offset:55296
	ds_read_b128 v[246:249], v163 offset:56320
	global_load_lds_dwordx4 v[6:7], off
	s_add_i32 m0, s12, 0x2000
	s_add_u32 s86, vcc_lo, 0x80080
	v_lshl_add_u64 v[6:7], v[212:213], 0, s[6:7]
	s_addc_u32 s87, vcc_hi, 0
	s_add_i32 s12, s13, s85
	global_load_lds_dwordx4 v[6:7], off
	v_lshl_add_u64 v[6:7], s[86:87], 0, v[144:145]
	s_mov_b32 m0, s12
	s_nop 0
	global_load_lds_dwordx4 v[6:7], off
	v_lshl_add_u64 v[6:7], s[86:87], 0, v[140:141]
	s_add_i32 m0, s12, 0x2000
	s_nop 0
	global_load_lds_dwordx4 v[6:7], off
	v_lshl_add_u64 v[6:7], s[96:97], 0, v[146:147]
	s_mov_b32 m0, s27
	s_nop 0
	global_load_lds_dwordx4 v[6:7], off
	v_lshl_add_u64 v[6:7], s[96:97], 0, v[142:143]
	s_mov_b32 m0, s38
	s_nop 0
	global_load_lds_dwordx4 v[6:7], off
	s_waitcnt vmcnt(8)
	s_waitcnt lgkmcnt(0)
	s_barrier
	s_setprio 1
	v_mfma_f32_16x16x32_bf16 v[64:67], v[132:135], v[206:209], v[64:67]
	v_mfma_f32_16x16x32_bf16 v[60:63], v[156:159], v[206:209], v[60:63]
	v_mfma_f32_16x16x32_bf16 v[48:51], v[132:135], v[226:229], v[48:51]
	v_mfma_f32_16x16x32_bf16 v[44:47], v[156:159], v[226:229], v[44:47]
	v_mfma_f32_16x16x32_bf16 v[32:35], v[132:135], v[234:237], v[32:35]
	v_mfma_f32_16x16x32_bf16 v[28:31], v[156:159], v[234:237], v[28:31]
	v_mfma_f32_16x16x32_bf16 v[16:19], v[132:135], v[242:245], v[16:19]
	v_mfma_f32_16x16x32_bf16 v[12:15], v[156:159], v[242:245], v[12:15]
	v_mfma_f32_16x16x32_bf16 v[64:67], v[136:139], v[222:225], v[64:67]
	v_mfma_f32_16x16x32_bf16 v[60:63], v[186:189], v[222:225], v[60:63]
	v_mfma_f32_16x16x32_bf16 v[48:51], v[136:139], v[230:233], v[48:51]
	v_mfma_f32_16x16x32_bf16 v[44:47], v[186:189], v[230:233], v[44:47]
	v_mfma_f32_16x16x32_bf16 v[32:35], v[136:139], v[238:241], v[32:35]
	v_mfma_f32_16x16x32_bf16 v[28:31], v[186:189], v[238:241], v[28:31]
	v_mfma_f32_16x16x32_bf16 v[16:19], v[136:139], v[246:249], v[16:19]
	v_mfma_f32_16x16x32_bf16 v[12:15], v[186:189], v[246:249], v[12:15]
	v_mfma_f32_16x16x32_bf16 v[56:59], v[190:193], v[206:209], v[56:59]
	v_mfma_f32_16x16x32_bf16 v[52:55], v[198:201], v[206:209], v[52:55]
	v_mfma_f32_16x16x32_bf16 v[40:43], v[190:193], v[226:229], v[40:43]
	v_mfma_f32_16x16x32_bf16 v[36:39], v[198:201], v[226:229], v[36:39]
	v_mfma_f32_16x16x32_bf16 v[24:27], v[190:193], v[234:237], v[24:27]
	v_mfma_f32_16x16x32_bf16 v[20:23], v[198:201], v[234:237], v[20:23]
	v_mfma_f32_16x16x32_bf16 v[6:9], v[190:193], v[242:245], v[8:11]
	v_mfma_f32_16x16x32_bf16 v[2:5], v[198:201], v[242:245], v[2:5]
	v_mfma_f32_16x16x32_bf16 v[56:59], v[194:197], v[222:225], v[56:59]
	v_mfma_f32_16x16x32_bf16 v[52:55], v[202:205], v[222:225], v[52:55]
	v_mfma_f32_16x16x32_bf16 v[40:43], v[194:197], v[230:233], v[40:43]
	v_mfma_f32_16x16x32_bf16 v[36:39], v[202:205], v[230:233], v[36:39]
	v_mfma_f32_16x16x32_bf16 v[24:27], v[194:197], v[238:241], v[24:27]
	v_mfma_f32_16x16x32_bf16 v[20:23], v[202:205], v[238:241], v[20:23]
	v_mfma_f32_16x16x32_bf16 v[8:11], v[194:197], v[246:249], v[6:9]
	v_mfma_f32_16x16x32_bf16 v[4:7], v[202:205], v[246:249], v[2:5]
	s_setprio 0
	s_barrier
	s_add_i32 s86, s33, 2
	s_add_u32 s36, s36, 0x100
	s_addc_u32 s37, s37, 0
	s_cmp_gt_u32 s33, 29
	s_cbranch_scc1 .LBB0_884
	s_mov_b32 s33, s86
	s_cmp_lt_i32 s33, 16
	s_cbranch_scc1 .LBB0_876
	s_branch .LBB0_875

; #define PG8_STAGE(bufoff, gbase, voff) do { _Pragma("unroll") for (int _i = 0; _i < 2; ++_i) \
;         __builtin_amdgcn_global_load_lds((const unsigned*)((const char*)(gbase) + (voff)[_i]), (LAS unsigned*)(lds + (bufoff) + ldsw + _i * 8192), 16, 0, 0); } while (0)
; #define PG8_LDA(dst, b, h) do { _Pragma("unroll") for (int m = 0; m < 4; ++m) _Pragma("unroll") for (int k = 0; k < 2; ++k) dst[m][k] = *(const LAS bf16x8*)(lds + PG8_SA(b, h) + aoff + m * 2048 + k * 1024); } while (0)
; #define PG8_LDB(dst, b, h) do { _Pragma("unroll") for (int n = 0; n < 2; ++n) _Pragma("unroll") for (int k = 0; k < 2; ++k) dst[n][k] = *(const LAS bf16x8*)(lds + PG8_SB(b, h) + boff + n * 2048 + k * 1024); } while (0)
; #define PG8_MMA(ai, bj, At, Bt) do { __builtin_amdgcn_s_setprio(1); _Pragma("unroll") for (int m = 0; m < 4; ++m) _Pragma("unroll") for (int n = 0; n < 2; ++n) _Pragma("unroll") for (int k = 0; k < 2; ++k) \
;         acc[ai][bj][m][n] = __builtin_amdgcn_mfma_f32_16x16x32_bf16(Bt[n][k], At[m][k], acc[ai][bj][m][n], 0, 0, 0); __builtin_amdgcn_s_setprio(0); } while (0)
; #define PG8_WAIT_V(n) asm volatile("s_waitcnt vmcnt(" #n ")" ::: "memory")
; #define PG8_WAIT_L(n) asm volatile("s_waitcnt lgkmcnt(" #n ")" ::: "memory")
; template <class Epi>
; __device__ __forceinline__ void gemm_phase(LAS unsigned char* lds, const Gemm g, const StaticOrder& S, const Epi& E) {
;     ...
;         for (int t = 0; t < nt; t += 2) {
;             if constexpr (Epi::GATED) { if (t == 8 || t == 16) E.rescale(acc, cur, t == 8 ? 0 : 1, wr, wc, fr, fq); }
;             const bool last = (t == nt - 2);
;             const char* a1 = PG8_AP(cA, t + 1);
;             const char* a2 = last ? nA : PG8_AP(cA, t + 2); const char* b2 = last ? nB : cB + (size_t)(t + 2) * kstep;
;             const char* a3 = last ? nA + kstep : PG8_AP(cA, t + 3); const char* b3 = b2 + kstep;
;             PG8_LDB(B0, 0, 0); PG8_LDB(B1, 0, 1); PG8_SCHED; PG8_LDA(At, 0, 0); PG8_STAGE(PG8_SA(1, 1), a1 + hstepA, voffA);
;             PG8_WAIT_V(8); PG8_WAIT_L(0); PG8_BAR; PG8_MMA(0, 0, At, B0); PG8_MMA(0, 1, At, B1); PG8_BAR; PG8_SCHED;
;             PG8_LDA(At, 0, 1); PG8_STAGE(PG8_SB(0, 0), b2, voffB); PG8_STAGE(PG8_SB(0, 1), b2 + hstep, voffB); PG8_STAGE(PG8_SA(0, 0), a2, voffA);
;             PG8_WAIT_V(8); PG8_WAIT_L(0); PG8_BAR; PG8_MMA(1, 0, At, B0); PG8_MMA(1, 1, At, B1); PG8_BAR; PG8_SCHED;
.LBB0_955:
	s_add_u32 s12, s50, s54
	s_addc_u32 s13, s51, s55
	s_add_u32 s14, s12, 0x100
	s_addc_u32 s15, s13, 0
	s_add_u32 s86, s85, s54
	s_addc_u32 s87, s92, s55
	s_add_u32 s12, s12, 0x180
	s_addc_u32 s13, s13, 0
	s_add_i32 s90, 0, 0x10000
	s_add_i32 s94, 0, 0x14000
	v_add_u32_e32 v147, s90, v1
	ds_read_b128 v[148:151], v147
	ds_read_b128 v[152:155], v147 offset:1024
	ds_read_b128 v[156:159], v147 offset:2048
	ds_read_b128 v[160:163], v147 offset:3072
	v_add_u32_e32 v147, s94, v1
	ds_read_b128 v[186:189], v147
	ds_read_b128 v[190:193], v147 offset:1024
	ds_read_b128 v[194:197], v147 offset:2048
	ds_read_b128 v[198:201], v147 offset:3072
	s_cmpk_eq_i32 s54, 0xf00
	s_cselect_b32 s57, s81, s13
	s_cselect_b32 s56, s80, s12
	s_cselect_b32 s97, s43, s87
	s_cselect_b32 s96, s67, s86
	s_cselect_b32 s87, s45, s15
	s_cselect_b32 s86, s63, s14
	v_lshl_add_u64 v[212:213], v[142:143], 0, s[54:55]
	s_add_i32 m0, s25, 0xc000
	ds_read_b128 v[202:205], v146
	ds_read_b128 v[206:209], v146 offset:1024
	ds_read_b128 v[222:225], v146 offset:2048
	ds_read_b128 v[226:229], v146 offset:3072
	ds_read_b128 v[230:233], v146 offset:4096
	ds_read_b128 v[234:237], v146 offset:5120
	ds_read_b128 v[238:241], v146 offset:6144
	ds_read_b128 v[242:245], v146 offset:7168
	global_load_lds_dwordx4 v[212:213], off
	v_lshl_add_u64 v[212:213], v[144:145], 0, s[54:55]
	s_add_i32 m0, s25, 0xe000
	s_nop 0
	global_load_lds_dwordx4 v[212:213], off
	s_waitcnt vmcnt(8)
	s_waitcnt lgkmcnt(0)
	s_barrier
	s_setprio 1
	v_mfma_f32_16x16x32_bf16 v[126:129], v[148:151], v[202:205], v[126:129]
	v_mfma_f32_16x16x32_bf16 v[122:125], v[156:159], v[202:205], v[122:125]
	v_mfma_f32_16x16x32_bf16 v[118:121], v[148:151], v[222:225], v[118:121]
	v_mfma_f32_16x16x32_bf16 v[110:113], v[156:159], v[222:225], v[110:113]
	v_mfma_f32_16x16x32_bf16 v[102:105], v[148:151], v[230:233], v[102:105]
	v_mfma_f32_16x16x32_bf16 v[94:97], v[156:159], v[230:233], v[94:97]
	v_mfma_f32_16x16x32_bf16 v[86:89], v[148:151], v[238:241], v[86:89]
	v_mfma_f32_16x16x32_bf16 v[78:81], v[156:159], v[238:241], v[78:81]
	v_mfma_f32_16x16x32_bf16 v[126:129], v[152:155], v[206:209], v[126:129]
	v_mfma_f32_16x16x32_bf16 v[122:125], v[160:163], v[206:209], v[122:125]
	v_mfma_f32_16x16x32_bf16 v[118:121], v[152:155], v[226:229], v[118:121]
	v_mfma_f32_16x16x32_bf16 v[110:113], v[160:163], v[226:229], v[110:113]
	v_mfma_f32_16x16x32_bf16 v[102:105], v[152:155], v[234:237], v[102:105]
	v_mfma_f32_16x16x32_bf16 v[94:97], v[160:163], v[234:237], v[94:97]
	v_mfma_f32_16x16x32_bf16 v[86:89], v[152:155], v[242:245], v[86:89]
	v_mfma_f32_16x16x32_bf16 v[78:81], v[160:163], v[242:245], v[78:81]
	v_mfma_f32_16x16x32_bf16 v[114:117], v[186:189], v[202:205], v[114:117]
	v_mfma_f32_16x16x32_bf16 v[106:109], v[194:197], v[202:205], v[106:109]
	v_mfma_f32_16x16x32_bf16 v[98:101], v[186:189], v[222:225], v[98:101]
	v_mfma_f32_16x16x32_bf16 v[90:93], v[194:197], v[222:225], v[90:93]
	v_mfma_f32_16x16x32_bf16 v[82:85], v[186:189], v[230:233], v[82:85]
	v_mfma_f32_16x16x32_bf16 v[74:77], v[194:197], v[230:233], v[74:77]
	v_mfma_f32_16x16x32_bf16 v[70:73], v[186:189], v[238:241], v[70:73]
	v_mfma_f32_16x16x32_bf16 v[66:69], v[194:197], v[238:241], v[66:69]
	v_mfma_f32_16x16x32_bf16 v[114:117], v[190:193], v[206:209], v[114:117]
	v_mfma_f32_16x16x32_bf16 v[106:109], v[198:201], v[206:209], v[106:109]
	v_mfma_f32_16x16x32_bf16 v[98:101], v[190:193], v[226:229], v[98:101]
	v_mfma_f32_16x16x32_bf16 v[90:93], v[198:201], v[226:229], v[90:93]
	v_mfma_f32_16x16x32_bf16 v[82:85], v[190:193], v[234:237], v[82:85]
	v_mfma_f32_16x16x32_bf16 v[74:77], v[198:201], v[234:237], v[74:77]
	v_mfma_f32_16x16x32_bf16 v[70:73], v[190:193], v[242:245], v[70:73]
	v_mfma_f32_16x16x32_bf16 v[66:69], v[198:201], v[242:245], v[66:69]
	s_setprio 0
	s_barrier
	s_add_i32 s12, s90, s24
	v_lshl_add_u64 v[212:213], s[96:97], 0, v[134:135]
	s_mov_b32 m0, s12
	ds_read_b128 v[202:205], v146 offset:16384
	ds_read_b128 v[206:209], v146 offset:17408
	ds_read_b128 v[222:225], v146 offset:18432
	ds_read_b128 v[226:229], v146 offset:19456
	ds_read_b128 v[230:233], v146 offset:20480
	ds_read_b128 v[234:237], v146 offset:21504
	ds_read_b128 v[238:241], v146 offset:22528
	ds_read_b128 v[242:245], v146 offset:23552
	global_load_lds_dwordx4 v[212:213], off
	s_add_i32 m0, s12, 0x2000
	s_add_u32 s90, s96, 0x80000
	v_lshl_add_u64 v[246:247], s[96:97], 0, v[130:131]
	s_addc_u32 s91, s97, 0
	s_add_i32 s12, s94, s24
	global_load_lds_dwordx4 v[246:247], off
	v_lshl_add_u64 v[248:249], s[90:91], 0, v[134:135]
	s_mov_b32 m0, s12
	s_nop 0
	global_load_lds_dwordx4 v[248:249], off
	v_lshl_add_u64 v[248:249], s[90:91], 0, v[130:131]
	s_add_i32 m0, s12, 0x2000
	s_nop 0
	global_load_lds_dwordx4 v[248:249], off
	v_lshl_add_u64 v[248:249], s[86:87], 0, v[136:137]
	s_mov_b32 m0, s25
	s_nop 0
	global_load_lds_dwordx4 v[248:249], off
	v_lshl_add_u64 v[248:249], s[86:87], 0, v[132:133]
	s_mov_b32 m0, s26
	s_nop 0
	global_load_lds_dwordx4 v[248:249], off
	s_waitcnt vmcnt(8)
	s_waitcnt lgkmcnt(0)
	s_barrier
; #define PG8_STAGE(bufoff, gbase, voff) do { _Pragma("unroll") for (int _i = 0; _i < 2; ++_i) \
;         __builtin_amdgcn_global_load_lds((const unsigned*)((const char*)(gbase) + (voff)[_i]), (LAS unsigned*)(lds + (bufoff) + ldsw + _i * 8192), 16, 0, 0); } while (0)
; #define PG8_LDA(dst, b, h) do { _Pragma("unroll") for (int m = 0; m < 4; ++m) _Pragma("unroll") for (int k = 0; k < 2; ++k) dst[m][k] = *(const LAS bf16x8*)(lds + PG8_SA(b, h) + aoff + m * 2048 + k * 1024); } while (0)
; #define PG8_LDB(dst, b, h) do { _Pragma("unroll") for (int n = 0; n < 2; ++n) _Pragma("unroll") for (int k = 0; k < 2; ++k) dst[n][k] = *(const LAS bf16x8*)(lds + PG8_SB(b, h) + boff + n * 2048 + k * 1024); } while (0)
; #define PG8_MMA(ai, bj, At, Bt) do { __builtin_amdgcn_s_setprio(1); _Pragma("unroll") for (int m = 0; m < 4; ++m) _Pragma("unroll") for (int n = 0; n < 2; ++n) _Pragma("unroll") for (int k = 0; k < 2; ++k) \
;         acc[ai][bj][m][n] = __builtin_amdgcn_mfma_f32_16x16x32_bf16(Bt[n][k], At[m][k], acc[ai][bj][m][n], 0, 0, 0); __builtin_amdgcn_s_setprio(0); } while (0)
; #define PG8_WAIT_V(n) asm volatile("s_waitcnt vmcnt(" #n ")" ::: "memory")
; #define PG8_WAIT_L(n) asm volatile("s_waitcnt lgkmcnt(" #n ")" ::: "memory")
; #define PG8_BAR __builtin_amdgcn_s_barrier()
; #define PG8_SCHED __builtin_amdgcn_sched_barrier(0)
; template <class Epi>
; __device__ __forceinline__ void gemm_phase(LAS unsigned char* lds, const Gemm g, const StaticOrder& S, const Epi& E) {
;     ...
;             PG8_WAIT_V(8); PG8_WAIT_L(0); PG8_BAR; PG8_MMA(1, 0, At, B0); PG8_MMA(1, 1, At, B1); PG8_BAR; PG8_SCHED;
;             PG8_LDB(B0, 1, 0); PG8_LDB(B1, 1, 1); PG8_SCHED; PG8_LDA(At, 1, 0); PG8_STAGE(PG8_SA(0, 1), a2 + hstepA, voffA);
;             PG8_WAIT_V(8); PG8_WAIT_L(0); PG8_BAR; PG8_MMA(0, 0, At, B0); PG8_MMA(0, 1, At, B1); PG8_BAR; PG8_SCHED;
	s_setprio 1
	v_mfma_f32_16x16x32_bf16 v[62:65], v[148:151], v[202:205], v[62:65]
	v_mfma_f32_16x16x32_bf16 v[58:61], v[156:159], v[202:205], v[58:61]
	v_mfma_f32_16x16x32_bf16 v[54:57], v[148:151], v[222:225], v[54:57]
	v_mfma_f32_16x16x32_bf16 v[46:49], v[156:159], v[222:225], v[46:49]
	v_mfma_f32_16x16x32_bf16 v[38:41], v[148:151], v[230:233], v[38:41]
	v_mfma_f32_16x16x32_bf16 v[30:33], v[156:159], v[230:233], v[30:33]
	v_mfma_f32_16x16x32_bf16 v[22:25], v[148:151], v[238:241], v[22:25]
	v_mfma_f32_16x16x32_bf16 v[14:17], v[156:159], v[238:241], v[14:17]
	v_mfma_f32_16x16x32_bf16 v[62:65], v[152:155], v[206:209], v[62:65]
	v_mfma_f32_16x16x32_bf16 v[58:61], v[160:163], v[206:209], v[58:61]
	v_mfma_f32_16x16x32_bf16 v[54:57], v[152:155], v[226:229], v[54:57]
	v_mfma_f32_16x16x32_bf16 v[46:49], v[160:163], v[226:229], v[46:49]
	v_mfma_f32_16x16x32_bf16 v[38:41], v[152:155], v[234:237], v[38:41]
	v_mfma_f32_16x16x32_bf16 v[30:33], v[160:163], v[234:237], v[30:33]
	v_mfma_f32_16x16x32_bf16 v[22:25], v[152:155], v[242:245], v[22:25]
	v_mfma_f32_16x16x32_bf16 v[14:17], v[160:163], v[242:245], v[14:17]
	v_mfma_f32_16x16x32_bf16 v[50:53], v[186:189], v[202:205], v[50:53]
	v_mfma_f32_16x16x32_bf16 v[42:45], v[194:197], v[202:205], v[42:45]
	v_mfma_f32_16x16x32_bf16 v[34:37], v[186:189], v[222:225], v[34:37]
	v_mfma_f32_16x16x32_bf16 v[26:29], v[194:197], v[222:225], v[26:29]
	v_mfma_f32_16x16x32_bf16 v[18:21], v[186:189], v[230:233], v[18:21]
	v_mfma_f32_16x16x32_bf16 v[10:13], v[194:197], v[230:233], v[10:13]
	v_mfma_f32_16x16x32_bf16 v[6:9], v[186:189], v[238:241], v[6:9]
	v_mfma_f32_16x16x32_bf16 v[2:5], v[194:197], v[238:241], v[2:5]
	v_mfma_f32_16x16x32_bf16 v[50:53], v[190:193], v[206:209], v[50:53]
	v_mfma_f32_16x16x32_bf16 v[42:45], v[198:201], v[206:209], v[42:45]
	v_mfma_f32_16x16x32_bf16 v[34:37], v[190:193], v[226:229], v[34:37]
	v_mfma_f32_16x16x32_bf16 v[26:29], v[198:201], v[226:229], v[26:29]
	v_mfma_f32_16x16x32_bf16 v[18:21], v[190:193], v[234:237], v[18:21]
	v_mfma_f32_16x16x32_bf16 v[10:13], v[198:201], v[234:237], v[10:13]
	v_mfma_f32_16x16x32_bf16 v[6:9], v[190:193], v[242:245], v[6:9]
	v_mfma_f32_16x16x32_bf16 v[2:5], v[198:201], v[242:245], v[2:5]
	s_setprio 0
	s_barrier
	s_add_i32 s12, 0, 0x18000
	v_add_u32_e32 v147, s12, v1
	s_add_i32 s13, 0, 0x1c000
	ds_read_b128 v[148:151], v147
	ds_read_b128 v[152:155], v147 offset:1024
	ds_read_b128 v[156:159], v147 offset:2048
	ds_read_b128 v[160:163], v147 offset:3072
	v_add_u32_e32 v147, s13, v1
	ds_read_b128 v[186:189], v147
	ds_read_b128 v[190:193], v147 offset:1024
	ds_read_b128 v[194:197], v147 offset:2048
	ds_read_b128 v[198:201], v147 offset:3072
	s_add_u32 s86, s86, 0x80000
	s_addc_u32 s87, s87, 0
	s_mov_b32 m0, s27
	v_lshl_add_u64 v[248:249], s[86:87], 0, v[136:137]
	ds_read_b128 v[202:205], v146 offset:32768
	ds_read_b128 v[206:209], v146 offset:33792
	ds_read_b128 v[222:225], v146 offset:34816
	ds_read_b128 v[226:229], v146 offset:35840
	ds_read_b128 v[230:233], v146 offset:36864
	ds_read_b128 v[234:237], v146 offset:37888
	ds_read_b128 v[238:241], v146 offset:38912
	ds_read_b128 v[242:245], v146 offset:39936
	global_load_lds_dwordx4 v[248:249], off
	v_lshl_add_u64 v[248:249], s[86:87], 0, v[132:133]
	s_mov_b32 m0, s28
	s_nop 0
	global_load_lds_dwordx4 v[248:249], off
	s_waitcnt vmcnt(8)
	s_waitcnt lgkmcnt(0)
	s_barrier
	s_setprio 1
	v_mfma_f32_16x16x32_bf16 v[126:129], v[148:151], v[202:205], v[126:129]
	v_mfma_f32_16x16x32_bf16 v[122:125], v[156:159], v[202:205], v[122:125]
	v_mfma_f32_16x16x32_bf16 v[118:121], v[148:151], v[222:225], v[118:121]
	v_mfma_f32_16x16x32_bf16 v[110:113], v[156:159], v[222:225], v[110:113]
	v_mfma_f32_16x16x32_bf16 v[102:105], v[148:151], v[230:233], v[102:105]
	v_mfma_f32_16x16x32_bf16 v[94:97], v[156:159], v[230:233], v[94:97]
	v_mfma_f32_16x16x32_bf16 v[86:89], v[148:151], v[238:241], v[86:89]
	v_mfma_f32_16x16x32_bf16 v[78:81], v[156:159], v[238:241], v[78:81]
	v_mfma_f32_16x16x32_bf16 v[126:129], v[152:155], v[206:209], v[126:129]
	v_mfma_f32_16x16x32_bf16 v[122:125], v[160:163], v[206:209], v[122:125]
	v_mfma_f32_16x16x32_bf16 v[118:121], v[152:155], v[226:229], v[118:121]
	v_mfma_f32_16x16x32_bf16 v[110:113], v[160:163], v[226:229], v[110:113]
	v_mfma_f32_16x16x32_bf16 v[102:105], v[152:155], v[234:237], v[102:105]
	v_mfma_f32_16x16x32_bf16 v[94:97], v[160:163], v[234:237], v[94:97]
	v_mfma_f32_16x16x32_bf16 v[86:89], v[152:155], v[242:245], v[86:89]
	v_mfma_f32_16x16x32_bf16 v[78:81], v[160:163], v[242:245], v[78:81]
	v_mfma_f32_16x16x32_bf16 v[114:117], v[186:189], v[202:205], v[114:117]
	v_mfma_f32_16x16x32_bf16 v[106:109], v[194:197], v[202:205], v[106:109]
	v_mfma_f32_16x16x32_bf16 v[98:101], v[186:189], v[222:225], v[98:101]
	v_mfma_f32_16x16x32_bf16 v[90:93], v[194:197], v[222:225], v[90:93]
	v_mfma_f32_16x16x32_bf16 v[82:85], v[186:189], v[230:233], v[82:85]
	v_mfma_f32_16x16x32_bf16 v[74:77], v[194:197], v[230:233], v[74:77]
	v_mfma_f32_16x16x32_bf16 v[70:73], v[186:189], v[238:241], v[70:73]
	v_mfma_f32_16x16x32_bf16 v[66:69], v[194:197], v[238:241], v[66:69]
	v_mfma_f32_16x16x32_bf16 v[114:117], v[190:193], v[206:209], v[114:117]
	v_mfma_f32_16x16x32_bf16 v[106:109], v[198:201], v[206:209], v[106:109]
	v_mfma_f32_16x16x32_bf16 v[98:101], v[190:193], v[226:229], v[98:101]
	v_mfma_f32_16x16x32_bf16 v[90:93], v[198:201], v[226:229], v[90:93]
	v_mfma_f32_16x16x32_bf16 v[82:85], v[190:193], v[234:237], v[82:85]
	v_mfma_f32_16x16x32_bf16 v[74:77], v[198:201], v[234:237], v[74:77]
	v_mfma_f32_16x16x32_bf16 v[70:73], v[190:193], v[242:245], v[70:73]
	v_mfma_f32_16x16x32_bf16 v[66:69], v[198:201], v[242:245], v[66:69]
	s_setprio 0
	s_barrier
; #define PG8_STAGE(bufoff, gbase, voff) do { _Pragma("unroll") for (int _i = 0; _i < 2; ++_i) \
;         __builtin_amdgcn_global_load_lds((const unsigned*)((const char*)(gbase) + (voff)[_i]), (LAS unsigned*)(lds + (bufoff) + ldsw + _i * 8192), 16, 0, 0); } while (0)
; #define PG8_LDA(dst, b, h) do { _Pragma("unroll") for (int m = 0; m < 4; ++m) _Pragma("unroll") for (int k = 0; k < 2; ++k) dst[m][k] = *(const LAS bf16x8*)(lds + PG8_SA(b, h) + aoff + m * 2048 + k * 1024); } while (0)
; #define PG8_MMA(ai, bj, At, Bt) do { __builtin_amdgcn_s_setprio(1); _Pragma("unroll") for (int m = 0; m < 4; ++m) _Pragma("unroll") for (int n = 0; n < 2; ++n) _Pragma("unroll") for (int k = 0; k < 2; ++k) \
;         acc[ai][bj][m][n] = __builtin_amdgcn_mfma_f32_16x16x32_bf16(Bt[n][k], At[m][k], acc[ai][bj][m][n], 0, 0, 0); __builtin_amdgcn_s_setprio(0); } while (0)
; #define PG8_WAIT_V(n) asm volatile("s_waitcnt vmcnt(" #n ")" ::: "memory")
; #define PG8_WAIT_L(n) asm volatile("s_waitcnt lgkmcnt(" #n ")" ::: "memory")
; #define PG8_BAR __builtin_amdgcn_s_barrier()
; #define PG8_SCHED __builtin_amdgcn_sched_barrier(0)
; template <class Epi>
; __device__ __forceinline__ void gemm_phase(LAS unsigned char* lds, const Gemm g, const StaticOrder& S, const Epi& E) {
;     ...
;             PG8_LDA(At, 1, 1); PG8_STAGE(PG8_SB(1, 0), b3, voffB); PG8_STAGE(PG8_SB(1, 1), b3 + hstep, voffB); PG8_STAGE(PG8_SA(1, 0), a3, voffA);
;             PG8_WAIT_V(8); PG8_WAIT_L(0); PG8_BAR; PG8_MMA(1, 0, At, B0); PG8_MMA(1, 1, At, B1); PG8_BAR; PG8_SCHED;
;         }
;         if (wr == 0) PG8_BAR;
	s_add_i32 s12, s12, s24
	v_lshl_add_u64 v[212:213], v[212:213], 0, s[6:7]
	s_mov_b32 m0, s12
	ds_read_b128 v[202:205], v146 offset:49152
	ds_read_b128 v[206:209], v146 offset:50176
	ds_read_b128 v[222:225], v146 offset:51200
	ds_read_b128 v[226:229], v146 offset:52224
	ds_read_b128 v[230:233], v146 offset:53248
	ds_read_b128 v[234:237], v146 offset:54272
	ds_read_b128 v[238:241], v146 offset:55296
	ds_read_b128 v[242:245], v146 offset:56320
	global_load_lds_dwordx4 v[212:213], off
	s_add_i32 m0, s12, 0x2000
	s_add_u32 s86, s96, 0x80080
	v_lshl_add_u64 v[212:213], v[246:247], 0, s[6:7]
	s_addc_u32 s87, s97, 0
	s_add_i32 s12, s13, s24
	global_load_lds_dwordx4 v[212:213], off
	v_lshl_add_u64 v[212:213], s[86:87], 0, v[134:135]
	s_mov_b32 m0, s12
	s_nop 0
	global_load_lds_dwordx4 v[212:213], off
	v_lshl_add_u64 v[212:213], s[86:87], 0, v[130:131]
	s_add_i32 m0, s12, 0x2000
	s_nop 0
	global_load_lds_dwordx4 v[212:213], off
	v_lshl_add_u64 v[212:213], s[56:57], 0, v[136:137]
	s_mov_b32 m0, s29
	s_nop 0
	global_load_lds_dwordx4 v[212:213], off
	v_lshl_add_u64 v[212:213], s[56:57], 0, v[132:133]
	s_mov_b32 m0, s33
	s_nop 0
	global_load_lds_dwordx4 v[212:213], off
	s_waitcnt vmcnt(8)
	s_waitcnt lgkmcnt(0)
	s_barrier
	s_setprio 1
	v_mfma_f32_16x16x32_bf16 v[62:65], v[148:151], v[202:205], v[62:65]
	v_mfma_f32_16x16x32_bf16 v[58:61], v[156:159], v[202:205], v[58:61]
	v_mfma_f32_16x16x32_bf16 v[54:57], v[148:151], v[222:225], v[54:57]
	v_mfma_f32_16x16x32_bf16 v[46:49], v[156:159], v[222:225], v[46:49]
	v_mfma_f32_16x16x32_bf16 v[38:41], v[148:151], v[230:233], v[38:41]
	v_mfma_f32_16x16x32_bf16 v[30:33], v[156:159], v[230:233], v[30:33]
	v_mfma_f32_16x16x32_bf16 v[22:25], v[148:151], v[238:241], v[22:25]
	v_mfma_f32_16x16x32_bf16 v[14:17], v[156:159], v[238:241], v[14:17]
	v_mfma_f32_16x16x32_bf16 v[62:65], v[152:155], v[206:209], v[62:65]
	v_mfma_f32_16x16x32_bf16 v[58:61], v[160:163], v[206:209], v[58:61]
	v_mfma_f32_16x16x32_bf16 v[54:57], v[152:155], v[226:229], v[54:57]
	v_mfma_f32_16x16x32_bf16 v[46:49], v[160:163], v[226:229], v[46:49]
	v_mfma_f32_16x16x32_bf16 v[38:41], v[152:155], v[234:237], v[38:41]
	v_mfma_f32_16x16x32_bf16 v[30:33], v[160:163], v[234:237], v[30:33]
	v_mfma_f32_16x16x32_bf16 v[22:25], v[152:155], v[242:245], v[22:25]
	v_mfma_f32_16x16x32_bf16 v[14:17], v[160:163], v[242:245], v[14:17]
	v_mfma_f32_16x16x32_bf16 v[50:53], v[186:189], v[202:205], v[50:53]
	v_mfma_f32_16x16x32_bf16 v[42:45], v[194:197], v[202:205], v[42:45]
	v_mfma_f32_16x16x32_bf16 v[34:37], v[186:189], v[222:225], v[34:37]
	v_mfma_f32_16x16x32_bf16 v[26:29], v[194:197], v[222:225], v[26:29]
	v_mfma_f32_16x16x32_bf16 v[18:21], v[186:189], v[230:233], v[18:21]
	v_mfma_f32_16x16x32_bf16 v[10:13], v[194:197], v[230:233], v[10:13]
	v_mfma_f32_16x16x32_bf16 v[6:9], v[186:189], v[238:241], v[6:9]
	v_mfma_f32_16x16x32_bf16 v[2:5], v[194:197], v[238:241], v[2:5]
	v_mfma_f32_16x16x32_bf16 v[50:53], v[190:193], v[206:209], v[50:53]
	v_mfma_f32_16x16x32_bf16 v[42:45], v[198:201], v[206:209], v[42:45]
	v_mfma_f32_16x16x32_bf16 v[34:37], v[190:193], v[226:229], v[34:37]
	v_mfma_f32_16x16x32_bf16 v[26:29], v[198:201], v[226:229], v[26:29]
	v_mfma_f32_16x16x32_bf16 v[18:21], v[190:193], v[234:237], v[18:21]
	v_mfma_f32_16x16x32_bf16 v[10:13], v[198:201], v[234:237], v[10:13]
	v_mfma_f32_16x16x32_bf16 v[6:9], v[190:193], v[242:245], v[6:9]
	v_mfma_f32_16x16x32_bf16 v[2:5], v[198:201], v[242:245], v[2:5]
	s_setprio 0
	s_barrier
	s_add_i32 s93, s93, 2
	s_add_u32 s54, s54, 0x100
	s_addc_u32 s55, s55, 0
	s_cmp_gt_u32 s93, 29
	s_cbranch_scc0 .LBB0_955
	s_and_b64 vcc, exec, s[36:37]
	s_cbranch_vccz .LBB0_958
	s_barrier

; #define PG8_STAGE(bufoff, gbase, voff) do { _Pragma("unroll") for (int _i = 0; _i < 2; ++_i) \
;         __builtin_amdgcn_global_load_lds((const unsigned*)((const char*)(gbase) + (voff)[_i]), (LAS unsigned*)(lds + (bufoff) + ldsw + _i * 8192), 16, 0, 0); } while (0)
; #define PG8_LDA(dst, b, h) do { _Pragma("unroll") for (int m = 0; m < 4; ++m) _Pragma("unroll") for (int k = 0; k < 2; ++k) dst[m][k] = *(const LAS bf16x8*)(lds + PG8_SA(b, h) + aoff + m * 2048 + k * 1024); } while (0)
; #define PG8_LDB(dst, b, h) do { _Pragma("unroll") for (int n = 0; n < 2; ++n) _Pragma("unroll") for (int k = 0; k < 2; ++k) dst[n][k] = *(const LAS bf16x8*)(lds + PG8_SB(b, h) + boff + n * 2048 + k * 1024); } while (0)
; #define PG8_MMA(ai, bj, At, Bt) do { __builtin_amdgcn_s_setprio(1); _Pragma("unroll") for (int m = 0; m < 4; ++m) _Pragma("unroll") for (int n = 0; n < 2; ++n) _Pragma("unroll") for (int k = 0; k < 2; ++k) \
;         acc[ai][bj][m][n] = __builtin_amdgcn_mfma_f32_16x16x32_bf16(Bt[n][k], At[m][k], acc[ai][bj][m][n], 0, 0, 0); __builtin_amdgcn_s_setprio(0); } while (0)
; #define PG8_WAIT_V(n) asm volatile("s_waitcnt vmcnt(" #n ")" ::: "memory")
; #define PG8_WAIT_L(n) asm volatile("s_waitcnt lgkmcnt(" #n ")" ::: "memory")
; template <class Epi>
; __device__ __forceinline__ void gemm_phase(LAS unsigned char* lds, const Gemm g, const StaticOrder& S, const Epi& E) {
;     ...
;         for (int t = 0; t < nt; t += 2) {
;             if constexpr (Epi::GATED) { if (t == 8 || t == 16) E.rescale(acc, cur, t == 8 ? 0 : 1, wr, wc, fr, fq); }
;             const bool last = (t == nt - 2);
;             const char* a1 = PG8_AP(cA, t + 1);
;             const char* a2 = last ? nA : PG8_AP(cA, t + 2); const char* b2 = last ? nB : cB + (size_t)(t + 2) * kstep;
;             const char* a3 = last ? nA + kstep : PG8_AP(cA, t + 3); const char* b3 = b2 + kstep;
;             PG8_LDB(B0, 0, 0); PG8_LDB(B1, 0, 1); PG8_SCHED; PG8_LDA(At, 0, 0); PG8_STAGE(PG8_SA(1, 1), a1 + hstepA, voffA);
;             PG8_WAIT_V(8); PG8_WAIT_L(0); PG8_BAR; PG8_MMA(0, 0, At, B0); PG8_MMA(0, 1, At, B1); PG8_BAR; PG8_SCHED;
;             PG8_LDA(At, 0, 1); PG8_STAGE(PG8_SB(0, 0), b2, voffB); PG8_STAGE(PG8_SB(0, 1), b2 + hstep, voffB); PG8_STAGE(PG8_SA(0, 0), a2, voffA);
;             PG8_WAIT_V(8); PG8_WAIT_L(0); PG8_BAR; PG8_MMA(1, 0, At, B0); PG8_MMA(1, 1, At, B1); PG8_BAR; PG8_SCHED;
.LBB0_1090:
	s_add_u32 s12, s48, s50
	s_addc_u32 s13, s49, s51
	s_add_u32 s14, s12, 0x100
	s_addc_u32 s15, s13, 0
	s_add_u32 s56, s96, s50
	s_addc_u32 s57, s97, s51
	s_add_u32 s12, s12, 0x180
	s_addc_u32 s13, s13, 0
	s_add_i32 s90, 0, 0x10000
	s_add_i32 vcc_hi, 0, 0x14000
	v_add_u32_e32 v147, s90, v1
	ds_read_b128 v[148:151], v147
	ds_read_b128 v[152:155], v147 offset:1024
	ds_read_b128 v[156:159], v147 offset:2048
	ds_read_b128 v[160:163], v147 offset:3072
	v_add_u32_e32 v147, vcc_hi, v1
	ds_read_b128 v[186:189], v147
	ds_read_b128 v[190:193], v147 offset:1024
	ds_read_b128 v[194:197], v147 offset:2048
	ds_read_b128 v[198:201], v147 offset:3072
	s_cmpk_eq_i32 s50, 0xf00
	s_cselect_b32 s55, s94, s13
	s_cselect_b32 s54, s93, s12
	s_cselect_b32 s57, s37, s57
	s_cselect_b32 s56, s92, s56
	s_cselect_b32 s87, s43, s15
	s_cselect_b32 s86, s85, s14
	v_lshl_add_u64 v[212:213], v[142:143], 0, s[50:51]
	s_add_i32 m0, s25, 0xc000
	ds_read_b128 v[202:205], v146
	ds_read_b128 v[206:209], v146 offset:1024
	ds_read_b128 v[222:225], v146 offset:2048
	ds_read_b128 v[226:229], v146 offset:3072
	ds_read_b128 v[230:233], v146 offset:4096
	ds_read_b128 v[234:237], v146 offset:5120
	ds_read_b128 v[238:241], v146 offset:6144
	ds_read_b128 v[242:245], v146 offset:7168
	global_load_lds_dwordx4 v[212:213], off
	v_lshl_add_u64 v[212:213], v[144:145], 0, s[50:51]
	s_add_i32 m0, s25, 0xe000
	s_nop 0
	global_load_lds_dwordx4 v[212:213], off
	s_waitcnt vmcnt(8)
	s_waitcnt lgkmcnt(0)
	s_barrier
	s_setprio 1
	v_mfma_f32_16x16x32_bf16 v[126:129], v[148:151], v[202:205], v[126:129]
	v_mfma_f32_16x16x32_bf16 v[122:125], v[156:159], v[202:205], v[122:125]
	v_mfma_f32_16x16x32_bf16 v[110:113], v[148:151], v[222:225], v[110:113]
	v_mfma_f32_16x16x32_bf16 v[106:109], v[156:159], v[222:225], v[106:109]
	v_mfma_f32_16x16x32_bf16 v[94:97], v[148:151], v[230:233], v[94:97]
	v_mfma_f32_16x16x32_bf16 v[90:93], v[156:159], v[230:233], v[90:93]
	v_mfma_f32_16x16x32_bf16 v[78:81], v[148:151], v[238:241], v[78:81]
	v_mfma_f32_16x16x32_bf16 v[74:77], v[156:159], v[238:241], v[74:77]
	v_mfma_f32_16x16x32_bf16 v[126:129], v[152:155], v[206:209], v[126:129]
	v_mfma_f32_16x16x32_bf16 v[122:125], v[160:163], v[206:209], v[122:125]
	v_mfma_f32_16x16x32_bf16 v[110:113], v[152:155], v[226:229], v[110:113]
	v_mfma_f32_16x16x32_bf16 v[106:109], v[160:163], v[226:229], v[106:109]
	v_mfma_f32_16x16x32_bf16 v[94:97], v[152:155], v[234:237], v[94:97]
	v_mfma_f32_16x16x32_bf16 v[90:93], v[160:163], v[234:237], v[90:93]
	v_mfma_f32_16x16x32_bf16 v[78:81], v[152:155], v[242:245], v[78:81]
	v_mfma_f32_16x16x32_bf16 v[74:77], v[160:163], v[242:245], v[74:77]
	v_mfma_f32_16x16x32_bf16 v[118:121], v[186:189], v[202:205], v[118:121]
	v_mfma_f32_16x16x32_bf16 v[114:117], v[194:197], v[202:205], v[114:117]
	v_mfma_f32_16x16x32_bf16 v[102:105], v[186:189], v[222:225], v[102:105]
	v_mfma_f32_16x16x32_bf16 v[98:101], v[194:197], v[222:225], v[98:101]
	v_mfma_f32_16x16x32_bf16 v[86:89], v[186:189], v[230:233], v[86:89]
	v_mfma_f32_16x16x32_bf16 v[82:85], v[194:197], v[230:233], v[82:85]
	v_mfma_f32_16x16x32_bf16 v[70:73], v[186:189], v[238:241], v[70:73]
	v_mfma_f32_16x16x32_bf16 v[66:69], v[194:197], v[238:241], v[66:69]
	v_mfma_f32_16x16x32_bf16 v[118:121], v[190:193], v[206:209], v[118:121]
	v_mfma_f32_16x16x32_bf16 v[114:117], v[198:201], v[206:209], v[114:117]
	v_mfma_f32_16x16x32_bf16 v[102:105], v[190:193], v[226:229], v[102:105]
	v_mfma_f32_16x16x32_bf16 v[98:101], v[198:201], v[226:229], v[98:101]
	v_mfma_f32_16x16x32_bf16 v[86:89], v[190:193], v[234:237], v[86:89]
	v_mfma_f32_16x16x32_bf16 v[82:85], v[198:201], v[234:237], v[82:85]
	v_mfma_f32_16x16x32_bf16 v[70:73], v[190:193], v[242:245], v[70:73]
	v_mfma_f32_16x16x32_bf16 v[66:69], v[198:201], v[242:245], v[66:69]
	s_setprio 0
	s_barrier
	s_add_i32 s12, s90, s24
	v_lshl_add_u64 v[212:213], s[56:57], 0, v[134:135]
	s_mov_b32 m0, s12
	ds_read_b128 v[202:205], v146 offset:16384
	ds_read_b128 v[206:209], v146 offset:17408
	ds_read_b128 v[222:225], v146 offset:18432
	ds_read_b128 v[226:229], v146 offset:19456
	ds_read_b128 v[230:233], v146 offset:20480
	ds_read_b128 v[234:237], v146 offset:21504
	ds_read_b128 v[238:241], v146 offset:22528
	ds_read_b128 v[242:245], v146 offset:23552
	global_load_lds_dwordx4 v[212:213], off
	s_add_i32 m0, s12, 0x2000
	s_add_u32 s90, s56, 0x80000
	v_lshl_add_u64 v[246:247], s[56:57], 0, v[130:131]
	s_addc_u32 s91, s57, 0
	s_add_i32 s12, vcc_hi, s24
	global_load_lds_dwordx4 v[246:247], off
	v_lshl_add_u64 v[248:249], s[90:91], 0, v[134:135]
	s_mov_b32 m0, s12
	s_nop 0
	global_load_lds_dwordx4 v[248:249], off
	v_lshl_add_u64 v[248:249], s[90:91], 0, v[130:131]
	s_add_i32 m0, s12, 0x2000
	s_nop 0
	global_load_lds_dwordx4 v[248:249], off
	v_lshl_add_u64 v[248:249], s[86:87], 0, v[136:137]
	s_mov_b32 m0, s25
	s_nop 0
	global_load_lds_dwordx4 v[248:249], off
	v_lshl_add_u64 v[248:249], s[86:87], 0, v[132:133]
	s_mov_b32 m0, s33
	s_nop 0
	global_load_lds_dwordx4 v[248:249], off
	s_waitcnt vmcnt(8)
	s_waitcnt lgkmcnt(0)
	s_barrier
; #define PG8_STAGE(bufoff, gbase, voff) do { _Pragma("unroll") for (int _i = 0; _i < 2; ++_i) \
;         __builtin_amdgcn_global_load_lds((const unsigned*)((const char*)(gbase) + (voff)[_i]), (LAS unsigned*)(lds + (bufoff) + ldsw + _i * 8192), 16, 0, 0); } while (0)
; #define PG8_LDA(dst, b, h) do { _Pragma("unroll") for (int m = 0; m < 4; ++m) _Pragma("unroll") for (int k = 0; k < 2; ++k) dst[m][k] = *(const LAS bf16x8*)(lds + PG8_SA(b, h) + aoff + m * 2048 + k * 1024); } while (0)
; #define PG8_LDB(dst, b, h) do { _Pragma("unroll") for (int n = 0; n < 2; ++n) _Pragma("unroll") for (int k = 0; k < 2; ++k) dst[n][k] = *(const LAS bf16x8*)(lds + PG8_SB(b, h) + boff + n * 2048 + k * 1024); } while (0)
; #define PG8_MMA(ai, bj, At, Bt) do { __builtin_amdgcn_s_setprio(1); _Pragma("unroll") for (int m = 0; m < 4; ++m) _Pragma("unroll") for (int n = 0; n < 2; ++n) _Pragma("unroll") for (int k = 0; k < 2; ++k) \
;         acc[ai][bj][m][n] = __builtin_amdgcn_mfma_f32_16x16x32_bf16(Bt[n][k], At[m][k], acc[ai][bj][m][n], 0, 0, 0); __builtin_amdgcn_s_setprio(0); } while (0)
; #define PG8_WAIT_V(n) asm volatile("s_waitcnt vmcnt(" #n ")" ::: "memory")
; #define PG8_WAIT_L(n) asm volatile("s_waitcnt lgkmcnt(" #n ")" ::: "memory")
; #define PG8_BAR __builtin_amdgcn_s_barrier()
; #define PG8_SCHED __builtin_amdgcn_sched_barrier(0)
; template <class Epi>
; __device__ __forceinline__ void gemm_phase(LAS unsigned char* lds, const Gemm g, const StaticOrder& S, const Epi& E) {
;     ...
;             PG8_WAIT_V(8); PG8_WAIT_L(0); PG8_BAR; PG8_MMA(1, 0, At, B0); PG8_MMA(1, 1, At, B1); PG8_BAR; PG8_SCHED;
;             PG8_LDB(B0, 1, 0); PG8_LDB(B1, 1, 1); PG8_SCHED; PG8_LDA(At, 1, 0); PG8_STAGE(PG8_SA(0, 1), a2 + hstepA, voffA);
;             PG8_WAIT_V(8); PG8_WAIT_L(0); PG8_BAR; PG8_MMA(0, 0, At, B0); PG8_MMA(0, 1, At, B1); PG8_BAR; PG8_SCHED;
	s_setprio 1
	v_mfma_f32_16x16x32_bf16 v[62:65], v[148:151], v[202:205], v[62:65]
	v_mfma_f32_16x16x32_bf16 v[58:61], v[156:159], v[202:205], v[58:61]
	v_mfma_f32_16x16x32_bf16 v[46:49], v[148:151], v[222:225], v[46:49]
	v_mfma_f32_16x16x32_bf16 v[42:45], v[156:159], v[222:225], v[42:45]
	v_mfma_f32_16x16x32_bf16 v[30:33], v[148:151], v[230:233], v[30:33]
	v_mfma_f32_16x16x32_bf16 v[26:29], v[156:159], v[230:233], v[26:29]
	v_mfma_f32_16x16x32_bf16 v[14:17], v[148:151], v[238:241], v[14:17]
	v_mfma_f32_16x16x32_bf16 v[10:13], v[156:159], v[238:241], v[10:13]
	v_mfma_f32_16x16x32_bf16 v[62:65], v[152:155], v[206:209], v[62:65]
	v_mfma_f32_16x16x32_bf16 v[58:61], v[160:163], v[206:209], v[58:61]
	v_mfma_f32_16x16x32_bf16 v[46:49], v[152:155], v[226:229], v[46:49]
	v_mfma_f32_16x16x32_bf16 v[42:45], v[160:163], v[226:229], v[42:45]
	v_mfma_f32_16x16x32_bf16 v[30:33], v[152:155], v[234:237], v[30:33]
	v_mfma_f32_16x16x32_bf16 v[26:29], v[160:163], v[234:237], v[26:29]
	v_mfma_f32_16x16x32_bf16 v[14:17], v[152:155], v[242:245], v[14:17]
	v_mfma_f32_16x16x32_bf16 v[10:13], v[160:163], v[242:245], v[10:13]
	v_mfma_f32_16x16x32_bf16 v[54:57], v[186:189], v[202:205], v[54:57]
	v_mfma_f32_16x16x32_bf16 v[50:53], v[194:197], v[202:205], v[50:53]
	v_mfma_f32_16x16x32_bf16 v[38:41], v[186:189], v[222:225], v[38:41]
	v_mfma_f32_16x16x32_bf16 v[34:37], v[194:197], v[222:225], v[34:37]
	v_mfma_f32_16x16x32_bf16 v[22:25], v[186:189], v[230:233], v[22:25]
	v_mfma_f32_16x16x32_bf16 v[18:21], v[194:197], v[230:233], v[18:21]
	v_mfma_f32_16x16x32_bf16 v[6:9], v[186:189], v[238:241], v[6:9]
	v_mfma_f32_16x16x32_bf16 v[2:5], v[194:197], v[238:241], v[2:5]
	v_mfma_f32_16x16x32_bf16 v[54:57], v[190:193], v[206:209], v[54:57]
	v_mfma_f32_16x16x32_bf16 v[50:53], v[198:201], v[206:209], v[50:53]
	v_mfma_f32_16x16x32_bf16 v[38:41], v[190:193], v[226:229], v[38:41]
	v_mfma_f32_16x16x32_bf16 v[34:37], v[198:201], v[226:229], v[34:37]
	v_mfma_f32_16x16x32_bf16 v[22:25], v[190:193], v[234:237], v[22:25]
	v_mfma_f32_16x16x32_bf16 v[18:21], v[198:201], v[234:237], v[18:21]
	v_mfma_f32_16x16x32_bf16 v[6:9], v[190:193], v[242:245], v[6:9]
	v_mfma_f32_16x16x32_bf16 v[2:5], v[198:201], v[242:245], v[2:5]
	s_setprio 0
	s_barrier
	s_add_i32 s12, 0, 0x18000
	v_add_u32_e32 v147, s12, v1
	s_add_i32 s13, 0, 0x1c000
	ds_read_b128 v[148:151], v147
	ds_read_b128 v[152:155], v147 offset:1024
	ds_read_b128 v[156:159], v147 offset:2048
	ds_read_b128 v[160:163], v147 offset:3072
	v_add_u32_e32 v147, s13, v1
	ds_read_b128 v[186:189], v147
	ds_read_b128 v[190:193], v147 offset:1024
	ds_read_b128 v[194:197], v147 offset:2048
	ds_read_b128 v[198:201], v147 offset:3072
	s_add_u32 s86, s86, 0x80000
	s_addc_u32 s87, s87, 0
	s_mov_b32 m0, s38
	v_lshl_add_u64 v[248:249], s[86:87], 0, v[136:137]
	ds_read_b128 v[202:205], v146 offset:32768
	ds_read_b128 v[206:209], v146 offset:33792
	ds_read_b128 v[222:225], v146 offset:34816
	ds_read_b128 v[226:229], v146 offset:35840
	ds_read_b128 v[230:233], v146 offset:36864
	ds_read_b128 v[234:237], v146 offset:37888
	ds_read_b128 v[238:241], v146 offset:38912
	ds_read_b128 v[242:245], v146 offset:39936
	global_load_lds_dwordx4 v[248:249], off
	v_lshl_add_u64 v[248:249], s[86:87], 0, v[132:133]
	s_mov_b32 m0, s39
	s_nop 0
	global_load_lds_dwordx4 v[248:249], off
	s_waitcnt vmcnt(8)
	s_waitcnt lgkmcnt(0)
	s_barrier
	s_setprio 1
	v_mfma_f32_16x16x32_bf16 v[126:129], v[148:151], v[202:205], v[126:129]
	v_mfma_f32_16x16x32_bf16 v[122:125], v[156:159], v[202:205], v[122:125]
	v_mfma_f32_16x16x32_bf16 v[110:113], v[148:151], v[222:225], v[110:113]
	v_mfma_f32_16x16x32_bf16 v[106:109], v[156:159], v[222:225], v[106:109]
	v_mfma_f32_16x16x32_bf16 v[94:97], v[148:151], v[230:233], v[94:97]
	v_mfma_f32_16x16x32_bf16 v[90:93], v[156:159], v[230:233], v[90:93]
	v_mfma_f32_16x16x32_bf16 v[78:81], v[148:151], v[238:241], v[78:81]
	v_mfma_f32_16x16x32_bf16 v[74:77], v[156:159], v[238:241], v[74:77]
	v_mfma_f32_16x16x32_bf16 v[126:129], v[152:155], v[206:209], v[126:129]
	v_mfma_f32_16x16x32_bf16 v[122:125], v[160:163], v[206:209], v[122:125]
	v_mfma_f32_16x16x32_bf16 v[110:113], v[152:155], v[226:229], v[110:113]
	v_mfma_f32_16x16x32_bf16 v[106:109], v[160:163], v[226:229], v[106:109]
	v_mfma_f32_16x16x32_bf16 v[94:97], v[152:155], v[234:237], v[94:97]
	v_mfma_f32_16x16x32_bf16 v[90:93], v[160:163], v[234:237], v[90:93]
	v_mfma_f32_16x16x32_bf16 v[78:81], v[152:155], v[242:245], v[78:81]
	v_mfma_f32_16x16x32_bf16 v[74:77], v[160:163], v[242:245], v[74:77]
	v_mfma_f32_16x16x32_bf16 v[118:121], v[186:189], v[202:205], v[118:121]
	v_mfma_f32_16x16x32_bf16 v[114:117], v[194:197], v[202:205], v[114:117]
	v_mfma_f32_16x16x32_bf16 v[102:105], v[186:189], v[222:225], v[102:105]
	v_mfma_f32_16x16x32_bf16 v[98:101], v[194:197], v[222:225], v[98:101]
	v_mfma_f32_16x16x32_bf16 v[86:89], v[186:189], v[230:233], v[86:89]
	v_mfma_f32_16x16x32_bf16 v[82:85], v[194:197], v[230:233], v[82:85]
	v_mfma_f32_16x16x32_bf16 v[70:73], v[186:189], v[238:241], v[70:73]
	v_mfma_f32_16x16x32_bf16 v[66:69], v[194:197], v[238:241], v[66:69]
	v_mfma_f32_16x16x32_bf16 v[118:121], v[190:193], v[206:209], v[118:121]
	v_mfma_f32_16x16x32_bf16 v[114:117], v[198:201], v[206:209], v[114:117]
	v_mfma_f32_16x16x32_bf16 v[102:105], v[190:193], v[226:229], v[102:105]
	v_mfma_f32_16x16x32_bf16 v[98:101], v[198:201], v[226:229], v[98:101]
	v_mfma_f32_16x16x32_bf16 v[86:89], v[190:193], v[234:237], v[86:89]
	v_mfma_f32_16x16x32_bf16 v[82:85], v[198:201], v[234:237], v[82:85]
	v_mfma_f32_16x16x32_bf16 v[70:73], v[190:193], v[242:245], v[70:73]
	v_mfma_f32_16x16x32_bf16 v[66:69], v[198:201], v[242:245], v[66:69]
	s_setprio 0
	s_barrier
; #define PG8_STAGE(bufoff, gbase, voff) do { _Pragma("unroll") for (int _i = 0; _i < 2; ++_i) \
;         __builtin_amdgcn_global_load_lds((const unsigned*)((const char*)(gbase) + (voff)[_i]), (LAS unsigned*)(lds + (bufoff) + ldsw + _i * 8192), 16, 0, 0); } while (0)
; #define PG8_LDA(dst, b, h) do { _Pragma("unroll") for (int m = 0; m < 4; ++m) _Pragma("unroll") for (int k = 0; k < 2; ++k) dst[m][k] = *(const LAS bf16x8*)(lds + PG8_SA(b, h) + aoff + m * 2048 + k * 1024); } while (0)
; #define PG8_MMA(ai, bj, At, Bt) do { __builtin_amdgcn_s_setprio(1); _Pragma("unroll") for (int m = 0; m < 4; ++m) _Pragma("unroll") for (int n = 0; n < 2; ++n) _Pragma("unroll") for (int k = 0; k < 2; ++k) \
;         acc[ai][bj][m][n] = __builtin_amdgcn_mfma_f32_16x16x32_bf16(Bt[n][k], At[m][k], acc[ai][bj][m][n], 0, 0, 0); __builtin_amdgcn_s_setprio(0); } while (0)
; #define PG8_WAIT_V(n) asm volatile("s_waitcnt vmcnt(" #n ")" ::: "memory")
; #define PG8_WAIT_L(n) asm volatile("s_waitcnt lgkmcnt(" #n ")" ::: "memory")
; #define PG8_BAR __builtin_amdgcn_s_barrier()
; #define PG8_SCHED __builtin_amdgcn_sched_barrier(0)
; template <class Epi>
; __device__ __forceinline__ void gemm_phase(LAS unsigned char* lds, const Gemm g, const StaticOrder& S, const Epi& E) {
;     ...
;             PG8_LDA(At, 1, 1); PG8_STAGE(PG8_SB(1, 0), b3, voffB); PG8_STAGE(PG8_SB(1, 1), b3 + hstep, voffB); PG8_STAGE(PG8_SA(1, 0), a3, voffA);
;             PG8_WAIT_V(8); PG8_WAIT_L(0); PG8_BAR; PG8_MMA(1, 0, At, B0); PG8_MMA(1, 1, At, B1); PG8_BAR; PG8_SCHED;
;         }
;         if (wr == 0) PG8_BAR;
	s_add_i32 s12, s12, s24
	v_lshl_add_u64 v[212:213], v[212:213], 0, s[6:7]
	s_mov_b32 m0, s12
	ds_read_b128 v[202:205], v146 offset:49152
	ds_read_b128 v[206:209], v146 offset:50176
	ds_read_b128 v[222:225], v146 offset:51200
	ds_read_b128 v[226:229], v146 offset:52224
	ds_read_b128 v[230:233], v146 offset:53248
	ds_read_b128 v[234:237], v146 offset:54272
	ds_read_b128 v[238:241], v146 offset:55296
	ds_read_b128 v[242:245], v146 offset:56320
	global_load_lds_dwordx4 v[212:213], off
	s_add_i32 m0, s12, 0x2000
	s_add_u32 s56, s56, 0x80080
	v_lshl_add_u64 v[212:213], v[246:247], 0, s[6:7]
	s_addc_u32 s57, s57, 0
	s_add_i32 s12, s13, s24
	global_load_lds_dwordx4 v[212:213], off
	v_lshl_add_u64 v[212:213], s[56:57], 0, v[134:135]
	s_mov_b32 m0, s12
	s_nop 0
	global_load_lds_dwordx4 v[212:213], off
	v_lshl_add_u64 v[212:213], s[56:57], 0, v[130:131]
	s_add_i32 m0, s12, 0x2000
	s_nop 0
	global_load_lds_dwordx4 v[212:213], off
	v_lshl_add_u64 v[212:213], s[54:55], 0, v[136:137]
	s_mov_b32 m0, s52
	s_nop 0
	global_load_lds_dwordx4 v[212:213], off
	v_lshl_add_u64 v[212:213], s[54:55], 0, v[132:133]
	s_mov_b32 m0, s63
	s_nop 0
	global_load_lds_dwordx4 v[212:213], off
	s_waitcnt vmcnt(8)
	s_waitcnt lgkmcnt(0)
	s_barrier
	s_setprio 1
	v_mfma_f32_16x16x32_bf16 v[62:65], v[148:151], v[202:205], v[62:65]
	v_mfma_f32_16x16x32_bf16 v[58:61], v[156:159], v[202:205], v[58:61]
	v_mfma_f32_16x16x32_bf16 v[46:49], v[148:151], v[222:225], v[46:49]
	v_mfma_f32_16x16x32_bf16 v[42:45], v[156:159], v[222:225], v[42:45]
	v_mfma_f32_16x16x32_bf16 v[30:33], v[148:151], v[230:233], v[30:33]
	v_mfma_f32_16x16x32_bf16 v[26:29], v[156:159], v[230:233], v[26:29]
	v_mfma_f32_16x16x32_bf16 v[14:17], v[148:151], v[238:241], v[14:17]
	v_mfma_f32_16x16x32_bf16 v[10:13], v[156:159], v[238:241], v[10:13]
	v_mfma_f32_16x16x32_bf16 v[62:65], v[152:155], v[206:209], v[62:65]
	v_mfma_f32_16x16x32_bf16 v[58:61], v[160:163], v[206:209], v[58:61]
	v_mfma_f32_16x16x32_bf16 v[46:49], v[152:155], v[226:229], v[46:49]
	v_mfma_f32_16x16x32_bf16 v[42:45], v[160:163], v[226:229], v[42:45]
	v_mfma_f32_16x16x32_bf16 v[30:33], v[152:155], v[234:237], v[30:33]
	v_mfma_f32_16x16x32_bf16 v[26:29], v[160:163], v[234:237], v[26:29]
	v_mfma_f32_16x16x32_bf16 v[14:17], v[152:155], v[242:245], v[14:17]
	v_mfma_f32_16x16x32_bf16 v[10:13], v[160:163], v[242:245], v[10:13]
	v_mfma_f32_16x16x32_bf16 v[54:57], v[186:189], v[202:205], v[54:57]
	v_mfma_f32_16x16x32_bf16 v[50:53], v[194:197], v[202:205], v[50:53]
	v_mfma_f32_16x16x32_bf16 v[38:41], v[186:189], v[222:225], v[38:41]
	v_mfma_f32_16x16x32_bf16 v[34:37], v[194:197], v[222:225], v[34:37]
	v_mfma_f32_16x16x32_bf16 v[22:25], v[186:189], v[230:233], v[22:25]
	v_mfma_f32_16x16x32_bf16 v[18:21], v[194:197], v[230:233], v[18:21]
	v_mfma_f32_16x16x32_bf16 v[6:9], v[186:189], v[238:241], v[6:9]
	v_mfma_f32_16x16x32_bf16 v[2:5], v[194:197], v[238:241], v[2:5]
	v_mfma_f32_16x16x32_bf16 v[54:57], v[190:193], v[206:209], v[54:57]
	v_mfma_f32_16x16x32_bf16 v[50:53], v[198:201], v[206:209], v[50:53]
	v_mfma_f32_16x16x32_bf16 v[38:41], v[190:193], v[226:229], v[38:41]
	v_mfma_f32_16x16x32_bf16 v[34:37], v[198:201], v[226:229], v[34:37]
	v_mfma_f32_16x16x32_bf16 v[22:25], v[190:193], v[234:237], v[22:25]
	v_mfma_f32_16x16x32_bf16 v[18:21], v[198:201], v[234:237], v[18:21]
	v_mfma_f32_16x16x32_bf16 v[6:9], v[190:193], v[242:245], v[6:9]
	v_mfma_f32_16x16x32_bf16 v[2:5], v[198:201], v[242:245], v[2:5]
	s_setprio 0
	s_barrier
	s_add_i32 vcc_lo, vcc_lo, 2
	s_add_u32 s50, s50, 0x100
	s_addc_u32 s51, s51, 0
	s_cmp_gt_u32 vcc_lo, 29
	s_cbranch_scc0 .LBB0_1090
	s_and_b64 vcc, exec, s[34:35]
	s_cbranch_vccz .LBB0_1093
	s_barrier

; #define PG8_STAGE(bufoff, gbase, voff) do { _Pragma("unroll") for (int _i = 0; _i < 2; ++_i) \
;         __builtin_amdgcn_global_load_lds((const unsigned*)((const char*)(gbase) + (voff)[_i]), (LAS unsigned*)(lds + (bufoff) + ldsw + _i * 8192), 16, 0, 0); } while (0)
; #define PG8_LDA(dst, b, h) do { _Pragma("unroll") for (int m = 0; m < 4; ++m) _Pragma("unroll") for (int k = 0; k < 2; ++k) dst[m][k] = *(const LAS bf16x8*)(lds + PG8_SA(b, h) + aoff + m * 2048 + k * 1024); } while (0)
; #define PG8_LDB(dst, b, h) do { _Pragma("unroll") for (int n = 0; n < 2; ++n) _Pragma("unroll") for (int k = 0; k < 2; ++k) dst[n][k] = *(const LAS bf16x8*)(lds + PG8_SB(b, h) + boff + n * 2048 + k * 1024); } while (0)
; #define PG8_MMA(ai, bj, At, Bt) do { __builtin_amdgcn_s_setprio(1); _Pragma("unroll") for (int m = 0; m < 4; ++m) _Pragma("unroll") for (int n = 0; n < 2; ++n) _Pragma("unroll") for (int k = 0; k < 2; ++k) \
;         acc[ai][bj][m][n] = __builtin_amdgcn_mfma_f32_16x16x32_bf16(Bt[n][k], At[m][k], acc[ai][bj][m][n], 0, 0, 0); __builtin_amdgcn_s_setprio(0); } while (0)
; #define PG8_WAIT_V(n) asm volatile("s_waitcnt vmcnt(" #n ")" ::: "memory")
; #define PG8_WAIT_L(n) asm volatile("s_waitcnt lgkmcnt(" #n ")" ::: "memory")
; template <class Epi>
; __device__ __forceinline__ void gemm_phase(LAS unsigned char* lds, const Gemm g, const StaticOrder& S, const Epi& E) {
;     ...
;         for (int t = 0; t < nt; t += 2) {
;             if constexpr (Epi::GATED) { if (t == 8 || t == 16) E.rescale(acc, cur, t == 8 ? 0 : 1, wr, wc, fr, fq); }
;             const bool last = (t == nt - 2);
;             const char* a1 = PG8_AP(cA, t + 1);
;             const char* a2 = last ? nA : PG8_AP(cA, t + 2); const char* b2 = last ? nB : cB + (size_t)(t + 2) * kstep;
;             const char* a3 = last ? nA + kstep : PG8_AP(cA, t + 3); const char* b3 = b2 + kstep;
;             PG8_LDB(B0, 0, 0); PG8_LDB(B1, 0, 1); PG8_SCHED; PG8_LDA(At, 0, 0); PG8_STAGE(PG8_SA(1, 1), a1 + hstepA, voffA);
;             PG8_WAIT_V(8); PG8_WAIT_L(0); PG8_BAR; PG8_MMA(0, 0, At, B0); PG8_MMA(0, 1, At, B1); PG8_BAR; PG8_SCHED;
;             PG8_LDA(At, 0, 1); PG8_STAGE(PG8_SB(0, 0), b2, voffB); PG8_STAGE(PG8_SB(0, 1), b2 + hstep, voffB); PG8_STAGE(PG8_SA(0, 0), a2, voffA);
;             PG8_WAIT_V(8); PG8_WAIT_L(0); PG8_BAR; PG8_MMA(1, 0, At, B0); PG8_MMA(1, 1, At, B1); PG8_BAR; PG8_SCHED;
.LBB0_1162:
	s_add_u32 s12, s46, s48
	s_addc_u32 s13, s47, s49
	s_add_u32 s14, s12, 0x100
	s_addc_u32 s15, s13, 0
	s_add_u32 s54, s96, s48
	s_addc_u32 s55, s97, s49
	s_add_u32 s12, s12, 0x180
	s_addc_u32 s13, s13, 0
	s_add_i32 s90, 0, 0x10000
	s_add_i32 vcc_hi, 0, 0x14000
	v_add_u32_e32 v147, s90, v1
	ds_read_b128 v[148:151], v147
	ds_read_b128 v[152:155], v147 offset:1024
	ds_read_b128 v[156:159], v147 offset:2048
	ds_read_b128 v[160:163], v147 offset:3072
	v_add_u32_e32 v147, vcc_hi, v1
	ds_read_b128 v[186:189], v147
	ds_read_b128 v[190:193], v147 offset:1024
	ds_read_b128 v[194:197], v147 offset:2048
	ds_read_b128 v[198:201], v147 offset:3072
	s_cmpk_eq_i32 s48, 0x3f00
	s_cselect_b32 s51, s94, s13
	s_cselect_b32 s50, s93, s12
	s_cselect_b32 s55, s37, s55
	s_cselect_b32 s54, s92, s54
	s_cselect_b32 s57, s41, s15
	s_cselect_b32 s56, s87, s14
	v_lshl_add_u64 v[212:213], v[142:143], 0, s[48:49]
	s_add_i32 m0, s25, 0xc000
	ds_read_b128 v[202:205], v146
	ds_read_b128 v[206:209], v146 offset:1024
	ds_read_b128 v[222:225], v146 offset:2048
	ds_read_b128 v[226:229], v146 offset:3072
	ds_read_b128 v[230:233], v146 offset:4096
	ds_read_b128 v[234:237], v146 offset:5120
	ds_read_b128 v[238:241], v146 offset:6144
	ds_read_b128 v[242:245], v146 offset:7168
	global_load_lds_dwordx4 v[212:213], off
	v_lshl_add_u64 v[212:213], v[144:145], 0, s[48:49]
	s_add_i32 m0, s25, 0xe000
	s_nop 0
	global_load_lds_dwordx4 v[212:213], off
	s_waitcnt vmcnt(8)
	s_waitcnt lgkmcnt(0)
	s_barrier
	s_setprio 1
	v_mfma_f32_16x16x32_bf16 v[126:129], v[148:151], v[202:205], v[126:129]
	v_mfma_f32_16x16x32_bf16 v[122:125], v[156:159], v[202:205], v[122:125]
	v_mfma_f32_16x16x32_bf16 v[118:121], v[148:151], v[222:225], v[118:121]
	v_mfma_f32_16x16x32_bf16 v[110:113], v[156:159], v[222:225], v[110:113]
	v_mfma_f32_16x16x32_bf16 v[102:105], v[148:151], v[230:233], v[102:105]
	v_mfma_f32_16x16x32_bf16 v[94:97], v[156:159], v[230:233], v[94:97]
	v_mfma_f32_16x16x32_bf16 v[86:89], v[148:151], v[238:241], v[86:89]
	v_mfma_f32_16x16x32_bf16 v[78:81], v[156:159], v[238:241], v[78:81]
	v_mfma_f32_16x16x32_bf16 v[126:129], v[152:155], v[206:209], v[126:129]
	v_mfma_f32_16x16x32_bf16 v[122:125], v[160:163], v[206:209], v[122:125]
	v_mfma_f32_16x16x32_bf16 v[118:121], v[152:155], v[226:229], v[118:121]
	v_mfma_f32_16x16x32_bf16 v[110:113], v[160:163], v[226:229], v[110:113]
	v_mfma_f32_16x16x32_bf16 v[102:105], v[152:155], v[234:237], v[102:105]
	v_mfma_f32_16x16x32_bf16 v[94:97], v[160:163], v[234:237], v[94:97]
	v_mfma_f32_16x16x32_bf16 v[86:89], v[152:155], v[242:245], v[86:89]
	v_mfma_f32_16x16x32_bf16 v[78:81], v[160:163], v[242:245], v[78:81]
	v_mfma_f32_16x16x32_bf16 v[114:117], v[186:189], v[202:205], v[114:117]
	v_mfma_f32_16x16x32_bf16 v[106:109], v[194:197], v[202:205], v[106:109]
	v_mfma_f32_16x16x32_bf16 v[98:101], v[186:189], v[222:225], v[98:101]
	v_mfma_f32_16x16x32_bf16 v[90:93], v[194:197], v[222:225], v[90:93]
	v_mfma_f32_16x16x32_bf16 v[82:85], v[186:189], v[230:233], v[82:85]
	v_mfma_f32_16x16x32_bf16 v[74:77], v[194:197], v[230:233], v[74:77]
	v_mfma_f32_16x16x32_bf16 v[70:73], v[186:189], v[238:241], v[70:73]
	v_mfma_f32_16x16x32_bf16 v[66:69], v[194:197], v[238:241], v[66:69]
	v_mfma_f32_16x16x32_bf16 v[114:117], v[190:193], v[206:209], v[114:117]
	v_mfma_f32_16x16x32_bf16 v[106:109], v[198:201], v[206:209], v[106:109]
	v_mfma_f32_16x16x32_bf16 v[98:101], v[190:193], v[226:229], v[98:101]
	v_mfma_f32_16x16x32_bf16 v[90:93], v[198:201], v[226:229], v[90:93]
	v_mfma_f32_16x16x32_bf16 v[82:85], v[190:193], v[234:237], v[82:85]
	v_mfma_f32_16x16x32_bf16 v[74:77], v[198:201], v[234:237], v[74:77]
	v_mfma_f32_16x16x32_bf16 v[70:73], v[190:193], v[242:245], v[70:73]
	v_mfma_f32_16x16x32_bf16 v[66:69], v[198:201], v[242:245], v[66:69]
	s_setprio 0
	s_barrier
	s_add_i32 s12, s90, s24
	v_lshl_add_u64 v[212:213], s[54:55], 0, v[134:135]
	s_mov_b32 m0, s12
	ds_read_b128 v[202:205], v146 offset:16384
	ds_read_b128 v[206:209], v146 offset:17408
	ds_read_b128 v[222:225], v146 offset:18432
	ds_read_b128 v[226:229], v146 offset:19456
	ds_read_b128 v[230:233], v146 offset:20480
	ds_read_b128 v[234:237], v146 offset:21504
	ds_read_b128 v[238:241], v146 offset:22528
	ds_read_b128 v[242:245], v146 offset:23552
	global_load_lds_dwordx4 v[212:213], off
	s_add_i32 m0, s12, 0x2000
	s_add_u32 s90, s54, 0x200000
	v_lshl_add_u64 v[246:247], s[54:55], 0, v[130:131]
	s_addc_u32 s91, s55, 0
	s_add_i32 s12, vcc_hi, s24
	global_load_lds_dwordx4 v[246:247], off
	v_lshl_add_u64 v[248:249], s[90:91], 0, v[134:135]
	s_mov_b32 m0, s12
	s_nop 0
	global_load_lds_dwordx4 v[248:249], off
	v_lshl_add_u64 v[248:249], s[90:91], 0, v[130:131]
	s_add_i32 m0, s12, 0x2000
	s_nop 0
	global_load_lds_dwordx4 v[248:249], off
	v_lshl_add_u64 v[248:249], s[56:57], 0, v[136:137]
	s_mov_b32 m0, s25
	s_nop 0
	global_load_lds_dwordx4 v[248:249], off
	v_lshl_add_u64 v[248:249], s[56:57], 0, v[132:133]
	s_mov_b32 m0, s33
	s_nop 0
	global_load_lds_dwordx4 v[248:249], off
	s_waitcnt vmcnt(8)
	s_waitcnt lgkmcnt(0)
	s_barrier
; #define PG8_STAGE(bufoff, gbase, voff) do { _Pragma("unroll") for (int _i = 0; _i < 2; ++_i) \
;         __builtin_amdgcn_global_load_lds((const unsigned*)((const char*)(gbase) + (voff)[_i]), (LAS unsigned*)(lds + (bufoff) + ldsw + _i * 8192), 16, 0, 0); } while (0)
; #define PG8_LDA(dst, b, h) do { _Pragma("unroll") for (int m = 0; m < 4; ++m) _Pragma("unroll") for (int k = 0; k < 2; ++k) dst[m][k] = *(const LAS bf16x8*)(lds + PG8_SA(b, h) + aoff + m * 2048 + k * 1024); } while (0)
; #define PG8_LDB(dst, b, h) do { _Pragma("unroll") for (int n = 0; n < 2; ++n) _Pragma("unroll") for (int k = 0; k < 2; ++k) dst[n][k] = *(const LAS bf16x8*)(lds + PG8_SB(b, h) + boff + n * 2048 + k * 1024); } while (0)
; #define PG8_MMA(ai, bj, At, Bt) do { __builtin_amdgcn_s_setprio(1); _Pragma("unroll") for (int m = 0; m < 4; ++m) _Pragma("unroll") for (int n = 0; n < 2; ++n) _Pragma("unroll") for (int k = 0; k < 2; ++k) \
;         acc[ai][bj][m][n] = __builtin_amdgcn_mfma_f32_16x16x32_bf16(Bt[n][k], At[m][k], acc[ai][bj][m][n], 0, 0, 0); __builtin_amdgcn_s_setprio(0); } while (0)
; #define PG8_WAIT_V(n) asm volatile("s_waitcnt vmcnt(" #n ")" ::: "memory")
; #define PG8_WAIT_L(n) asm volatile("s_waitcnt lgkmcnt(" #n ")" ::: "memory")
; #define PG8_BAR __builtin_amdgcn_s_barrier()
; #define PG8_SCHED __builtin_amdgcn_sched_barrier(0)
; template <class Epi>
; __device__ __forceinline__ void gemm_phase(LAS unsigned char* lds, const Gemm g, const StaticOrder& S, const Epi& E) {
;     ...
;             PG8_WAIT_V(8); PG8_WAIT_L(0); PG8_BAR; PG8_MMA(1, 0, At, B0); PG8_MMA(1, 1, At, B1); PG8_BAR; PG8_SCHED;
;             PG8_LDB(B0, 1, 0); PG8_LDB(B1, 1, 1); PG8_SCHED; PG8_LDA(At, 1, 0); PG8_STAGE(PG8_SA(0, 1), a2 + hstepA, voffA);
;             PG8_WAIT_V(8); PG8_WAIT_L(0); PG8_BAR; PG8_MMA(0, 0, At, B0); PG8_MMA(0, 1, At, B1); PG8_BAR; PG8_SCHED;
	s_setprio 1
	v_mfma_f32_16x16x32_bf16 v[62:65], v[148:151], v[202:205], v[62:65]
	v_mfma_f32_16x16x32_bf16 v[58:61], v[156:159], v[202:205], v[58:61]
	v_mfma_f32_16x16x32_bf16 v[54:57], v[148:151], v[222:225], v[54:57]
	v_mfma_f32_16x16x32_bf16 v[46:49], v[156:159], v[222:225], v[46:49]
	v_mfma_f32_16x16x32_bf16 v[38:41], v[148:151], v[230:233], v[38:41]
	v_mfma_f32_16x16x32_bf16 v[30:33], v[156:159], v[230:233], v[30:33]
	v_mfma_f32_16x16x32_bf16 v[22:25], v[148:151], v[238:241], v[22:25]
	v_mfma_f32_16x16x32_bf16 v[14:17], v[156:159], v[238:241], v[14:17]
	v_mfma_f32_16x16x32_bf16 v[62:65], v[152:155], v[206:209], v[62:65]
	v_mfma_f32_16x16x32_bf16 v[58:61], v[160:163], v[206:209], v[58:61]
	v_mfma_f32_16x16x32_bf16 v[54:57], v[152:155], v[226:229], v[54:57]
	v_mfma_f32_16x16x32_bf16 v[46:49], v[160:163], v[226:229], v[46:49]
	v_mfma_f32_16x16x32_bf16 v[38:41], v[152:155], v[234:237], v[38:41]
	v_mfma_f32_16x16x32_bf16 v[30:33], v[160:163], v[234:237], v[30:33]
	v_mfma_f32_16x16x32_bf16 v[22:25], v[152:155], v[242:245], v[22:25]
	v_mfma_f32_16x16x32_bf16 v[14:17], v[160:163], v[242:245], v[14:17]
	v_mfma_f32_16x16x32_bf16 v[50:53], v[186:189], v[202:205], v[50:53]
	v_mfma_f32_16x16x32_bf16 v[42:45], v[194:197], v[202:205], v[42:45]
	v_mfma_f32_16x16x32_bf16 v[34:37], v[186:189], v[222:225], v[34:37]
	v_mfma_f32_16x16x32_bf16 v[26:29], v[194:197], v[222:225], v[26:29]
	v_mfma_f32_16x16x32_bf16 v[18:21], v[186:189], v[230:233], v[18:21]
	v_mfma_f32_16x16x32_bf16 v[10:13], v[194:197], v[230:233], v[10:13]
	v_mfma_f32_16x16x32_bf16 v[6:9], v[186:189], v[238:241], v[6:9]
	v_mfma_f32_16x16x32_bf16 v[2:5], v[194:197], v[238:241], v[2:5]
	v_mfma_f32_16x16x32_bf16 v[50:53], v[190:193], v[206:209], v[50:53]
	v_mfma_f32_16x16x32_bf16 v[42:45], v[198:201], v[206:209], v[42:45]
	v_mfma_f32_16x16x32_bf16 v[34:37], v[190:193], v[226:229], v[34:37]
	v_mfma_f32_16x16x32_bf16 v[26:29], v[198:201], v[226:229], v[26:29]
	v_mfma_f32_16x16x32_bf16 v[18:21], v[190:193], v[234:237], v[18:21]
	v_mfma_f32_16x16x32_bf16 v[10:13], v[198:201], v[234:237], v[10:13]
	v_mfma_f32_16x16x32_bf16 v[6:9], v[190:193], v[242:245], v[6:9]
	v_mfma_f32_16x16x32_bf16 v[2:5], v[198:201], v[242:245], v[2:5]
	s_setprio 0
	s_barrier
	s_add_i32 s12, 0, 0x18000
	v_add_u32_e32 v147, s12, v1
	s_add_i32 s13, 0, 0x1c000
	ds_read_b128 v[148:151], v147
	ds_read_b128 v[152:155], v147 offset:1024
	ds_read_b128 v[156:159], v147 offset:2048
	ds_read_b128 v[160:163], v147 offset:3072
	v_add_u32_e32 v147, s13, v1
	ds_read_b128 v[186:189], v147
	ds_read_b128 v[190:193], v147 offset:1024
	ds_read_b128 v[194:197], v147 offset:2048
	ds_read_b128 v[198:201], v147 offset:3072
	s_add_u32 s56, s56, 0x200000
	s_addc_u32 s57, s57, 0
	s_mov_b32 m0, s52
	v_lshl_add_u64 v[248:249], s[56:57], 0, v[136:137]
	ds_read_b128 v[202:205], v146 offset:32768
	ds_read_b128 v[206:209], v146 offset:33792
	ds_read_b128 v[222:225], v146 offset:34816
	ds_read_b128 v[226:229], v146 offset:35840
	ds_read_b128 v[230:233], v146 offset:36864
	ds_read_b128 v[234:237], v146 offset:37888
	ds_read_b128 v[238:241], v146 offset:38912
	ds_read_b128 v[242:245], v146 offset:39936
	global_load_lds_dwordx4 v[248:249], off
	v_lshl_add_u64 v[248:249], s[56:57], 0, v[132:133]
	s_mov_b32 m0, s63
	s_nop 0
	global_load_lds_dwordx4 v[248:249], off
	s_waitcnt vmcnt(8)
	s_waitcnt lgkmcnt(0)
	s_barrier
	s_setprio 1
	v_mfma_f32_16x16x32_bf16 v[126:129], v[148:151], v[202:205], v[126:129]
	v_mfma_f32_16x16x32_bf16 v[122:125], v[156:159], v[202:205], v[122:125]
	v_mfma_f32_16x16x32_bf16 v[118:121], v[148:151], v[222:225], v[118:121]
	v_mfma_f32_16x16x32_bf16 v[110:113], v[156:159], v[222:225], v[110:113]
	v_mfma_f32_16x16x32_bf16 v[102:105], v[148:151], v[230:233], v[102:105]
	v_mfma_f32_16x16x32_bf16 v[94:97], v[156:159], v[230:233], v[94:97]
	v_mfma_f32_16x16x32_bf16 v[86:89], v[148:151], v[238:241], v[86:89]
	v_mfma_f32_16x16x32_bf16 v[78:81], v[156:159], v[238:241], v[78:81]
	v_mfma_f32_16x16x32_bf16 v[126:129], v[152:155], v[206:209], v[126:129]
	v_mfma_f32_16x16x32_bf16 v[122:125], v[160:163], v[206:209], v[122:125]
	v_mfma_f32_16x16x32_bf16 v[118:121], v[152:155], v[226:229], v[118:121]
	v_mfma_f32_16x16x32_bf16 v[110:113], v[160:163], v[226:229], v[110:113]
	v_mfma_f32_16x16x32_bf16 v[102:105], v[152:155], v[234:237], v[102:105]
	v_mfma_f32_16x16x32_bf16 v[94:97], v[160:163], v[234:237], v[94:97]
	v_mfma_f32_16x16x32_bf16 v[86:89], v[152:155], v[242:245], v[86:89]
	v_mfma_f32_16x16x32_bf16 v[78:81], v[160:163], v[242:245], v[78:81]
	v_mfma_f32_16x16x32_bf16 v[114:117], v[186:189], v[202:205], v[114:117]
	v_mfma_f32_16x16x32_bf16 v[106:109], v[194:197], v[202:205], v[106:109]
	v_mfma_f32_16x16x32_bf16 v[98:101], v[186:189], v[222:225], v[98:101]
	v_mfma_f32_16x16x32_bf16 v[90:93], v[194:197], v[222:225], v[90:93]
	v_mfma_f32_16x16x32_bf16 v[82:85], v[186:189], v[230:233], v[82:85]
	v_mfma_f32_16x16x32_bf16 v[74:77], v[194:197], v[230:233], v[74:77]
	v_mfma_f32_16x16x32_bf16 v[70:73], v[186:189], v[238:241], v[70:73]
	v_mfma_f32_16x16x32_bf16 v[66:69], v[194:197], v[238:241], v[66:69]
	v_mfma_f32_16x16x32_bf16 v[114:117], v[190:193], v[206:209], v[114:117]
	v_mfma_f32_16x16x32_bf16 v[106:109], v[198:201], v[206:209], v[106:109]
	v_mfma_f32_16x16x32_bf16 v[98:101], v[190:193], v[226:229], v[98:101]
	v_mfma_f32_16x16x32_bf16 v[90:93], v[198:201], v[226:229], v[90:93]
	v_mfma_f32_16x16x32_bf16 v[82:85], v[190:193], v[234:237], v[82:85]
	v_mfma_f32_16x16x32_bf16 v[74:77], v[198:201], v[234:237], v[74:77]
	v_mfma_f32_16x16x32_bf16 v[70:73], v[190:193], v[242:245], v[70:73]
	v_mfma_f32_16x16x32_bf16 v[66:69], v[198:201], v[242:245], v[66:69]
	s_setprio 0
	s_barrier
; #define PG8_STAGE(bufoff, gbase, voff) do { _Pragma("unroll") for (int _i = 0; _i < 2; ++_i) \
;         __builtin_amdgcn_global_load_lds((const unsigned*)((const char*)(gbase) + (voff)[_i]), (LAS unsigned*)(lds + (bufoff) + ldsw + _i * 8192), 16, 0, 0); } while (0)
; #define PG8_LDA(dst, b, h) do { _Pragma("unroll") for (int m = 0; m < 4; ++m) _Pragma("unroll") for (int k = 0; k < 2; ++k) dst[m][k] = *(const LAS bf16x8*)(lds + PG8_SA(b, h) + aoff + m * 2048 + k * 1024); } while (0)
; #define PG8_MMA(ai, bj, At, Bt) do { __builtin_amdgcn_s_setprio(1); _Pragma("unroll") for (int m = 0; m < 4; ++m) _Pragma("unroll") for (int n = 0; n < 2; ++n) _Pragma("unroll") for (int k = 0; k < 2; ++k) \
;         acc[ai][bj][m][n] = __builtin_amdgcn_mfma_f32_16x16x32_bf16(Bt[n][k], At[m][k], acc[ai][bj][m][n], 0, 0, 0); __builtin_amdgcn_s_setprio(0); } while (0)
; #define PG8_WAIT_V(n) asm volatile("s_waitcnt vmcnt(" #n ")" ::: "memory")
; #define PG8_WAIT_L(n) asm volatile("s_waitcnt lgkmcnt(" #n ")" ::: "memory")
; #define PG8_BAR __builtin_amdgcn_s_barrier()
; #define PG8_SCHED __builtin_amdgcn_sched_barrier(0)
; template <class Epi>
; __device__ __forceinline__ void gemm_phase(LAS unsigned char* lds, const Gemm g, const StaticOrder& S, const Epi& E) {
;     ...
;             PG8_LDA(At, 1, 1); PG8_STAGE(PG8_SB(1, 0), b3, voffB); PG8_STAGE(PG8_SB(1, 1), b3 + hstep, voffB); PG8_STAGE(PG8_SA(1, 0), a3, voffA);
;             PG8_WAIT_V(8); PG8_WAIT_L(0); PG8_BAR; PG8_MMA(1, 0, At, B0); PG8_MMA(1, 1, At, B1); PG8_BAR; PG8_SCHED;
;         }
;         if (wr == 0) PG8_BAR;
	s_add_i32 s12, s12, s24
	v_lshl_add_u64 v[212:213], v[212:213], 0, s[6:7]
	s_mov_b32 m0, s12
	ds_read_b128 v[202:205], v146 offset:49152
	ds_read_b128 v[206:209], v146 offset:50176
	ds_read_b128 v[222:225], v146 offset:51200
	ds_read_b128 v[226:229], v146 offset:52224
	ds_read_b128 v[230:233], v146 offset:53248
	ds_read_b128 v[234:237], v146 offset:54272
	ds_read_b128 v[238:241], v146 offset:55296
	ds_read_b128 v[242:245], v146 offset:56320
	global_load_lds_dwordx4 v[212:213], off
	s_add_i32 m0, s12, 0x2000
	s_add_u32 s54, s54, 0x200080
	v_lshl_add_u64 v[212:213], v[246:247], 0, s[6:7]
	s_addc_u32 s55, s55, 0
	s_add_i32 s12, s13, s24
	global_load_lds_dwordx4 v[212:213], off
	v_lshl_add_u64 v[212:213], s[54:55], 0, v[134:135]
	s_mov_b32 m0, s12
	s_nop 0
	global_load_lds_dwordx4 v[212:213], off
	v_lshl_add_u64 v[212:213], s[54:55], 0, v[130:131]
	s_add_i32 m0, s12, 0x2000
	s_nop 0
	global_load_lds_dwordx4 v[212:213], off
	v_lshl_add_u64 v[212:213], s[50:51], 0, v[136:137]
	s_mov_b32 m0, s67
	s_nop 0
	global_load_lds_dwordx4 v[212:213], off
	v_lshl_add_u64 v[212:213], s[50:51], 0, v[132:133]
	s_mov_b32 m0, s80
	s_nop 0
	global_load_lds_dwordx4 v[212:213], off
	s_waitcnt vmcnt(8)
	s_waitcnt lgkmcnt(0)
	s_barrier
	s_setprio 1
	v_mfma_f32_16x16x32_bf16 v[62:65], v[148:151], v[202:205], v[62:65]
	v_mfma_f32_16x16x32_bf16 v[58:61], v[156:159], v[202:205], v[58:61]
	v_mfma_f32_16x16x32_bf16 v[54:57], v[148:151], v[222:225], v[54:57]
	v_mfma_f32_16x16x32_bf16 v[46:49], v[156:159], v[222:225], v[46:49]
	v_mfma_f32_16x16x32_bf16 v[38:41], v[148:151], v[230:233], v[38:41]
	v_mfma_f32_16x16x32_bf16 v[30:33], v[156:159], v[230:233], v[30:33]
	v_mfma_f32_16x16x32_bf16 v[22:25], v[148:151], v[238:241], v[22:25]
	v_mfma_f32_16x16x32_bf16 v[14:17], v[156:159], v[238:241], v[14:17]
	v_mfma_f32_16x16x32_bf16 v[62:65], v[152:155], v[206:209], v[62:65]
	v_mfma_f32_16x16x32_bf16 v[58:61], v[160:163], v[206:209], v[58:61]
	v_mfma_f32_16x16x32_bf16 v[54:57], v[152:155], v[226:229], v[54:57]
	v_mfma_f32_16x16x32_bf16 v[46:49], v[160:163], v[226:229], v[46:49]
	v_mfma_f32_16x16x32_bf16 v[38:41], v[152:155], v[234:237], v[38:41]
	v_mfma_f32_16x16x32_bf16 v[30:33], v[160:163], v[234:237], v[30:33]
	v_mfma_f32_16x16x32_bf16 v[22:25], v[152:155], v[242:245], v[22:25]
	v_mfma_f32_16x16x32_bf16 v[14:17], v[160:163], v[242:245], v[14:17]
	v_mfma_f32_16x16x32_bf16 v[50:53], v[186:189], v[202:205], v[50:53]
	v_mfma_f32_16x16x32_bf16 v[42:45], v[194:197], v[202:205], v[42:45]
	v_mfma_f32_16x16x32_bf16 v[34:37], v[186:189], v[222:225], v[34:37]
	v_mfma_f32_16x16x32_bf16 v[26:29], v[194:197], v[222:225], v[26:29]
	v_mfma_f32_16x16x32_bf16 v[18:21], v[186:189], v[230:233], v[18:21]
	v_mfma_f32_16x16x32_bf16 v[10:13], v[194:197], v[230:233], v[10:13]
	v_mfma_f32_16x16x32_bf16 v[6:9], v[186:189], v[238:241], v[6:9]
	v_mfma_f32_16x16x32_bf16 v[2:5], v[194:197], v[238:241], v[2:5]
	v_mfma_f32_16x16x32_bf16 v[50:53], v[190:193], v[206:209], v[50:53]
	v_mfma_f32_16x16x32_bf16 v[42:45], v[198:201], v[206:209], v[42:45]
	v_mfma_f32_16x16x32_bf16 v[34:37], v[190:193], v[226:229], v[34:37]
	v_mfma_f32_16x16x32_bf16 v[26:29], v[198:201], v[226:229], v[26:29]
	v_mfma_f32_16x16x32_bf16 v[18:21], v[190:193], v[234:237], v[18:21]
	v_mfma_f32_16x16x32_bf16 v[10:13], v[198:201], v[234:237], v[10:13]
	v_mfma_f32_16x16x32_bf16 v[6:9], v[190:193], v[242:245], v[6:9]
	v_mfma_f32_16x16x32_bf16 v[2:5], v[198:201], v[242:245], v[2:5]
	s_setprio 0
	s_barrier
	s_add_i32 vcc_lo, vcc_lo, 2
	s_add_u32 s48, s48, 0x100
	s_addc_u32 s49, s49, 0
	s_cmpk_gt_u32 vcc_lo, 0x7d
	s_cbranch_scc0 .LBB0_1162
	s_and_b64 vcc, exec, s[34:35]
	s_cbranch_vccz .LBB0_1165
	s_barrier
